# GEMM mainloops: the 16 MFMAs of each phase reordered so the two k-halves of one accumulator issue back to back, pairs in n-major snake order (same math, same per-accumulator order)
# speedup vs baseline: 1.0168x; 1.0150x over previous
; #define PG8_STAGE(bufoff, gbase, voff) do { _Pragma("unroll") for (int _i = 0; _i < 2; ++_i) \
;         __builtin_amdgcn_global_load_lds((const unsigned*)((const char*)(gbase) + (voff)[_i]), (LAS unsigned*)(lds + (bufoff) + ldsw + _i * 8192), 16, 0, 0); } while (0)
; #define PG8_LDA(dst, b, h) do { _Pragma("unroll") for (int m = 0; m < 4; ++m) _Pragma("unroll") for (int k = 0; k < 2; ++k) dst[m][k] = *(const LAS bf16x8*)(lds + PG8_SA(b, h) + aoff + m * 2048 + k * 1024); } while (0)
; #define PG8_LDB(dst, b, h) do { _Pragma("unroll") for (int n = 0; n < 2; ++n) _Pragma("unroll") for (int k = 0; k < 2; ++k) dst[n][k] = *(const LAS bf16x8*)(lds + PG8_SB(b, h) + boff + n * 2048 + k * 1024); } while (0)
; #define PG8_MMA(ai, bj, At, Bt) do { __builtin_amdgcn_s_setprio(1); _Pragma("unroll") for (int m = 0; m < 4; ++m) _Pragma("unroll") for (int n = 0; n < 2; ++n) _Pragma("unroll") for (int k = 0; k < 2; ++k) \
;         acc[ai][bj][m][n] = __builtin_amdgcn_mfma_f32_16x16x32_bf16(Bt[n][k], At[m][k], acc[ai][bj][m][n], 0, 0, 0); __builtin_amdgcn_s_setprio(0); } while (0)
; #define PG8_WAIT_L(n) asm volatile("s_waitcnt lgkmcnt(" #n ")" ::: "memory")
; #define PG8_BAR __builtin_amdgcn_s_barrier()
; #define PG8_SCHED __builtin_amdgcn_sched_barrier(0)
; template <class Epi>
; __device__ __forceinline__ void gemm_phase(LAS unsigned char* lds, const Gemm g, const StaticOrder& S, const Epi& E) {
;     ...
;             PG8_LDB(B0, 0, 0); PG8_SCHED; PG8_LDA(At, 0, 0); PG8_STAGE(PG8_SA(1, 1), a1 + hstep, voffA);
;             PG8_WAIT_L(8); PG8_BAR; PG8_WAIT_L(0); PG8_MMA(0, 0, At, B0); PG8_BAR; PG8_SCHED;
;             PG8_LDB(B1, 0, 1); PG8_STAGE(PG8_SB(0, 0), b2, voffB);
;             PG8_BAR; PG8_WAIT_L(0); PG8_MMA(0, 1, At, B1); PG8_BAR;
;             PG8_LDA(At, 0, 1); PG8_STAGE(PG8_SA(0, 0), a2, voffA);
;             PG8_BAR; PG8_WAIT_L(0); PG8_MMA(1, 0, At, B0); PG8_BAR; PG8_SCHED;
.LBB0_43:
	s_add_u32 s24, s22, 0xfffc0080
	s_addc_u32 s25, s23, -1
	s_add_i32 s47, 0, 0x10000
	v_add_u32_e32 v140, s47, v247
	ds_read_b128 v[128:131], v140
	ds_read_b128 v[132:135], v140 offset:1024
	ds_read_b128 v[136:139], v140 offset:2048
	ds_read_b128 v[140:143], v140 offset:3072
	s_cmp_eq_u32 s46, 12
	s_cselect_b32 s27, s3, s25
	s_cselect_b32 s26, s9, s24
	s_cselect_b32 s25, s13, s45
	s_cselect_b32 s24, s15, s43
	v_lshl_add_u64 v[176:177], s[22:23], 0, v[214:215]
	s_add_i32 m0, s21, 0xc000
	ds_read_b128 v[144:147], v249
	ds_read_b128 v[148:151], v249 offset:1024
	ds_read_b128 v[152:155], v249 offset:2048
	ds_read_b128 v[156:159], v249 offset:3072
	ds_read_b128 v[160:163], v249 offset:4096
	ds_read_b128 v[164:167], v249 offset:5120
	ds_read_b128 v[168:171], v249 offset:6144
	ds_read_b128 v[172:175], v249 offset:7168
	global_load_lds_dwordx4 v[176:177], off
	v_lshl_add_u64 v[176:177], s[22:23], 0, v[216:217]
	s_add_i32 m0, s21, 0xe000
	s_nop 0
	global_load_lds_dwordx4 v[176:177], off
	s_waitcnt lgkmcnt(8)
	s_barrier
	s_waitcnt lgkmcnt(0)
	s_setprio 1
	s_waitcnt lgkmcnt(0)
	v_mfma_f32_16x16x32_bf16 v[124:127], v[128:131], v[144:147], v[124:127]
	v_mfma_f32_16x16x32_bf16 v[124:127], v[132:135], v[148:151], v[124:127]
	v_mfma_f32_16x16x32_bf16 v[108:111], v[128:131], v[152:155], v[108:111]
	v_mfma_f32_16x16x32_bf16 v[108:111], v[132:135], v[156:159], v[108:111]
	v_mfma_f32_16x16x32_bf16 v[92:95], v[128:131], v[160:163], v[92:95]
	v_mfma_f32_16x16x32_bf16 v[92:95], v[132:135], v[164:167], v[92:95]
	v_mfma_f32_16x16x32_bf16 v[76:79], v[128:131], v[168:171], v[76:79]
	v_mfma_f32_16x16x32_bf16 v[76:79], v[132:135], v[172:175], v[76:79]
	v_mfma_f32_16x16x32_bf16 v[72:75], v[136:139], v[168:171], v[72:75]
	v_mfma_f32_16x16x32_bf16 v[72:75], v[140:143], v[172:175], v[72:75]
	v_mfma_f32_16x16x32_bf16 v[88:91], v[136:139], v[160:163], v[88:91]
	v_mfma_f32_16x16x32_bf16 v[88:91], v[140:143], v[164:167], v[88:91]
	v_mfma_f32_16x16x32_bf16 v[104:107], v[136:139], v[152:155], v[104:107]
	v_mfma_f32_16x16x32_bf16 v[104:107], v[140:143], v[156:159], v[104:107]
	v_mfma_f32_16x16x32_bf16 v[120:123], v[136:139], v[144:147], v[120:123]
	v_mfma_f32_16x16x32_bf16 v[120:123], v[140:143], v[148:151], v[120:123]
	s_setprio 0
	s_barrier
	s_add_i32 s52, 0, 0x14000
	v_add_u32_e32 v188, s52, v247
	s_add_i32 s47, s47, s36
	ds_read_b128 v[176:179], v188
	ds_read_b128 v[180:183], v188 offset:1024
	ds_read_b128 v[204:207], v188 offset:2048
	ds_read_b128 v[218:221], v188 offset:3072
	v_lshl_add_u64 v[188:189], s[24:25], 0, v[184:185]
	s_mov_b32 m0, s47
	v_lshl_add_u64 v[190:191], s[24:25], 0, v[212:213]
	global_load_lds_dwordx4 v[188:189], off
	s_add_i32 m0, s47, 0x2000
	s_nop 0
	global_load_lds_dwordx4 v[190:191], off
	s_barrier
	s_waitcnt lgkmcnt(0)
	s_setprio 1
	s_waitcnt lgkmcnt(0)
	v_mfma_f32_16x16x32_bf16 v[116:119], v[176:179], v[144:147], v[116:119]
	v_mfma_f32_16x16x32_bf16 v[116:119], v[180:183], v[148:151], v[116:119]
	v_mfma_f32_16x16x32_bf16 v[100:103], v[176:179], v[152:155], v[100:103]
	v_mfma_f32_16x16x32_bf16 v[100:103], v[180:183], v[156:159], v[100:103]
	v_mfma_f32_16x16x32_bf16 v[84:87], v[176:179], v[160:163], v[84:87]
	v_mfma_f32_16x16x32_bf16 v[84:87], v[180:183], v[164:167], v[84:87]
	v_mfma_f32_16x16x32_bf16 v[68:71], v[176:179], v[168:171], v[68:71]
	v_mfma_f32_16x16x32_bf16 v[68:71], v[180:183], v[172:175], v[68:71]
	v_mfma_f32_16x16x32_bf16 v[64:67], v[204:207], v[168:171], v[64:67]
	v_mfma_f32_16x16x32_bf16 v[64:67], v[218:221], v[172:175], v[64:67]
	v_mfma_f32_16x16x32_bf16 v[80:83], v[204:207], v[160:163], v[80:83]
	v_mfma_f32_16x16x32_bf16 v[80:83], v[218:221], v[164:167], v[80:83]
	v_mfma_f32_16x16x32_bf16 v[96:99], v[204:207], v[152:155], v[96:99]
	v_mfma_f32_16x16x32_bf16 v[96:99], v[218:221], v[156:159], v[96:99]
	v_mfma_f32_16x16x32_bf16 v[112:115], v[204:207], v[144:147], v[112:115]
	v_mfma_f32_16x16x32_bf16 v[112:115], v[218:221], v[148:151], v[112:115]
	s_setprio 0
	s_mov_b32 m0, s21
	v_lshl_add_u64 v[192:193], s[26:27], 0, v[208:209]
	s_barrier
	ds_read_b128 v[144:147], v249 offset:16384
	ds_read_b128 v[148:151], v249 offset:17408
	ds_read_b128 v[152:155], v249 offset:18432
	ds_read_b128 v[156:159], v249 offset:19456
	ds_read_b128 v[160:163], v249 offset:20480
	ds_read_b128 v[164:167], v249 offset:21504
	ds_read_b128 v[168:171], v249 offset:22528
	ds_read_b128 v[172:175], v249 offset:23552
	global_load_lds_dwordx4 v[192:193], off
	v_lshl_add_u64 v[222:223], s[26:27], 0, v[210:211]
	s_mov_b32 m0, s37
	s_nop 0
	global_load_lds_dwordx4 v[222:223], off
	s_barrier
	s_waitcnt lgkmcnt(0)
	s_setprio 1
	s_waitcnt lgkmcnt(0)
	v_mfma_f32_16x16x32_bf16 v[60:63], v[128:131], v[144:147], v[60:63]
	v_mfma_f32_16x16x32_bf16 v[60:63], v[132:135], v[148:151], v[60:63]
	v_mfma_f32_16x16x32_bf16 v[44:47], v[128:131], v[152:155], v[44:47]
	v_mfma_f32_16x16x32_bf16 v[44:47], v[132:135], v[156:159], v[44:47]
	v_mfma_f32_16x16x32_bf16 v[28:31], v[128:131], v[160:163], v[28:31]
	v_mfma_f32_16x16x32_bf16 v[28:31], v[132:135], v[164:167], v[28:31]
	v_mfma_f32_16x16x32_bf16 v[16:19], v[128:131], v[168:171], v[16:19]
	v_mfma_f32_16x16x32_bf16 v[16:19], v[132:135], v[172:175], v[16:19]
	v_mfma_f32_16x16x32_bf16 v[8:11], v[136:139], v[168:171], v[8:11]
	v_mfma_f32_16x16x32_bf16 v[8:11], v[140:143], v[172:175], v[8:11]
	v_mfma_f32_16x16x32_bf16 v[24:27], v[136:139], v[160:163], v[24:27]
	v_mfma_f32_16x16x32_bf16 v[24:27], v[140:143], v[164:167], v[24:27]
	v_mfma_f32_16x16x32_bf16 v[40:43], v[136:139], v[152:155], v[40:43]
	v_mfma_f32_16x16x32_bf16 v[40:43], v[140:143], v[156:159], v[40:43]
	v_mfma_f32_16x16x32_bf16 v[56:59], v[136:139], v[144:147], v[56:59]
	v_mfma_f32_16x16x32_bf16 v[56:59], v[140:143], v[148:151], v[56:59]
	s_setprio 0
	s_barrier
; #define PG8_STAGE(bufoff, gbase, voff) do { _Pragma("unroll") for (int _i = 0; _i < 2; ++_i) \
;         __builtin_amdgcn_global_load_lds((const unsigned*)((const char*)(gbase) + (voff)[_i]), (LAS unsigned*)(lds + (bufoff) + ldsw + _i * 8192), 16, 0, 0); } while (0)
; #define PG8_LDA(dst, b, h) do { _Pragma("unroll") for (int m = 0; m < 4; ++m) _Pragma("unroll") for (int k = 0; k < 2; ++k) dst[m][k] = *(const LAS bf16x8*)(lds + PG8_SA(b, h) + aoff + m * 2048 + k * 1024); } while (0)
; #define PG8_LDB(dst, b, h) do { _Pragma("unroll") for (int n = 0; n < 2; ++n) _Pragma("unroll") for (int k = 0; k < 2; ++k) dst[n][k] = *(const LAS bf16x8*)(lds + PG8_SB(b, h) + boff + n * 2048 + k * 1024); } while (0)
; #define PG8_MMA(ai, bj, At, Bt) do { __builtin_amdgcn_s_setprio(1); _Pragma("unroll") for (int m = 0; m < 4; ++m) _Pragma("unroll") for (int n = 0; n < 2; ++n) _Pragma("unroll") for (int k = 0; k < 2; ++k) \
;         acc[ai][bj][m][n] = __builtin_amdgcn_mfma_f32_16x16x32_bf16(Bt[n][k], At[m][k], acc[ai][bj][m][n], 0, 0, 0); __builtin_amdgcn_s_setprio(0); } while (0)
; #define PG8_WAIT_V(n) asm volatile("s_waitcnt vmcnt(" #n ")" ::: "memory")
; #define PG8_WAIT_L(n) asm volatile("s_waitcnt lgkmcnt(" #n ")" ::: "memory")
; #define PG8_BAR __builtin_amdgcn_s_barrier()
; #define PG8_SCHED __builtin_amdgcn_sched_barrier(0)
; template <class Epi>
; __device__ __forceinline__ void gemm_phase(LAS unsigned char* lds, const Gemm g, const StaticOrder& S, const Epi& E) {
;     ...
;             PG8_STAGE(PG8_SB(0, 1), b2 + hstep, voffB);
;             PG8_WAIT_V(6); PG8_BAR; PG8_MMA(1, 1, At, B1); PG8_BAR;
;             PG8_LDB(B0, 1, 0); PG8_SCHED; PG8_LDA(At, 1, 0); PG8_STAGE(PG8_SA(0, 1), a2 + hstep, voffA);
;             PG8_WAIT_L(8); PG8_BAR; PG8_WAIT_L(0); PG8_MMA(0, 0, At, B0); PG8_BAR; PG8_SCHED;
;             PG8_LDB(B1, 1, 1); PG8_STAGE(PG8_SB(1, 0), b3, voffB);
;             PG8_BAR; PG8_WAIT_L(0); PG8_MMA(0, 1, At, B1); PG8_BAR;
	s_add_u32 s50, s24, 0x40000
	s_addc_u32 s51, s25, 0
	s_add_i32 s47, s52, s36
	v_lshl_add_u64 v[128:129], s[50:51], 0, v[184:185]
	s_mov_b32 m0, s47
	s_nop 0
	global_load_lds_dwordx4 v[128:129], off
	v_lshl_add_u64 v[128:129], s[50:51], 0, v[212:213]
	s_add_i32 m0, s47, 0x2000
	s_nop 0
	global_load_lds_dwordx4 v[128:129], off
	s_waitcnt vmcnt(6)
	s_barrier
	s_setprio 1
	v_mfma_f32_16x16x32_bf16 v[52:55], v[176:179], v[144:147], v[52:55]
	v_mfma_f32_16x16x32_bf16 v[52:55], v[180:183], v[148:151], v[52:55]
	v_mfma_f32_16x16x32_bf16 v[36:39], v[176:179], v[152:155], v[36:39]
	v_mfma_f32_16x16x32_bf16 v[36:39], v[180:183], v[156:159], v[36:39]
	v_mfma_f32_16x16x32_bf16 v[20:23], v[176:179], v[160:163], v[20:23]
	v_mfma_f32_16x16x32_bf16 v[20:23], v[180:183], v[164:167], v[20:23]
	v_mfma_f32_16x16x32_bf16 v[4:7], v[176:179], v[168:171], v[4:7]
	v_mfma_f32_16x16x32_bf16 v[4:7], v[180:183], v[172:175], v[4:7]
	v_mfma_f32_16x16x32_bf16 v[0:3], v[204:207], v[168:171], v[0:3]
	v_mfma_f32_16x16x32_bf16 v[0:3], v[218:221], v[172:175], v[0:3]
	v_mfma_f32_16x16x32_bf16 v[12:15], v[204:207], v[160:163], v[12:15]
	v_mfma_f32_16x16x32_bf16 v[12:15], v[218:221], v[164:167], v[12:15]
	v_mfma_f32_16x16x32_bf16 v[32:35], v[204:207], v[152:155], v[32:35]
	v_mfma_f32_16x16x32_bf16 v[32:35], v[218:221], v[156:159], v[32:35]
	v_mfma_f32_16x16x32_bf16 v[48:51], v[204:207], v[144:147], v[48:51]
	v_mfma_f32_16x16x32_bf16 v[48:51], v[218:221], v[148:151], v[48:51]
	s_setprio 0
	s_add_i32 s47, 0, 0x18000
	v_add_u32_e32 v140, s47, v247
	s_barrier
	ds_read_b128 v[128:131], v140
	ds_read_b128 v[132:135], v140 offset:1024
	ds_read_b128 v[136:139], v140 offset:2048
	ds_read_b128 v[140:143], v140 offset:3072
	s_add_u32 s26, s26, 0x40000
	s_addc_u32 s27, s27, 0
	s_mov_b32 m0, s38
	v_lshl_add_u64 v[176:177], s[26:27], 0, v[208:209]
	ds_read_b128 v[144:147], v249 offset:32768
	ds_read_b128 v[148:151], v249 offset:33792
	ds_read_b128 v[152:155], v249 offset:34816
	ds_read_b128 v[156:159], v249 offset:35840
	ds_read_b128 v[160:163], v249 offset:36864
	ds_read_b128 v[164:167], v249 offset:37888
	ds_read_b128 v[168:171], v249 offset:38912
	ds_read_b128 v[172:175], v249 offset:39936
	global_load_lds_dwordx4 v[176:177], off
	v_lshl_add_u64 v[176:177], s[26:27], 0, v[210:211]
	s_mov_b32 m0, s39
	s_nop 0
	global_load_lds_dwordx4 v[176:177], off
	s_waitcnt lgkmcnt(8)
	s_barrier
	s_waitcnt lgkmcnt(0)
	s_setprio 1
	s_waitcnt lgkmcnt(0)
	v_mfma_f32_16x16x32_bf16 v[124:127], v[128:131], v[144:147], v[124:127]
	v_mfma_f32_16x16x32_bf16 v[124:127], v[132:135], v[148:151], v[124:127]
	v_mfma_f32_16x16x32_bf16 v[108:111], v[128:131], v[152:155], v[108:111]
	v_mfma_f32_16x16x32_bf16 v[108:111], v[132:135], v[156:159], v[108:111]
	v_mfma_f32_16x16x32_bf16 v[92:95], v[128:131], v[160:163], v[92:95]
	v_mfma_f32_16x16x32_bf16 v[92:95], v[132:135], v[164:167], v[92:95]
	v_mfma_f32_16x16x32_bf16 v[76:79], v[128:131], v[168:171], v[76:79]
	v_mfma_f32_16x16x32_bf16 v[76:79], v[132:135], v[172:175], v[76:79]
	v_mfma_f32_16x16x32_bf16 v[72:75], v[136:139], v[168:171], v[72:75]
	v_mfma_f32_16x16x32_bf16 v[72:75], v[140:143], v[172:175], v[72:75]
	v_mfma_f32_16x16x32_bf16 v[88:91], v[136:139], v[160:163], v[88:91]
	v_mfma_f32_16x16x32_bf16 v[88:91], v[140:143], v[164:167], v[88:91]
	v_mfma_f32_16x16x32_bf16 v[104:107], v[136:139], v[152:155], v[104:107]
	v_mfma_f32_16x16x32_bf16 v[104:107], v[140:143], v[156:159], v[104:107]
	v_mfma_f32_16x16x32_bf16 v[120:123], v[136:139], v[144:147], v[120:123]
	v_mfma_f32_16x16x32_bf16 v[120:123], v[140:143], v[148:151], v[120:123]
	s_setprio 0
	s_barrier
	s_add_i32 s26, 0, 0x1c000
	s_add_i32 s27, s47, s36
	v_add_u32_e32 v218, s26, v247
	v_lshl_add_u64 v[188:189], v[188:189], 0, s[58:59]
	s_mov_b32 m0, s27
	ds_read_b128 v[176:179], v218
	ds_read_b128 v[180:183], v218 offset:1024
	ds_read_b128 v[204:207], v218 offset:2048
	ds_read_b128 v[218:221], v218 offset:3072
	global_load_lds_dwordx4 v[188:189], off
	v_lshl_add_u64 v[188:189], v[190:191], 0, s[58:59]
	s_add_i32 m0, s27, 0x2000
	s_nop 0
	global_load_lds_dwordx4 v[188:189], off
	s_barrier
	s_waitcnt lgkmcnt(0)
	s_setprio 1
	s_waitcnt lgkmcnt(0)
	v_mfma_f32_16x16x32_bf16 v[116:119], v[176:179], v[144:147], v[116:119]
	v_mfma_f32_16x16x32_bf16 v[116:119], v[180:183], v[148:151], v[116:119]
	v_mfma_f32_16x16x32_bf16 v[100:103], v[176:179], v[152:155], v[100:103]
	v_mfma_f32_16x16x32_bf16 v[100:103], v[180:183], v[156:159], v[100:103]
	v_mfma_f32_16x16x32_bf16 v[84:87], v[176:179], v[160:163], v[84:87]
	v_mfma_f32_16x16x32_bf16 v[84:87], v[180:183], v[164:167], v[84:87]
	v_mfma_f32_16x16x32_bf16 v[68:71], v[176:179], v[168:171], v[68:71]
	v_mfma_f32_16x16x32_bf16 v[68:71], v[180:183], v[172:175], v[68:71]
	v_mfma_f32_16x16x32_bf16 v[64:67], v[204:207], v[168:171], v[64:67]
	v_mfma_f32_16x16x32_bf16 v[64:67], v[218:221], v[172:175], v[64:67]
	v_mfma_f32_16x16x32_bf16 v[80:83], v[204:207], v[160:163], v[80:83]
	v_mfma_f32_16x16x32_bf16 v[80:83], v[218:221], v[164:167], v[80:83]
	v_mfma_f32_16x16x32_bf16 v[96:99], v[204:207], v[152:155], v[96:99]
	v_mfma_f32_16x16x32_bf16 v[96:99], v[218:221], v[156:159], v[96:99]
	v_mfma_f32_16x16x32_bf16 v[112:115], v[204:207], v[144:147], v[112:115]
	v_mfma_f32_16x16x32_bf16 v[112:115], v[218:221], v[148:151], v[112:115]
	s_setprio 0
	s_mov_b32 m0, s41
	v_lshl_add_u64 v[188:189], v[192:193], 0, s[58:59]
	s_barrier
; #define PG8_STAGE(bufoff, gbase, voff) do { _Pragma("unroll") for (int _i = 0; _i < 2; ++_i) \
;         __builtin_amdgcn_global_load_lds((const unsigned*)((const char*)(gbase) + (voff)[_i]), (LAS unsigned*)(lds + (bufoff) + ldsw + _i * 8192), 16, 0, 0); } while (0)
; #define PG8_LDA(dst, b, h) do { _Pragma("unroll") for (int m = 0; m < 4; ++m) _Pragma("unroll") for (int k = 0; k < 2; ++k) dst[m][k] = *(const LAS bf16x8*)(lds + PG8_SA(b, h) + aoff + m * 2048 + k * 1024); } while (0)
; #define PG8_MMA(ai, bj, At, Bt) do { __builtin_amdgcn_s_setprio(1); _Pragma("unroll") for (int m = 0; m < 4; ++m) _Pragma("unroll") for (int n = 0; n < 2; ++n) _Pragma("unroll") for (int k = 0; k < 2; ++k) \
;         acc[ai][bj][m][n] = __builtin_amdgcn_mfma_f32_16x16x32_bf16(Bt[n][k], At[m][k], acc[ai][bj][m][n], 0, 0, 0); __builtin_amdgcn_s_setprio(0); } while (0)
; #define PG8_WAIT_V(n) asm volatile("s_waitcnt vmcnt(" #n ")" ::: "memory")
; #define PG8_WAIT_L(n) asm volatile("s_waitcnt lgkmcnt(" #n ")" ::: "memory")
; #define PG8_BAR __builtin_amdgcn_s_barrier()
; #define PG8_SCHED __builtin_amdgcn_sched_barrier(0)
; template <class Epi>
; __device__ __forceinline__ void gemm_phase(LAS unsigned char* lds, const Gemm g, const StaticOrder& S, const Epi& E) {
;     ...
;             PG8_LDA(At, 1, 1); PG8_STAGE(PG8_SA(1, 0), a3, voffA);
;             PG8_BAR; PG8_WAIT_L(0); PG8_MMA(1, 0, At, B0); PG8_BAR; PG8_SCHED;
;             PG8_STAGE(PG8_SB(1, 1), b3 + hstep, voffB);
;             PG8_WAIT_V(6); PG8_BAR; PG8_MMA(1, 1, At, B1); PG8_BAR;
;     __device__ __forceinline__ void operator()(const Acc& acc, const Unit& u, int wr, int wc, int fr, int fq) const {
;         const int row0 = u.pm * 256 + wr * 64 + fr, col0 = u.pn * 256 + wc * 32 + 8 * fq;
;         const bf16_t* __restrict__ gp = gate; bf16_t* __restrict__ mg = merged;
;         u32x4 gw[4][2], pw[2][2];
; #pragma unroll
;         for (int gidx = 0; gidx < 4; ++gidx)
; #pragma unroll
;             for (int bj = 0; bj < 2; ++bj) gw[gidx][bj] = *(const u32x4*)(gp + (size_t)(row0 + gidx * 16) * 4096 + col0 + bj * 128);
; #pragma unroll
;         for (int bj = 0; bj < 2; ++bj) pw[0][bj] = accum ? *(const u32x4*)(mg + (size_t)row0 * 2048 + col0 + bj * 128) : (u32x4){0u, 0u, 0u, 0u};
	ds_read_b128 v[144:147], v249 offset:49152
	ds_read_b128 v[148:151], v249 offset:50176
	ds_read_b128 v[152:155], v249 offset:51200
	ds_read_b128 v[156:159], v249 offset:52224
	ds_read_b128 v[160:163], v249 offset:53248
	ds_read_b128 v[164:167], v249 offset:54272
	ds_read_b128 v[168:171], v249 offset:55296
	ds_read_b128 v[172:175], v249 offset:56320
	global_load_lds_dwordx4 v[188:189], off
	v_lshl_add_u64 v[188:189], v[222:223], 0, s[58:59]
	s_mov_b32 m0, s42
	s_nop 0
	global_load_lds_dwordx4 v[188:189], off
	s_barrier
	s_waitcnt lgkmcnt(0)
	s_setprio 1
	s_waitcnt lgkmcnt(0)
	v_mfma_f32_16x16x32_bf16 v[60:63], v[128:131], v[144:147], v[60:63]
	v_mfma_f32_16x16x32_bf16 v[60:63], v[132:135], v[148:151], v[60:63]
	v_mfma_f32_16x16x32_bf16 v[44:47], v[128:131], v[152:155], v[44:47]
	v_mfma_f32_16x16x32_bf16 v[44:47], v[132:135], v[156:159], v[44:47]
	v_mfma_f32_16x16x32_bf16 v[28:31], v[128:131], v[160:163], v[28:31]
	v_mfma_f32_16x16x32_bf16 v[28:31], v[132:135], v[164:167], v[28:31]
	v_mfma_f32_16x16x32_bf16 v[16:19], v[128:131], v[168:171], v[16:19]
	v_mfma_f32_16x16x32_bf16 v[16:19], v[132:135], v[172:175], v[16:19]
	v_mfma_f32_16x16x32_bf16 v[8:11], v[136:139], v[168:171], v[8:11]
	v_mfma_f32_16x16x32_bf16 v[8:11], v[140:143], v[172:175], v[8:11]
	v_mfma_f32_16x16x32_bf16 v[24:27], v[136:139], v[160:163], v[24:27]
	v_mfma_f32_16x16x32_bf16 v[24:27], v[140:143], v[164:167], v[24:27]
	v_mfma_f32_16x16x32_bf16 v[40:43], v[136:139], v[152:155], v[40:43]
	v_mfma_f32_16x16x32_bf16 v[40:43], v[140:143], v[156:159], v[40:43]
	v_mfma_f32_16x16x32_bf16 v[56:59], v[136:139], v[144:147], v[56:59]
	v_mfma_f32_16x16x32_bf16 v[56:59], v[140:143], v[148:151], v[56:59]
	s_setprio 0
	s_barrier
	s_add_u32 s24, s24, 0x40080
	s_addc_u32 s25, s25, 0
	s_add_i32 s26, s26, s36
	v_lshl_add_u64 v[128:129], s[24:25], 0, v[184:185]
	s_mov_b32 m0, s26
	s_nop 0
	global_load_lds_dwordx4 v[128:129], off
	v_lshl_add_u64 v[128:129], s[24:25], 0, v[212:213]
	s_add_i32 m0, s26, 0x2000
	s_nop 0
	global_load_lds_dwordx4 v[128:129], off
	s_waitcnt vmcnt(6)
	s_barrier
	s_setprio 1
	v_mfma_f32_16x16x32_bf16 v[52:55], v[176:179], v[144:147], v[52:55]
	v_mfma_f32_16x16x32_bf16 v[52:55], v[180:183], v[148:151], v[52:55]
	v_mfma_f32_16x16x32_bf16 v[36:39], v[176:179], v[152:155], v[36:39]
	v_mfma_f32_16x16x32_bf16 v[36:39], v[180:183], v[156:159], v[36:39]
	v_mfma_f32_16x16x32_bf16 v[20:23], v[176:179], v[160:163], v[20:23]
	v_mfma_f32_16x16x32_bf16 v[20:23], v[180:183], v[164:167], v[20:23]
	v_mfma_f32_16x16x32_bf16 v[4:7], v[176:179], v[168:171], v[4:7]
	v_mfma_f32_16x16x32_bf16 v[4:7], v[180:183], v[172:175], v[4:7]
	v_mfma_f32_16x16x32_bf16 v[0:3], v[204:207], v[168:171], v[0:3]
	v_mfma_f32_16x16x32_bf16 v[0:3], v[218:221], v[172:175], v[0:3]
	v_mfma_f32_16x16x32_bf16 v[12:15], v[204:207], v[160:163], v[12:15]
	v_mfma_f32_16x16x32_bf16 v[12:15], v[218:221], v[164:167], v[12:15]
	v_mfma_f32_16x16x32_bf16 v[32:35], v[204:207], v[152:155], v[32:35]
	v_mfma_f32_16x16x32_bf16 v[32:35], v[218:221], v[156:159], v[32:35]
	v_mfma_f32_16x16x32_bf16 v[48:51], v[204:207], v[144:147], v[48:51]
	v_mfma_f32_16x16x32_bf16 v[48:51], v[218:221], v[148:151], v[48:51]
	s_setprio 0
	s_add_i32 s46, s46, 2
	s_add_u32 s22, s22, 0x100
	s_addc_u32 s23, s23, 0
	s_add_u32 s43, s43, 0x100
	s_addc_u32 s45, s45, 0
	s_cmp_gt_u32 s46, 13
	s_barrier
	s_cbranch_scc0 .LBB0_43
	v_lshl_or_b32 v128, s8, 8, v248
	v_lshl_add_u32 v222, s20, 8, v187
	v_ashrrev_i32_e32 v129, 31, v128
	v_lshlrev_b64 v[136:137], 1, v[128:129]
	v_ashrrev_i32_e32 v223, 31, v222
	v_lshl_add_u64 v[224:225], s[10:11], 0, v[136:137]
	v_lshlrev_b64 v[130:131], 13, v[222:223]
	v_lshl_add_u64 v[130:131], v[224:225], 0, v[130:131]
	global_load_dwordx4 v[176:179], v[130:131], off
	global_load_dwordx4 v[168:171], v[130:131], off offset:256
	v_or_b32_e32 v130, 16, v222
	v_ashrrev_i32_e32 v131, 31, v130
	v_lshlrev_b64 v[132:133], 13, v[130:131]
	v_or_b32_e32 v230, 32, v222
	v_lshl_add_u64 v[132:133], v[224:225], 0, v[132:133]
	v_ashrrev_i32_e32 v231, 31, v230
	global_load_dwordx4 v[156:159], v[132:133], off
	global_load_dwordx4 v[152:155], v[132:133], off offset:256
	v_lshlrev_b64 v[132:133], 13, v[230:231]
	v_or_b32_e32 v226, 48, v222
	v_lshl_add_u64 v[132:133], v[224:225], 0, v[132:133]
	v_ashrrev_i32_e32 v227, 31, v226
	global_load_dwordx4 v[148:151], v[132:133], off
	global_load_dwordx4 v[144:147], v[132:133], off offset:256
	v_lshlrev_b64 v[132:133], 13, v[226:227]
	v_lshl_add_u64 v[132:133], v[224:225], 0, v[132:133]
	global_load_dwordx4 v[140:143], v[132:133], off
	s_nop 0
	global_load_dwordx4 v[132:135], v[132:133], off offset:256
	v_lshlrev_b64 v[232:233], 12, v[222:223]
	v_lshl_add_u64 v[138:139], s[66:67], 0, v[232:233]
	v_lshl_add_u64 v[136:137], v[138:139], 0, v[136:137]
	v_cndmask_b32_e64 v138, 0, 1, s[0:1]
	v_mov_b32_e32 v172, 0
	v_cmp_ne_u32_e64 s[8:9], 1, v138
	s_andn2_b64 vcc, exec, s[0:1]
	v_mov_b32_e32 v180, 0
	v_mov_b32_e32 v181, 0
	v_mov_b32_e32 v182, 0
	v_mov_b32_e32 v183, 0
	s_cbranch_vccnz .LBB0_46
	global_load_dwordx4 v[180:183], v[136:137], off

; #define LAS __attribute__((address_space(3)))
; __device__ void mlstm_phase(const bf16_t* qk, const bf16_t* vo, const float* gates, const float* gate_b, bf16_t* hf, bf16_t* hb, unsigned char* shm) {
;     ...
;                 const int s = st * 16 + fr; const float cv = vec[64 + s];
;                 float sv[4];
; #pragma unroll
;                 for (int j = 0; j < 4; ++j) { const int t = tt * 16 + fq * 4 + j; sv[j] = (s <= t) ? acc[j] * __expf(vec[t] + cv) : 0.f; }
;                 const unsigned w01 = pk2(sv[0], sv[1]), w23 = pk2(sv[2], sv[3]);
;                 bf16_t* scp = SC + (tt * 16 + fq * 4) * 72 + s;
;                 scp[0] = (bf16_t)(w01 & 0xffff); scp[72] = (bf16_t)(w01 >> 16); scp[144] = (bf16_t)(w23 & 0xffff); scp[216] = (bf16_t)(w23 >> 16); }
;             { const float decay = vec[320];
; #pragma unroll
;               for (int dt = 0; dt < 2; ++dt)
; #pragma unroll
;                   for (int et = 0; et < 5; ++et) state[dt][et] = state[dt][et] * decay;
;               { u32x2 r000, r001, r010, r011, r100, r101, r110, r111;
;                 const unsigned kaddr = (unsigned)(size_t)(LAS unsigned char*)shm + ML_KS + (unsigned)(((fq * 8 + (fr >> 2)) * 264 + wid * 32 + 4 * (fr & 3)) * 2);
;                 asm volatile("ds_read_b64_tr_b16 %0, %8\n\tds_read_b64_tr_b16 %1, %8 offset:32\n\tds_read_b64_tr_b16 %2, %8 offset:2112\n\tds_read_b64_tr_b16 %3, %8 offset:2144\n\t"
;                              "ds_read_b64_tr_b16 %4, %8 offset:16896\n\tds_read_b64_tr_b16 %5, %8 offset:16928\n\tds_read_b64_tr_b16 %6, %8 offset:19008\n\tds_read_b64_tr_b16 %7, %8 offset:19040\n\t"
;                              "s_waitcnt lgkmcnt(0)"
;                              : "=&v"(r000), "=&v"(r001), "=&v"(r010), "=&v"(r011), "=&v"(r100), "=&v"(r101), "=&v"(r110), "=&v"(r111) : "v"(kaddr) : "memory");
;                 bf16x8 a[2][2];
;                 { const u32x4 t0 = (u32x4){r000.x, r000.y, r010.x, r010.y}; a[0][0] = *(const bf16x8*)&t0; const u32x4 t1 = (u32x4){r001.x, r001.y, r011.x, r011.y}; a[0][1] = *(const bf16x8*)&t1;
;                   const u32x4 t2 = (u32x4){r100.x, r100.y, r110.x, r110.y}; a[1][0] = *(const bf16x8*)&t2; const u32x4 t3 = (u32x4){r101.x, r101.y, r111.x, r111.y}; a[1][1] = *(const bf16x8*)&t3; }
; #pragma unroll
;                 for (int kk = 0; kk < 2; ++kk)
; #pragma unroll
.Lmle_t2_done:
	v_mov_b32_e32 v159, s76
	ds_read_b32 v150, v159 offset:1280
	s_waitcnt lgkmcnt(1)
	s_or_b64 vcc, s[0:1], s[84:85]
	s_and_b64 vcc, exec, vcc
	s_cbranch_vccnz .Lmle_exp
	v_mov_b32_e32 v126, 0
	ds_write_b16 v181, v126
	ds_write_b16 v181, v126 offset:144
	ds_write_b16 v181, v126 offset:288
	ds_write_b16 v181, v126 offset:432
	ds_write_b16 v182, v126
	ds_write_b16 v182, v126 offset:144
	ds_write_b16 v182, v126 offset:288
	ds_write_b16 v182, v126 offset:432
	s_branch .Lmle_exp_done
.Lmle_exp:
	v_add_f32_e32 v126, v124, v120
	v_add_f32_e32 v127, v124, v121
	v_add_f32_e32 v158, v124, v122
	v_add_f32_e32 v159, v124, v123
	v_mul_f32_e32 v126, 0x3fb8aa3b, v126
	v_mul_f32_e32 v127, 0x3fb8aa3b, v127
	v_mul_f32_e32 v158, 0x3fb8aa3b, v158
	v_mul_f32_e32 v159, 0x3fb8aa3b, v159
	v_exp_f32_e32 v126, v126
	v_exp_f32_e32 v127, v127
	v_exp_f32_e32 v158, v158
	v_exp_f32_e32 v159, v159
	v_mul_f32_e32 v126, v112, v126
	v_mul_f32_e32 v127, v113, v127
	v_mul_f32_e32 v158, v114, v158
	v_mul_f32_e32 v159, v115, v159
	v_cndmask_b32_e64 v126, 0, v126, s[78:79]
	v_cndmask_b32_e64 v127, 0, v127, s[92:93]
	v_cndmask_b32_e64 v158, 0, v158, s[28:29]
	v_cndmask_b32_e64 v159, 0, v159, s[30:31]
	v_cvt_pk_bf16_f32 v126, v126, v127
	v_cvt_pk_bf16_f32 v158, v158, v159
	ds_write_b16 v181, v126
	ds_write_b16_d16_hi v181, v126 offset:144
	ds_write_b16 v181, v158 offset:288
	ds_write_b16_d16_hi v181, v158 offset:432
	v_add_f32_e32 v126, v125, v120
	v_add_f32_e32 v127, v125, v121
	v_add_f32_e32 v158, v125, v122
	v_add_f32_e32 v159, v125, v123
	v_mul_f32_e32 v126, 0x3fb8aa3b, v126
	v_mul_f32_e32 v127, 0x3fb8aa3b, v127
	v_mul_f32_e32 v158, 0x3fb8aa3b, v158
	v_mul_f32_e32 v159, 0x3fb8aa3b, v159
	v_exp_f32_e32 v126, v126
	v_exp_f32_e32 v127, v127
	v_exp_f32_e32 v158, v158
	v_exp_f32_e32 v159, v159
	v_mul_f32_e32 v126, v116, v126
	v_mul_f32_e32 v127, v117, v127
	v_mul_f32_e32 v158, v118, v158
	v_mul_f32_e32 v159, v119, v159
	v_cndmask_b32_e64 v126, 0, v126, s[34:35]
	v_cndmask_b32_e64 v127, 0, v127, s[36:37]
	v_cndmask_b32_e64 v158, 0, v158, s[38:39]
	v_cndmask_b32_e64 v159, 0, v159, s[40:41]
	v_cvt_pk_bf16_f32 v126, v126, v127
	v_cvt_pk_bf16_f32 v158, v158, v159
	ds_write_b16 v182, v126
	ds_write_b16_d16_hi v182, v126 offset:144
	ds_write_b16 v182, v158 offset:288
	ds_write_b16_d16_hi v182, v158 offset:432
.Lmle_exp_done:
	s_or_b64 s[46:47], s[50:51], s[46:47]
	s_waitcnt lgkmcnt(8)
	v_pk_mul_f32 v[42:43], v[42:43], v[150:151] op_sel_hi:[1,0]
	v_pk_mul_f32 v[40:41], v[40:41], v[150:151] op_sel_hi:[1,0]
	v_pk_mul_f32 v[50:51], v[50:51], v[150:151] op_sel_hi:[1,0]
	v_pk_mul_f32 v[48:49], v[48:49], v[150:151] op_sel_hi:[1,0]
	v_pk_mul_f32 v[58:59], v[58:59], v[150:151] op_sel_hi:[1,0]
	v_pk_mul_f32 v[56:57], v[56:57], v[150:151] op_sel_hi:[1,0]
	v_pk_mul_f32 v[66:67], v[66:67], v[150:151] op_sel_hi:[1,0]
	v_pk_mul_f32 v[64:65], v[64:65], v[150:151] op_sel_hi:[1,0]
	v_pk_mul_f32 v[114:115], v[74:75], v[150:151] op_sel_hi:[1,0]
	v_pk_mul_f32 v[112:113], v[72:73], v[150:151] op_sel_hi:[1,0]
	v_pk_mul_f32 v[46:47], v[46:47], v[150:151] op_sel_hi:[1,0]
	v_pk_mul_f32 v[44:45], v[44:45], v[150:151] op_sel_hi:[1,0]
	v_pk_mul_f32 v[54:55], v[54:55], v[150:151] op_sel_hi:[1,0]
	v_pk_mul_f32 v[52:53], v[52:53], v[150:151] op_sel_hi:[1,0]
	v_pk_mul_f32 v[62:63], v[62:63], v[150:151] op_sel_hi:[1,0]
	v_pk_mul_f32 v[60:61], v[60:61], v[150:151] op_sel_hi:[1,0]
	v_pk_mul_f32 v[70:71], v[70:71], v[150:151] op_sel_hi:[1,0]
	v_pk_mul_f32 v[68:69], v[68:69], v[150:151] op_sel_hi:[1,0]
	v_pk_mul_f32 v[118:119], v[78:79], v[150:151] op_sel_hi:[1,0]
	v_pk_mul_f32 v[116:117], v[76:77], v[150:151] op_sel_hi:[1,0]
	ds_read_b64_tr_b16 v[124:125], v168
	ds_read_b64_tr_b16 v[120:121], v168 offset:32
	ds_read_b64_tr_b16 v[126:127], v168 offset:2112
	ds_read_b64_tr_b16 v[122:123], v168 offset:2144
	ds_read_b64_tr_b16 v[72:73], v168 offset:16896
	ds_read_b64_tr_b16 v[76:77], v168 offset:16928
	ds_read_b64_tr_b16 v[74:75], v168 offset:19008
	ds_read_b64_tr_b16 v[78:79], v168 offset:19040
	ds_read_b128 v[204:207], v215
	ds_read_b128 v[152:155], v215 offset:2304
	ds_read_b128 v[160:163], v215 offset:4608
	ds_read_b128 v[188:191], v215 offset:6912
	s_waitcnt lgkmcnt(3)
	v_mfma_f32_16x16x32_bf16 v[40:43], v[124:127], v[204:207], v[40:43]
	v_mfma_f32_16x16x32_bf16 v[44:47], v[120:123], v[204:207], v[44:47]
	ds_read_b128 v[204:207], v215 offset:9216
	s_waitcnt lgkmcnt(3)
	v_mfma_f32_16x16x32_bf16 v[48:51], v[124:127], v[152:155], v[48:51]
	v_mfma_f32_16x16x32_bf16 v[52:55], v[120:123], v[152:155], v[52:55]
	ds_read_b128 v[152:155], v215 offset:64
	s_waitcnt lgkmcnt(3)
	v_mfma_f32_16x16x32_bf16 v[56:59], v[124:127], v[160:163], v[56:59]
	v_mfma_f32_16x16x32_bf16 v[60:63], v[120:123], v[160:163], v[60:63]
	ds_read_b128 v[160:163], v215 offset:2368
	s_waitcnt lgkmcnt(3)
	v_mfma_f32_16x16x32_bf16 v[64:67], v[124:127], v[188:191], v[64:67]
	v_mfma_f32_16x16x32_bf16 v[68:71], v[120:123], v[188:191], v[68:71]
	ds_read_b128 v[188:191], v215 offset:4672
	s_waitcnt lgkmcnt(3)
	v_mfma_f32_16x16x32_bf16 v[112:115], v[124:127], v[204:207], v[112:115]
	v_mfma_f32_16x16x32_bf16 v[116:119], v[120:123], v[204:207], v[116:119]
	ds_read_b128 v[204:207], v215 offset:6976
	s_waitcnt lgkmcnt(3)
	v_mfma_f32_16x16x32_bf16 v[40:43], v[72:75], v[152:155], v[40:43]
	v_mfma_f32_16x16x32_bf16 v[44:47], v[76:79], v[152:155], v[44:47]
	ds_read_b128 v[152:155], v215 offset:9280
	s_waitcnt lgkmcnt(3)
	v_mfma_f32_16x16x32_bf16 v[48:51], v[72:75], v[160:163], v[48:51]
	v_mfma_f32_16x16x32_bf16 v[52:55], v[76:79], v[160:163], v[52:55]
	s_waitcnt lgkmcnt(2)
	v_mfma_f32_16x16x32_bf16 v[56:59], v[72:75], v[188:191], v[56:59]
	v_mfma_f32_16x16x32_bf16 v[60:63], v[76:79], v[188:191], v[60:63]
	s_waitcnt lgkmcnt(1)
	v_mfma_f32_16x16x32_bf16 v[64:67], v[72:75], v[204:207], v[64:67]
	v_mfma_f32_16x16x32_bf16 v[68:71], v[76:79], v[204:207], v[68:71]
	s_waitcnt lgkmcnt(0)
	v_mfma_f32_16x16x32_bf16 v[72:75], v[72:75], v[152:155], v[112:115]
	v_mfma_f32_16x16x32_bf16 v[76:79], v[76:79], v[152:155], v[116:119]
	s_and_b64 vcc, exec, s[46:47]
	s_cbranch_vccnz .LBB0_160
	s_nop 3
	v_add_f32_e32 v112, v224, v233
	s_mov_b32 s46, 0xbfb8aa3b
	v_mul_f32_e64 v113, |v112|, s46
	v_exp_f32_e32 v114, v113
	v_min_f32_e32 v115, 0, v112
	s_mov_b32 s46, 0x3f2aaaab
	s_bitcmp1_b32 s69, 0
	v_add_f32_e32 v116, 1.0, v114
	v_add_f32_e32 v112, -1.0, v116
	v_sub_f32_e32 v113, v112, v116
	v_sub_f32_e32 v112, v114, v112
	v_add_f32_e32 v113, 1.0, v113
	v_frexp_mant_f32_e32 v117, v116
	v_add_f32_e32 v118, v112, v113
	v_cvt_f64_f32_e32 v[112:113], v116
	v_frexp_exp_i32_f64_e32 v112, v[112:113]
	v_cmp_gt_f32_e32 vcc, s46, v117
	s_mov_b32 s46, 0x3f317218
	s_nop 0
	v_subbrev_co_u32_e32 v112, vcc, 0, v112, vcc
	v_sub_u32_e32 v113, 0, v112
	v_ldexp_f32 v116, v116, v113
	v_add_f32_e32 v117, -1.0, v116
	v_add_f32_e32 v120, 1.0, v116
	v_ldexp_f32 v113, v118, v113
	v_add_f32_e32 v118, 1.0, v117
	v_add_f32_e32 v121, -1.0, v120
	v_sub_f32_e32 v118, v116, v118
	v_sub_f32_e32 v116, v116, v121
	v_add_f32_e32 v118, v113, v118
	v_add_f32_e32 v113, v113, v116
	v_add_f32_e32 v116, v120, v113
	v_rcp_f32_e32 v121, v116
	v_add_f32_e32 v119, v117, v118
	v_sub_f32_e32 v117, v119, v117
	v_sub_f32_e32 v117, v118, v117
	v_sub_f32_e32 v118, v116, v120
	v_sub_f32_e32 v113, v113, v118
	v_mul_f32_e32 v118, v119, v121
	v_mul_f32_e32 v120, v116, v118
	v_fma_f32 v122, v118, v116, -v120
	v_fmac_f32_e32 v122, v118, v113
	v_add_f32_e32 v123, v120, v122
	v_sub_f32_e32 v124, v119, v123
	v_sub_f32_e32 v119, v119, v124
	v_sub_f32_e32 v120, v123, v120
	v_sub_f32_e32 v119, v119, v123
	v_add_f32_e32 v117, v117, v119
	v_sub_f32_e32 v119, v120, v122
	v_add_f32_e32 v117, v119, v117
	v_add_f32_e32 v119, v124, v117
	v_mul_f32_e32 v120, v121, v119
	v_mul_f32_e32 v122, v116, v120
	v_fma_f32 v116, v120, v116, -v122
	v_fmac_f32_e32 v116, v120, v113
	v_sub_f32_e32 v113, v124, v119
	v_add_f32_e32 v113, v117, v113
	v_add_f32_e32 v117, v122, v116
	v_sub_f32_e32 v123, v119, v117
	v_sub_f32_e32 v119, v119, v123
	v_sub_f32_e32 v122, v117, v122
	v_sub_f32_e32 v117, v119, v117
	v_add_f32_e32 v113, v113, v117
	v_sub_f32_e32 v116, v122, v116
	v_cvt_f32_i32_e32 v112, v112
	v_add_f32_e32 v113, v116, v113
	v_add_f32_e32 v116, v118, v120
	v_add_f32_e32 v113, v123, v113
	v_sub_f32_e32 v117, v116, v118
	v_mul_f32_e32 v113, v121, v113
	v_sub_f32_e32 v117, v120, v117
	v_add_f32_e32 v113, v117, v113
	v_mul_f32_e32 v120, 0x3f317218, v112
	v_add_f32_e32 v117, v116, v113
	v_fma_f32 v121, v112, s46, -v120
	v_mul_f32_e32 v118, v117, v117
	v_fmac_f32_e32 v121, 0xb102e308, v112
	v_sub_f32_e32 v112, v117, v116
	v_fmamk_f32 v119, v118, 0x3e9b6dac, v235
	v_sub_f32_e32 v112, v113, v112
	v_add_f32_e32 v113, v120, v121
	v_fmaak_f32 v119, v118, v119, 0x3f2aaada
	v_sub_f32_e32 v116, v113, v120
	v_ldexp_f32 v120, v117, 1
	v_mul_f32_e32 v117, v117, v118
	v_mul_f32_e32 v117, v117, v119
	v_add_f32_e32 v118, v120, v117
	v_sub_f32_e32 v119, v118, v120
	v_ldexp_f32 v112, v112, 1
	v_sub_f32_e32 v117, v117, v119
	v_add_f32_e32 v112, v112, v117
	v_add_f32_e32 v117, v118, v112
	v_sub_f32_e32 v118, v117, v118
	v_sub_f32_e32 v112, v112, v118
	v_add_f32_e32 v118, v113, v117
	v_sub_f32_e32 v119, v118, v113
	v_sub_f32_e32 v120, v118, v119
	v_sub_f32_e32 v116, v121, v116
	v_sub_f32_e32 v113, v113, v120
	v_sub_f32_e32 v117, v117, v119
	v_add_f32_e32 v113, v117, v113
	v_add_f32_e32 v117, v116, v112
	v_sub_f32_e32 v119, v117, v116
	v_sub_f32_e32 v120, v117, v119
	v_sub_f32_e32 v116, v116, v120
	v_sub_f32_e32 v112, v112, v119
	v_add_f32_e32 v113, v117, v113
	v_add_f32_e32 v112, v112, v116
	v_add_f32_e32 v116, v118, v113
	v_sub_f32_e32 v117, v116, v118
	v_sub_f32_e32 v113, v113, v117
	v_add_f32_e32 v112, v112, v113
	s_mov_b32 s46, 0x7f800000
	v_add_f32_e32 v112, v116, v112
	v_cmp_neq_f32_e32 vcc, s46, v114
	s_mov_b32 s46, 0x33800000
	v_and_b32_e32 v113, 64, v240
	v_cndmask_b32_e32 v112, v242, v112, vcc
	v_cmp_ngt_f32_e32 vcc, -1.0, v114
	s_nop 1
	v_cndmask_b32_e32 v112, v243, v112, vcc
	v_cmp_neq_f32_e32 vcc, -1.0, v114
	s_nop 1
	v_cndmask_b32_e32 v112, v244, v112, vcc
	v_cmp_lt_f32_e64 vcc, |v114|, s46
	s_cselect_b32 s46, 0x520, 0
	s_nop 0
	v_cndmask_b32_e32 v112, v112, v114, vcc
	v_sub_f32_e32 v112, v115, v112
	s_add_i32 vcc_lo, s46, 0
	s_add_i32 vcc_lo, vcc_lo, 0x1da00
	s_nop 1
	v_add_f32_dpp v112, v112, v112 row_shr:1 row_mask:0xf bank_mask:0xf
	s_nop 1
	v_add_f32_dpp v112, v112, v112 row_shr:2 row_mask:0xf bank_mask:0xf
	s_nop 1
	v_add_f32_dpp v112, v112, v112 row_shr:4 row_mask:0xf bank_mask:0xf
	s_nop 1
	v_add_f32_dpp v112, v112, v112 row_shr:8 row_mask:0xf bank_mask:0xf
	s_nop 1
	v_add_f32_dpp v112, v112, v112 row_bcast:15 row_mask:0xa bank_mask:0xf
	s_nop 1
	v_add_f32_dpp v112, v112, v112 row_bcast:31 row_mask:0xc bank_mask:0xf
	v_mov_b32_e32 v119, v112
	v_add_f32_e32 v112, v223, v232
	v_sub_f32_e32 v120, v112, v119
	v_max_f32_e32 v114, v120, v120
	s_nop 1
	v_max_f32_dpp v114, v114, v114 row_shr:1 row_mask:0xf bank_mask:0xf
	s_nop 1
	v_max_f32_dpp v114, v114, v114 row_shr:2 row_mask:0xf bank_mask:0xf
	s_nop 1
	v_max_f32_dpp v114, v114, v114 row_shr:4 row_mask:0xf bank_mask:0xf
	s_nop 1
	v_max_f32_dpp v114, v114, v114 row_shr:8 row_mask:0xf bank_mask:0xf
	s_nop 1
	v_max_f32_dpp v114, v114, v114 row_bcast:15 row_mask:0xa bank_mask:0xf
	s_nop 1
	v_max_f32_dpp v114, v114, v114 row_bcast:31 row_mask:0xc bank_mask:0xf
	v_max_f32_e32 v115, v231, v231
	v_lshl_add_u32 v118, v131, 2, vcc_lo
	s_nop 0
	v_readlane_b32 s46, v114, 63
	v_readlane_b32 s47, v119, 63
	v_max_f32_e64 v114, -v114, -v114
	s_nop 1
	v_mov_b32_e32 v113, s46
	v_mov_b32_e32 v112, s47
	v_max_f32_e32 v113, v115, v113
	v_max_f32_e64 v115, -v231, -v231
	v_min_f32_e32 v114, v115, v114
	v_add_f32_e32 v115, v231, v114
	v_sub_f32_e32 v116, v119, v114
	v_mul_f32_e32 v115, 0x3fb8aa3b, v115
	v_mul_f32_e32 v116, 0xbfb8aa3b, v116
	v_sub_f32_e32 v117, v120, v113
	v_exp_f32_e32 v115, v115
	v_exp_f32_e32 v116, v116
	v_mul_f32_e32 v117, 0x3fb8aa3b, v117
	v_exp_f32_e32 v117, v117
	ds_write2st64_b32 v118, v114, v120 offset1:1
	ds_write2st64_b32 v118, v115, v116 offset0:2 offset1:3
	ds_write_b32 v118, v117 offset:1024
	s_and_saveexec_b64 s[46:47], s[10:11]
	s_cbranch_execz .LBB0_157
	v_sub_f32_e32 v114, v231, v113
	v_mul_f32_e32 v114, 0x3fb8aa3b, v114
	v_exp_f32_e32 v114, v114
	v_mov_b32_e32 v115, vcc_lo
	ds_write_b32 v115, v114 offset:1280

; #define PG8_STAGE(bufoff, gbase, voff) do { _Pragma("unroll") for (int _i = 0; _i < 2; ++_i) \
;         __builtin_amdgcn_global_load_lds((const unsigned*)((const char*)(gbase) + (voff)[_i]), (LAS unsigned*)(lds + (bufoff) + ldsw + _i * 8192), 16, 0, 0); } while (0)
; #define PG8_LDA(dst, b, h) do { _Pragma("unroll") for (int m = 0; m < 4; ++m) _Pragma("unroll") for (int k = 0; k < 2; ++k) dst[m][k] = *(const LAS bf16x8*)(lds + PG8_SA(b, h) + aoff + m * 2048 + k * 1024); } while (0)
; #define PG8_LDB(dst, b, h) do { _Pragma("unroll") for (int n = 0; n < 2; ++n) _Pragma("unroll") for (int k = 0; k < 2; ++k) dst[n][k] = *(const LAS bf16x8*)(lds + PG8_SB(b, h) + boff + n * 2048 + k * 1024); } while (0)
; #define PG8_MMA(ai, bj, At, Bt) do { __builtin_amdgcn_s_setprio(1); _Pragma("unroll") for (int m = 0; m < 4; ++m) _Pragma("unroll") for (int n = 0; n < 2; ++n) _Pragma("unroll") for (int k = 0; k < 2; ++k) \
;         acc[ai][bj][m][n] = __builtin_amdgcn_mfma_f32_16x16x32_bf16(Bt[n][k], At[m][k], acc[ai][bj][m][n], 0, 0, 0); __builtin_amdgcn_s_setprio(0); } while (0)
; #define PG8_WAIT_L(n) asm volatile("s_waitcnt lgkmcnt(" #n ")" ::: "memory")
; #define PG8_BAR __builtin_amdgcn_s_barrier()
; #define PG8_SCHED __builtin_amdgcn_sched_barrier(0)
; template <class Epi>
; __device__ __forceinline__ void gemm_phase(LAS unsigned char* lds, const Gemm g, const StaticOrder& S, const Epi& E) {
;     ...
;             PG8_LDB(B0, 0, 0); PG8_SCHED; PG8_LDA(At, 0, 0); PG8_STAGE(PG8_SA(1, 1), a1 + hstep, voffA);
;             PG8_WAIT_L(8); PG8_BAR; PG8_WAIT_L(0); PG8_MMA(0, 0, At, B0); PG8_BAR; PG8_SCHED;
;             PG8_LDB(B1, 0, 1); PG8_STAGE(PG8_SB(0, 0), b2, voffB);
;             PG8_BAR; PG8_WAIT_L(0); PG8_MMA(0, 1, At, B1); PG8_BAR;
;             PG8_LDA(At, 0, 1); PG8_STAGE(PG8_SA(0, 0), a2, voffA);
;             PG8_BAR; PG8_WAIT_L(0); PG8_MMA(1, 0, At, B0); PG8_BAR; PG8_SCHED;
.LBB0_366:
	s_add_u32 s28, s26, 0xfff80080
	s_addc_u32 s29, s27, -1
	s_add_i32 s47, 0, 0x10000
	v_add_u32_e32 v154, s47, v143
	ds_read_b128 v[138:141], v154
	ds_read_b128 v[146:149], v154 offset:1024
	ds_read_b128 v[150:153], v154 offset:2048
	ds_read_b128 v[154:157], v154 offset:3072
	s_cmp_eq_u32 s43, 28
	s_cselect_b32 s31, s3, s29
	s_cselect_b32 s30, s9, s28
	s_cselect_b32 s29, s1, s35
	s_cselect_b32 s28, s19, s34
	v_lshl_add_u64 v[182:183], s[26:27], 0, v[134:135]
	s_add_i32 m0, s25, 0xc000
	ds_read_b128 v[158:161], v145
	ds_read_b128 v[162:165], v145 offset:1024
	ds_read_b128 v[166:169], v145 offset:2048
	ds_read_b128 v[170:173], v145 offset:3072
	ds_read_b128 v[174:177], v145 offset:4096
	ds_read_b128 v[178:181], v145 offset:5120
	ds_read_b128 v[204:207], v145 offset:6144
	ds_read_b128 v[208:211], v145 offset:7168
	global_load_lds_dwordx4 v[182:183], off
	v_lshl_add_u64 v[182:183], s[26:27], 0, v[136:137]
	s_add_i32 m0, s25, 0xe000
	s_nop 0
	global_load_lds_dwordx4 v[182:183], off
	s_waitcnt lgkmcnt(8)
	s_barrier
	s_waitcnt lgkmcnt(0)
	s_setprio 1
	s_waitcnt lgkmcnt(0)
	v_mfma_f32_16x16x32_bf16 v[124:127], v[138:141], v[158:161], v[124:127]
	v_mfma_f32_16x16x32_bf16 v[124:127], v[146:149], v[162:165], v[124:127]
	v_mfma_f32_16x16x32_bf16 v[108:111], v[138:141], v[166:169], v[108:111]
	v_mfma_f32_16x16x32_bf16 v[108:111], v[146:149], v[170:173], v[108:111]
	v_mfma_f32_16x16x32_bf16 v[92:95], v[138:141], v[174:177], v[92:95]
	v_mfma_f32_16x16x32_bf16 v[92:95], v[146:149], v[178:181], v[92:95]
	v_mfma_f32_16x16x32_bf16 v[76:79], v[138:141], v[204:207], v[76:79]
	v_mfma_f32_16x16x32_bf16 v[76:79], v[146:149], v[208:211], v[76:79]
	v_mfma_f32_16x16x32_bf16 v[72:75], v[150:153], v[204:207], v[72:75]
	v_mfma_f32_16x16x32_bf16 v[72:75], v[154:157], v[208:211], v[72:75]
	v_mfma_f32_16x16x32_bf16 v[88:91], v[150:153], v[174:177], v[88:91]
	v_mfma_f32_16x16x32_bf16 v[88:91], v[154:157], v[178:181], v[88:91]
	v_mfma_f32_16x16x32_bf16 v[104:107], v[150:153], v[166:169], v[104:107]
	v_mfma_f32_16x16x32_bf16 v[104:107], v[154:157], v[170:173], v[104:107]
	v_mfma_f32_16x16x32_bf16 v[120:123], v[150:153], v[158:161], v[120:123]
	v_mfma_f32_16x16x32_bf16 v[120:123], v[154:157], v[162:165], v[120:123]
	s_setprio 0
	s_barrier
	s_add_i32 s52, 0, 0x14000
	v_add_u32_e32 v182, s52, v143
	s_add_i32 s47, s47, s38
	ds_read_b128 v[212:215], v182
	ds_read_b128 v[216:219], v182 offset:1024
	ds_read_b128 v[220:223], v182 offset:2048
	ds_read_b128 v[224:227], v182 offset:3072
	v_lshl_add_u64 v[182:183], s[28:29], 0, v[184:185]
	s_mov_b32 m0, s47
	v_lshl_add_u64 v[188:189], s[28:29], 0, v[132:133]
	global_load_lds_dwordx4 v[182:183], off
	s_add_i32 m0, s47, 0x2000
	s_nop 0
	global_load_lds_dwordx4 v[188:189], off
	s_barrier
	s_waitcnt lgkmcnt(0)
	s_setprio 1
	s_waitcnt lgkmcnt(0)
	v_mfma_f32_16x16x32_bf16 v[116:119], v[212:215], v[158:161], v[116:119]
	v_mfma_f32_16x16x32_bf16 v[116:119], v[216:219], v[162:165], v[116:119]
	v_mfma_f32_16x16x32_bf16 v[100:103], v[212:215], v[166:169], v[100:103]
	v_mfma_f32_16x16x32_bf16 v[100:103], v[216:219], v[170:173], v[100:103]
	v_mfma_f32_16x16x32_bf16 v[84:87], v[212:215], v[174:177], v[84:87]
	v_mfma_f32_16x16x32_bf16 v[84:87], v[216:219], v[178:181], v[84:87]
	v_mfma_f32_16x16x32_bf16 v[68:71], v[212:215], v[204:207], v[68:71]
	v_mfma_f32_16x16x32_bf16 v[68:71], v[216:219], v[208:211], v[68:71]
	v_mfma_f32_16x16x32_bf16 v[64:67], v[220:223], v[204:207], v[64:67]
	v_mfma_f32_16x16x32_bf16 v[64:67], v[224:227], v[208:211], v[64:67]
	v_mfma_f32_16x16x32_bf16 v[80:83], v[220:223], v[174:177], v[80:83]
	v_mfma_f32_16x16x32_bf16 v[80:83], v[224:227], v[178:181], v[80:83]
	v_mfma_f32_16x16x32_bf16 v[96:99], v[220:223], v[166:169], v[96:99]
	v_mfma_f32_16x16x32_bf16 v[96:99], v[224:227], v[170:173], v[96:99]
	v_mfma_f32_16x16x32_bf16 v[112:115], v[220:223], v[158:161], v[112:115]
	v_mfma_f32_16x16x32_bf16 v[112:115], v[224:227], v[162:165], v[112:115]
	s_setprio 0
	s_mov_b32 m0, s25
	v_lshl_add_u64 v[190:191], s[30:31], 0, v[128:129]
	s_barrier
	ds_read_b128 v[158:161], v145 offset:16384
	ds_read_b128 v[162:165], v145 offset:17408
	ds_read_b128 v[166:169], v145 offset:18432
	ds_read_b128 v[170:173], v145 offset:19456
	ds_read_b128 v[174:177], v145 offset:20480
	ds_read_b128 v[178:181], v145 offset:21504
	ds_read_b128 v[204:207], v145 offset:22528
	ds_read_b128 v[208:211], v145 offset:23552
	global_load_lds_dwordx4 v[190:191], off
	v_lshl_add_u64 v[192:193], s[30:31], 0, v[130:131]
	s_mov_b32 m0, s39
	s_nop 0
	global_load_lds_dwordx4 v[192:193], off
	s_barrier
	s_waitcnt lgkmcnt(0)
	s_setprio 1
	s_waitcnt lgkmcnt(0)
	v_mfma_f32_16x16x32_bf16 v[60:63], v[138:141], v[158:161], v[60:63]
	v_mfma_f32_16x16x32_bf16 v[60:63], v[146:149], v[162:165], v[60:63]
	v_mfma_f32_16x16x32_bf16 v[44:47], v[138:141], v[166:169], v[44:47]
	v_mfma_f32_16x16x32_bf16 v[44:47], v[146:149], v[170:173], v[44:47]
	v_mfma_f32_16x16x32_bf16 v[28:31], v[138:141], v[174:177], v[28:31]
	v_mfma_f32_16x16x32_bf16 v[28:31], v[146:149], v[178:181], v[28:31]
	v_mfma_f32_16x16x32_bf16 v[12:15], v[138:141], v[204:207], v[12:15]
	v_mfma_f32_16x16x32_bf16 v[12:15], v[146:149], v[208:211], v[12:15]
	v_mfma_f32_16x16x32_bf16 v[8:11], v[150:153], v[204:207], v[8:11]
	v_mfma_f32_16x16x32_bf16 v[8:11], v[154:157], v[208:211], v[8:11]
	v_mfma_f32_16x16x32_bf16 v[24:27], v[150:153], v[174:177], v[24:27]
	v_mfma_f32_16x16x32_bf16 v[24:27], v[154:157], v[178:181], v[24:27]
	v_mfma_f32_16x16x32_bf16 v[40:43], v[150:153], v[166:169], v[40:43]
	v_mfma_f32_16x16x32_bf16 v[40:43], v[154:157], v[170:173], v[40:43]
	v_mfma_f32_16x16x32_bf16 v[56:59], v[150:153], v[158:161], v[56:59]
	v_mfma_f32_16x16x32_bf16 v[56:59], v[154:157], v[162:165], v[56:59]
	s_setprio 0
	s_barrier
; #define PG8_STAGE(bufoff, gbase, voff) do { _Pragma("unroll") for (int _i = 0; _i < 2; ++_i) \
;         __builtin_amdgcn_global_load_lds((const unsigned*)((const char*)(gbase) + (voff)[_i]), (LAS unsigned*)(lds + (bufoff) + ldsw + _i * 8192), 16, 0, 0); } while (0)
; #define PG8_LDA(dst, b, h) do { _Pragma("unroll") for (int m = 0; m < 4; ++m) _Pragma("unroll") for (int k = 0; k < 2; ++k) dst[m][k] = *(const LAS bf16x8*)(lds + PG8_SA(b, h) + aoff + m * 2048 + k * 1024); } while (0)
; #define PG8_LDB(dst, b, h) do { _Pragma("unroll") for (int n = 0; n < 2; ++n) _Pragma("unroll") for (int k = 0; k < 2; ++k) dst[n][k] = *(const LAS bf16x8*)(lds + PG8_SB(b, h) + boff + n * 2048 + k * 1024); } while (0)
; #define PG8_MMA(ai, bj, At, Bt) do { __builtin_amdgcn_s_setprio(1); _Pragma("unroll") for (int m = 0; m < 4; ++m) _Pragma("unroll") for (int n = 0; n < 2; ++n) _Pragma("unroll") for (int k = 0; k < 2; ++k) \
;         acc[ai][bj][m][n] = __builtin_amdgcn_mfma_f32_16x16x32_bf16(Bt[n][k], At[m][k], acc[ai][bj][m][n], 0, 0, 0); __builtin_amdgcn_s_setprio(0); } while (0)
; #define PG8_WAIT_V(n) asm volatile("s_waitcnt vmcnt(" #n ")" ::: "memory")
; #define PG8_WAIT_L(n) asm volatile("s_waitcnt lgkmcnt(" #n ")" ::: "memory")
; #define PG8_BAR __builtin_amdgcn_s_barrier()
; #define PG8_SCHED __builtin_amdgcn_sched_barrier(0)
; template <class Epi>
; __device__ __forceinline__ void gemm_phase(LAS unsigned char* lds, const Gemm g, const StaticOrder& S, const Epi& E) {
;     ...
;             PG8_LDA(At, 0, 1); PG8_STAGE(PG8_SA(0, 0), a2, voffA);
;             PG8_BAR; PG8_WAIT_L(0); PG8_MMA(1, 0, At, B0); PG8_BAR; PG8_SCHED;
;             PG8_STAGE(PG8_SB(0, 1), b2 + hstep, voffB);
;             PG8_WAIT_V(6); PG8_BAR; PG8_MMA(1, 1, At, B1); PG8_BAR;
;             PG8_LDB(B0, 1, 0); PG8_SCHED; PG8_LDA(At, 1, 0); PG8_STAGE(PG8_SA(0, 1), a2 + hstep, voffA);
;             PG8_WAIT_L(8); PG8_BAR; PG8_WAIT_L(0); PG8_MMA(0, 0, At, B0); PG8_BAR; PG8_SCHED;
	s_add_u32 s50, s28, 0x80000
	s_addc_u32 s51, s29, 0
	s_add_i32 s47, s52, s38
	v_lshl_add_u64 v[138:139], s[50:51], 0, v[184:185]
	s_mov_b32 m0, s47
	s_nop 0
	global_load_lds_dwordx4 v[138:139], off
	v_lshl_add_u64 v[138:139], s[50:51], 0, v[132:133]
	s_add_i32 m0, s47, 0x2000
	s_nop 0
	global_load_lds_dwordx4 v[138:139], off
	s_waitcnt vmcnt(6)
	s_barrier
	s_setprio 1
	v_mfma_f32_16x16x32_bf16 v[52:55], v[212:215], v[158:161], v[52:55]
	v_mfma_f32_16x16x32_bf16 v[52:55], v[216:219], v[162:165], v[52:55]
	v_mfma_f32_16x16x32_bf16 v[36:39], v[212:215], v[166:169], v[36:39]
	v_mfma_f32_16x16x32_bf16 v[36:39], v[216:219], v[170:173], v[36:39]
	v_mfma_f32_16x16x32_bf16 v[20:23], v[212:215], v[174:177], v[20:23]
	v_mfma_f32_16x16x32_bf16 v[20:23], v[216:219], v[178:181], v[20:23]
	v_mfma_f32_16x16x32_bf16 v[4:7], v[212:215], v[204:207], v[4:7]
	v_mfma_f32_16x16x32_bf16 v[4:7], v[216:219], v[208:211], v[4:7]
	v_mfma_f32_16x16x32_bf16 v[0:3], v[220:223], v[204:207], v[0:3]
	v_mfma_f32_16x16x32_bf16 v[0:3], v[224:227], v[208:211], v[0:3]
	v_mfma_f32_16x16x32_bf16 v[16:19], v[220:223], v[174:177], v[16:19]
	v_mfma_f32_16x16x32_bf16 v[16:19], v[224:227], v[178:181], v[16:19]
	v_mfma_f32_16x16x32_bf16 v[32:35], v[220:223], v[166:169], v[32:35]
	v_mfma_f32_16x16x32_bf16 v[32:35], v[224:227], v[170:173], v[32:35]
	v_mfma_f32_16x16x32_bf16 v[48:51], v[220:223], v[158:161], v[48:51]
	v_mfma_f32_16x16x32_bf16 v[48:51], v[224:227], v[162:165], v[48:51]
	s_setprio 0
	s_add_i32 s47, 0, 0x18000
	v_add_u32_e32 v154, s47, v143
	s_barrier
	ds_read_b128 v[138:141], v154
	ds_read_b128 v[146:149], v154 offset:1024
	ds_read_b128 v[150:153], v154 offset:2048
	ds_read_b128 v[154:157], v154 offset:3072
	s_add_u32 s30, s30, 0x80000
	s_addc_u32 s31, s31, 0
	s_mov_b32 m0, s40
	v_lshl_add_u64 v[212:213], s[30:31], 0, v[128:129]
	ds_read_b128 v[158:161], v145 offset:32768
	ds_read_b128 v[162:165], v145 offset:33792
	ds_read_b128 v[166:169], v145 offset:34816
	ds_read_b128 v[170:173], v145 offset:35840
	ds_read_b128 v[174:177], v145 offset:36864
	ds_read_b128 v[178:181], v145 offset:37888
	ds_read_b128 v[204:207], v145 offset:38912
	ds_read_b128 v[208:211], v145 offset:39936
	global_load_lds_dwordx4 v[212:213], off
	v_lshl_add_u64 v[212:213], s[30:31], 0, v[130:131]
	s_mov_b32 m0, s41
	s_nop 0
	global_load_lds_dwordx4 v[212:213], off
	s_waitcnt lgkmcnt(8)
	s_barrier
	s_waitcnt lgkmcnt(0)
	s_setprio 1
	s_waitcnt lgkmcnt(0)
	v_mfma_f32_16x16x32_bf16 v[124:127], v[138:141], v[158:161], v[124:127]
	v_mfma_f32_16x16x32_bf16 v[124:127], v[146:149], v[162:165], v[124:127]
	v_mfma_f32_16x16x32_bf16 v[108:111], v[138:141], v[166:169], v[108:111]
	v_mfma_f32_16x16x32_bf16 v[108:111], v[146:149], v[170:173], v[108:111]
	v_mfma_f32_16x16x32_bf16 v[92:95], v[138:141], v[174:177], v[92:95]
	v_mfma_f32_16x16x32_bf16 v[92:95], v[146:149], v[178:181], v[92:95]
	v_mfma_f32_16x16x32_bf16 v[76:79], v[138:141], v[204:207], v[76:79]
	v_mfma_f32_16x16x32_bf16 v[76:79], v[146:149], v[208:211], v[76:79]
	v_mfma_f32_16x16x32_bf16 v[72:75], v[150:153], v[204:207], v[72:75]
	v_mfma_f32_16x16x32_bf16 v[72:75], v[154:157], v[208:211], v[72:75]
	v_mfma_f32_16x16x32_bf16 v[88:91], v[150:153], v[174:177], v[88:91]
	v_mfma_f32_16x16x32_bf16 v[88:91], v[154:157], v[178:181], v[88:91]
	v_mfma_f32_16x16x32_bf16 v[104:107], v[150:153], v[166:169], v[104:107]
	v_mfma_f32_16x16x32_bf16 v[104:107], v[154:157], v[170:173], v[104:107]
	v_mfma_f32_16x16x32_bf16 v[120:123], v[150:153], v[158:161], v[120:123]
	v_mfma_f32_16x16x32_bf16 v[120:123], v[154:157], v[162:165], v[120:123]
	s_setprio 0
	s_barrier
	s_add_i32 s30, 0, 0x1c000
	s_add_i32 s31, s47, s38
	v_add_u32_e32 v187, s30, v143
	v_lshl_add_u64 v[182:183], v[182:183], 0, s[58:59]
	s_mov_b32 m0, s31
	ds_read_b128 v[212:215], v187
	ds_read_b128 v[216:219], v187 offset:1024
	ds_read_b128 v[220:223], v187 offset:2048
	ds_read_b128 v[224:227], v187 offset:3072
	global_load_lds_dwordx4 v[182:183], off
	v_lshl_add_u64 v[182:183], v[188:189], 0, s[58:59]
	s_add_i32 m0, s31, 0x2000
	s_nop 0
	global_load_lds_dwordx4 v[182:183], off
	s_barrier
; #define PG8_STAGE(bufoff, gbase, voff) do { _Pragma("unroll") for (int _i = 0; _i < 2; ++_i) \
;         __builtin_amdgcn_global_load_lds((const unsigned*)((const char*)(gbase) + (voff)[_i]), (LAS unsigned*)(lds + (bufoff) + ldsw + _i * 8192), 16, 0, 0); } while (0)
; #define PG8_LDA(dst, b, h) do { _Pragma("unroll") for (int m = 0; m < 4; ++m) _Pragma("unroll") for (int k = 0; k < 2; ++k) dst[m][k] = *(const LAS bf16x8*)(lds + PG8_SA(b, h) + aoff + m * 2048 + k * 1024); } while (0)
; #define PG8_LDB(dst, b, h) do { _Pragma("unroll") for (int n = 0; n < 2; ++n) _Pragma("unroll") for (int k = 0; k < 2; ++k) dst[n][k] = *(const LAS bf16x8*)(lds + PG8_SB(b, h) + boff + n * 2048 + k * 1024); } while (0)
; #define PG8_WAIT_V(n) asm volatile("s_waitcnt vmcnt(" #n ")" ::: "memory")
; #define PG8_WAIT_L(n) asm volatile("s_waitcnt lgkmcnt(" #n ")" ::: "memory")
; #define PG8_BAR __builtin_amdgcn_s_barrier()
; #define PG8_SCHED __builtin_amdgcn_sched_barrier(0)
; template <class Epi>
; __device__ __forceinline__ void gemm_phase(LAS unsigned char* lds, const Gemm g, const StaticOrder& S, const Epi& E) {
;     ...
;             PG8_WAIT_L(8); PG8_BAR; PG8_WAIT_L(0); PG8_MMA(0, 0, At, B0); PG8_BAR; PG8_SCHED;
;             PG8_LDB(B1, 1, 1); PG8_STAGE(PG8_SB(1, 0), b3, voffB);
;             PG8_BAR; PG8_WAIT_L(0); PG8_MMA(0, 1, At, B1); PG8_BAR;
;             PG8_LDA(At, 1, 1); PG8_STAGE(PG8_SA(1, 0), a3, voffA);
;             PG8_BAR; PG8_WAIT_L(0); PG8_MMA(1, 0, At, B0); PG8_BAR; PG8_SCHED;
;             PG8_STAGE(PG8_SB(1, 1), b3 + hstep, voffB);
;             PG8_WAIT_V(6); PG8_BAR; PG8_MMA(1, 1, At, B1); PG8_BAR;
;     __device__ __forceinline__ void operator()(const Acc& acc, const Unit& u, int wr, int wc, int fr, int fq) const {
;         const int pn = u.pn; const int row0 = u.pm * 256 + wr * 64 + fr;
;         bf16_t* base; int ld, cb; bool act;
;         if (vt) { base = vt; ld = TH; cb = 256 * pn; act = false; }
;         else if (gmode) { base = g; ld = 4096; cb = 256 * pn; act = true; }
;         else if (pn < 8) { base = zna; ld = 2048; cb = 256 * pn; act = false; }
;         else if (pn < 16) { base = zqk; ld = 2048; cb = 256 * (pn - 8); act = false; }
;         else if (pn < 24) { base = vo; ld = 2048; cb = 256 * (pn - 16); act = pn >= 20; }
;         else { base = g; ld = 4096; cb = 256 * (pn - 24); act = true; }
	s_waitcnt lgkmcnt(0)
	s_setprio 1
	s_waitcnt lgkmcnt(0)
	v_mfma_f32_16x16x32_bf16 v[116:119], v[212:215], v[158:161], v[116:119]
	v_mfma_f32_16x16x32_bf16 v[116:119], v[216:219], v[162:165], v[116:119]
	v_mfma_f32_16x16x32_bf16 v[100:103], v[212:215], v[166:169], v[100:103]
	v_mfma_f32_16x16x32_bf16 v[100:103], v[216:219], v[170:173], v[100:103]
	v_mfma_f32_16x16x32_bf16 v[84:87], v[212:215], v[174:177], v[84:87]
	v_mfma_f32_16x16x32_bf16 v[84:87], v[216:219], v[178:181], v[84:87]
	v_mfma_f32_16x16x32_bf16 v[68:71], v[212:215], v[204:207], v[68:71]
	v_mfma_f32_16x16x32_bf16 v[68:71], v[216:219], v[208:211], v[68:71]
	v_mfma_f32_16x16x32_bf16 v[64:67], v[220:223], v[204:207], v[64:67]
	v_mfma_f32_16x16x32_bf16 v[64:67], v[224:227], v[208:211], v[64:67]
	v_mfma_f32_16x16x32_bf16 v[80:83], v[220:223], v[174:177], v[80:83]
	v_mfma_f32_16x16x32_bf16 v[80:83], v[224:227], v[178:181], v[80:83]
	v_mfma_f32_16x16x32_bf16 v[96:99], v[220:223], v[166:169], v[96:99]
	v_mfma_f32_16x16x32_bf16 v[96:99], v[224:227], v[170:173], v[96:99]
	v_mfma_f32_16x16x32_bf16 v[112:115], v[220:223], v[158:161], v[112:115]
	v_mfma_f32_16x16x32_bf16 v[112:115], v[224:227], v[162:165], v[112:115]
	s_setprio 0
	s_mov_b32 m0, s42
	v_lshl_add_u64 v[182:183], v[190:191], 0, s[58:59]
	s_barrier
	ds_read_b128 v[158:161], v145 offset:49152
	ds_read_b128 v[162:165], v145 offset:50176
	ds_read_b128 v[166:169], v145 offset:51200
	ds_read_b128 v[170:173], v145 offset:52224
	ds_read_b128 v[174:177], v145 offset:53248
	ds_read_b128 v[178:181], v145 offset:54272
	ds_read_b128 v[204:207], v145 offset:55296
	ds_read_b128 v[208:211], v145 offset:56320
	global_load_lds_dwordx4 v[182:183], off
	v_lshl_add_u64 v[182:183], v[192:193], 0, s[58:59]
	s_mov_b32 m0, s44
	s_nop 0
	global_load_lds_dwordx4 v[182:183], off
	s_barrier
	s_waitcnt lgkmcnt(0)
	s_setprio 1
	s_waitcnt lgkmcnt(0)
	v_mfma_f32_16x16x32_bf16 v[60:63], v[138:141], v[158:161], v[60:63]
	v_mfma_f32_16x16x32_bf16 v[60:63], v[146:149], v[162:165], v[60:63]
	v_mfma_f32_16x16x32_bf16 v[44:47], v[138:141], v[166:169], v[44:47]
	v_mfma_f32_16x16x32_bf16 v[44:47], v[146:149], v[170:173], v[44:47]
	v_mfma_f32_16x16x32_bf16 v[28:31], v[138:141], v[174:177], v[28:31]
	v_mfma_f32_16x16x32_bf16 v[28:31], v[146:149], v[178:181], v[28:31]
	v_mfma_f32_16x16x32_bf16 v[12:15], v[138:141], v[204:207], v[12:15]
	v_mfma_f32_16x16x32_bf16 v[12:15], v[146:149], v[208:211], v[12:15]
	v_mfma_f32_16x16x32_bf16 v[8:11], v[150:153], v[204:207], v[8:11]
	v_mfma_f32_16x16x32_bf16 v[8:11], v[154:157], v[208:211], v[8:11]
	v_mfma_f32_16x16x32_bf16 v[24:27], v[150:153], v[174:177], v[24:27]
	v_mfma_f32_16x16x32_bf16 v[24:27], v[154:157], v[178:181], v[24:27]
	v_mfma_f32_16x16x32_bf16 v[40:43], v[150:153], v[166:169], v[40:43]
	v_mfma_f32_16x16x32_bf16 v[40:43], v[154:157], v[170:173], v[40:43]
	v_mfma_f32_16x16x32_bf16 v[56:59], v[150:153], v[158:161], v[56:59]
	v_mfma_f32_16x16x32_bf16 v[56:59], v[154:157], v[162:165], v[56:59]
	s_setprio 0
	s_barrier
	s_add_u32 s28, s28, 0x80080
	s_addc_u32 s29, s29, 0
	s_add_i32 s30, s30, s38
	v_lshl_add_u64 v[138:139], s[28:29], 0, v[184:185]
	s_mov_b32 m0, s30
	s_nop 0
	global_load_lds_dwordx4 v[138:139], off
	v_lshl_add_u64 v[138:139], s[28:29], 0, v[132:133]
	s_add_i32 m0, s30, 0x2000
	s_nop 0
	global_load_lds_dwordx4 v[138:139], off
	s_waitcnt vmcnt(6)
	s_barrier
	s_setprio 1
	v_mfma_f32_16x16x32_bf16 v[52:55], v[212:215], v[158:161], v[52:55]
	v_mfma_f32_16x16x32_bf16 v[52:55], v[216:219], v[162:165], v[52:55]
	v_mfma_f32_16x16x32_bf16 v[36:39], v[212:215], v[166:169], v[36:39]
	v_mfma_f32_16x16x32_bf16 v[36:39], v[216:219], v[170:173], v[36:39]
	v_mfma_f32_16x16x32_bf16 v[20:23], v[212:215], v[174:177], v[20:23]
	v_mfma_f32_16x16x32_bf16 v[20:23], v[216:219], v[178:181], v[20:23]
	v_mfma_f32_16x16x32_bf16 v[4:7], v[212:215], v[204:207], v[4:7]
	v_mfma_f32_16x16x32_bf16 v[4:7], v[216:219], v[208:211], v[4:7]
	v_mfma_f32_16x16x32_bf16 v[0:3], v[220:223], v[204:207], v[0:3]
	v_mfma_f32_16x16x32_bf16 v[0:3], v[224:227], v[208:211], v[0:3]
	v_mfma_f32_16x16x32_bf16 v[16:19], v[220:223], v[174:177], v[16:19]
	v_mfma_f32_16x16x32_bf16 v[16:19], v[224:227], v[178:181], v[16:19]
	v_mfma_f32_16x16x32_bf16 v[32:35], v[220:223], v[166:169], v[32:35]
	v_mfma_f32_16x16x32_bf16 v[32:35], v[224:227], v[170:173], v[32:35]
	v_mfma_f32_16x16x32_bf16 v[48:51], v[220:223], v[158:161], v[48:51]
	v_mfma_f32_16x16x32_bf16 v[48:51], v[224:227], v[162:165], v[48:51]
	s_setprio 0
	s_add_i32 s43, s43, 2
	s_add_u32 s26, s26, 0x100
	s_addc_u32 s27, s27, 0
	s_add_u32 s34, s34, 0x100
	s_addc_u32 s35, s35, 0
	s_cmp_gt_u32 s43, 29
	s_barrier
	s_cbranch_scc0 .LBB0_366
	s_andn2_b64 vcc, exec, s[16:17]
	s_lshl_b32 s1, s8, 8
	s_cbranch_vccnz .LBB0_378
	s_cmp_lt_i32 s8, 8
	s_cbranch_scc1 .LBB0_410
	s_cmp_gt_u32 s8, 15
	s_mov_b64 s[34:35], -1
	s_cbranch_scc0 .LBB0_375
	s_mov_b64 s[30:31], -1
	s_cmp_gt_u32 s8, 23
	s_mov_b64 s[28:29], -1
	s_cbranch_scc0 .LBB0_372
	s_add_i32 s3, s1, 0xffffe800
	s_mov_b64 s[28:29], 0

; #define PG8_STAGE(bufoff, gbase, voff) do { _Pragma("unroll") for (int _i = 0; _i < 2; ++_i) \
;         __builtin_amdgcn_global_load_lds((const unsigned*)((const char*)(gbase) + (voff)[_i]), (LAS unsigned*)(lds + (bufoff) + ldsw + _i * 8192), 16, 0, 0); } while (0)
; #define PG8_LDA(dst, b, h) do { _Pragma("unroll") for (int m = 0; m < 4; ++m) _Pragma("unroll") for (int k = 0; k < 2; ++k) dst[m][k] = *(const LAS bf16x8*)(lds + PG8_SA(b, h) + aoff + m * 2048 + k * 1024); } while (0)
; #define PG8_LDB(dst, b, h) do { _Pragma("unroll") for (int n = 0; n < 2; ++n) _Pragma("unroll") for (int k = 0; k < 2; ++k) dst[n][k] = *(const LAS bf16x8*)(lds + PG8_SB(b, h) + boff + n * 2048 + k * 1024); } while (0)
; #define PG8_MMA(ai, bj, At, Bt) do { __builtin_amdgcn_s_setprio(1); _Pragma("unroll") for (int m = 0; m < 4; ++m) _Pragma("unroll") for (int n = 0; n < 2; ++n) _Pragma("unroll") for (int k = 0; k < 2; ++k) \
;         acc[ai][bj][m][n] = __builtin_amdgcn_mfma_f32_16x16x32_bf16(Bt[n][k], At[m][k], acc[ai][bj][m][n], 0, 0, 0); __builtin_amdgcn_s_setprio(0); } while (0)
; #define PG8_WAIT_L(n) asm volatile("s_waitcnt lgkmcnt(" #n ")" ::: "memory")
; #define PG8_BAR __builtin_amdgcn_s_barrier()
; #define PG8_SCHED __builtin_amdgcn_sched_barrier(0)
; template <class Epi>
; __device__ __forceinline__ void gemm_phase(LAS unsigned char* lds, const Gemm g, const StaticOrder& S, const Epi& E) {
;     ...
;             PG8_LDB(B0, 0, 0); PG8_SCHED; PG8_LDA(At, 0, 0); PG8_STAGE(PG8_SA(1, 1), a1 + hstep, voffA);
;             PG8_WAIT_L(8); PG8_BAR; PG8_WAIT_L(0); PG8_MMA(0, 0, At, B0); PG8_BAR; PG8_SCHED;
;             PG8_LDB(B1, 0, 1); PG8_STAGE(PG8_SB(0, 0), b2, voffB);
;             PG8_BAR; PG8_WAIT_L(0); PG8_MMA(0, 1, At, B1); PG8_BAR;
;             PG8_LDA(At, 0, 1); PG8_STAGE(PG8_SA(0, 0), a2, voffA);
;             PG8_BAR; PG8_WAIT_L(0); PG8_MMA(1, 0, At, B0); PG8_BAR; PG8_SCHED;
.LBB0_490:
	s_add_u32 s30, s8, 0xfff80080
	s_addc_u32 s31, s9, -1
	s_add_i32 s52, 0, 0x10000
	v_add_u32_e32 v154, s52, v143
	ds_read_b128 v[138:141], v154
	ds_read_b128 v[146:149], v154 offset:1024
	ds_read_b128 v[150:153], v154 offset:2048
	ds_read_b128 v[154:157], v154 offset:3072
	s_cmp_eq_u32 s51, 28
	s_cselect_b32 s35, s3, s31
	s_cselect_b32 s34, s21, s30
	s_cselect_b32 s31, s19, s50
	s_cselect_b32 s30, s43, s47
	v_lshl_add_u64 v[182:183], s[8:9], 0, v[134:135]
	s_add_i32 m0, s27, 0xc000
	ds_read_b128 v[158:161], v145
	ds_read_b128 v[162:165], v145 offset:1024
	ds_read_b128 v[166:169], v145 offset:2048
	ds_read_b128 v[170:173], v145 offset:3072
	ds_read_b128 v[174:177], v145 offset:4096
	ds_read_b128 v[178:181], v145 offset:5120
	ds_read_b128 v[204:207], v145 offset:6144
	ds_read_b128 v[208:211], v145 offset:7168
	global_load_lds_dwordx4 v[182:183], off
	v_lshl_add_u64 v[182:183], s[8:9], 0, v[136:137]
	s_add_i32 m0, s27, 0xe000
	s_nop 0
	global_load_lds_dwordx4 v[182:183], off
	s_waitcnt lgkmcnt(8)
	s_barrier
	s_waitcnt lgkmcnt(0)
	s_setprio 1
	s_waitcnt lgkmcnt(0)
	v_mfma_f32_16x16x32_bf16 v[124:127], v[138:141], v[158:161], v[124:127]
	v_mfma_f32_16x16x32_bf16 v[124:127], v[146:149], v[162:165], v[124:127]
	v_mfma_f32_16x16x32_bf16 v[108:111], v[138:141], v[166:169], v[108:111]
	v_mfma_f32_16x16x32_bf16 v[108:111], v[146:149], v[170:173], v[108:111]
	v_mfma_f32_16x16x32_bf16 v[92:95], v[138:141], v[174:177], v[92:95]
	v_mfma_f32_16x16x32_bf16 v[92:95], v[146:149], v[178:181], v[92:95]
	v_mfma_f32_16x16x32_bf16 v[76:79], v[138:141], v[204:207], v[76:79]
	v_mfma_f32_16x16x32_bf16 v[76:79], v[146:149], v[208:211], v[76:79]
	v_mfma_f32_16x16x32_bf16 v[72:75], v[150:153], v[204:207], v[72:75]
	v_mfma_f32_16x16x32_bf16 v[72:75], v[154:157], v[208:211], v[72:75]
	v_mfma_f32_16x16x32_bf16 v[88:91], v[150:153], v[174:177], v[88:91]
	v_mfma_f32_16x16x32_bf16 v[88:91], v[154:157], v[178:181], v[88:91]
	v_mfma_f32_16x16x32_bf16 v[104:107], v[150:153], v[166:169], v[104:107]
	v_mfma_f32_16x16x32_bf16 v[104:107], v[154:157], v[170:173], v[104:107]
	v_mfma_f32_16x16x32_bf16 v[120:123], v[150:153], v[158:161], v[120:123]
	v_mfma_f32_16x16x32_bf16 v[120:123], v[154:157], v[162:165], v[120:123]
	s_setprio 0
	s_barrier
	s_add_i32 s56, 0, 0x14000
	v_add_u32_e32 v182, s56, v143
	s_add_i32 s52, s52, s38
	ds_read_b128 v[212:215], v182
	ds_read_b128 v[216:219], v182 offset:1024
	ds_read_b128 v[220:223], v182 offset:2048
	ds_read_b128 v[224:227], v182 offset:3072
	v_lshl_add_u64 v[182:183], s[30:31], 0, v[184:185]
	s_mov_b32 m0, s52
	v_lshl_add_u64 v[188:189], s[30:31], 0, v[132:133]
	global_load_lds_dwordx4 v[182:183], off
	s_add_i32 m0, s52, 0x2000
	s_nop 0
	global_load_lds_dwordx4 v[188:189], off
	s_barrier
	s_waitcnt lgkmcnt(0)
	s_setprio 1
	s_waitcnt lgkmcnt(0)
	v_mfma_f32_16x16x32_bf16 v[116:119], v[212:215], v[158:161], v[116:119]
	v_mfma_f32_16x16x32_bf16 v[116:119], v[216:219], v[162:165], v[116:119]
	v_mfma_f32_16x16x32_bf16 v[100:103], v[212:215], v[166:169], v[100:103]
	v_mfma_f32_16x16x32_bf16 v[100:103], v[216:219], v[170:173], v[100:103]
	v_mfma_f32_16x16x32_bf16 v[84:87], v[212:215], v[174:177], v[84:87]
	v_mfma_f32_16x16x32_bf16 v[84:87], v[216:219], v[178:181], v[84:87]
	v_mfma_f32_16x16x32_bf16 v[68:71], v[212:215], v[204:207], v[68:71]
	v_mfma_f32_16x16x32_bf16 v[68:71], v[216:219], v[208:211], v[68:71]
	v_mfma_f32_16x16x32_bf16 v[64:67], v[220:223], v[204:207], v[64:67]
	v_mfma_f32_16x16x32_bf16 v[64:67], v[224:227], v[208:211], v[64:67]
	v_mfma_f32_16x16x32_bf16 v[80:83], v[220:223], v[174:177], v[80:83]
	v_mfma_f32_16x16x32_bf16 v[80:83], v[224:227], v[178:181], v[80:83]
	v_mfma_f32_16x16x32_bf16 v[96:99], v[220:223], v[166:169], v[96:99]
	v_mfma_f32_16x16x32_bf16 v[96:99], v[224:227], v[170:173], v[96:99]
	v_mfma_f32_16x16x32_bf16 v[112:115], v[220:223], v[158:161], v[112:115]
	v_mfma_f32_16x16x32_bf16 v[112:115], v[224:227], v[162:165], v[112:115]
	s_setprio 0
	s_mov_b32 m0, s27
	v_lshl_add_u64 v[190:191], s[34:35], 0, v[128:129]
	s_barrier
	ds_read_b128 v[158:161], v145 offset:16384
	ds_read_b128 v[162:165], v145 offset:17408
	ds_read_b128 v[166:169], v145 offset:18432
	ds_read_b128 v[170:173], v145 offset:19456
	ds_read_b128 v[174:177], v145 offset:20480
	ds_read_b128 v[178:181], v145 offset:21504
	ds_read_b128 v[204:207], v145 offset:22528
	ds_read_b128 v[208:211], v145 offset:23552
	global_load_lds_dwordx4 v[190:191], off
	v_lshl_add_u64 v[192:193], s[34:35], 0, v[130:131]
	s_mov_b32 m0, s29
	s_nop 0
	global_load_lds_dwordx4 v[192:193], off
	s_barrier
	s_waitcnt lgkmcnt(0)
	s_setprio 1
	s_waitcnt lgkmcnt(0)
	v_mfma_f32_16x16x32_bf16 v[60:63], v[138:141], v[158:161], v[60:63]
	v_mfma_f32_16x16x32_bf16 v[60:63], v[146:149], v[162:165], v[60:63]
	v_mfma_f32_16x16x32_bf16 v[44:47], v[138:141], v[166:169], v[44:47]
	v_mfma_f32_16x16x32_bf16 v[44:47], v[146:149], v[170:173], v[44:47]
	v_mfma_f32_16x16x32_bf16 v[28:31], v[138:141], v[174:177], v[28:31]
	v_mfma_f32_16x16x32_bf16 v[28:31], v[146:149], v[178:181], v[28:31]
	v_mfma_f32_16x16x32_bf16 v[12:15], v[138:141], v[204:207], v[12:15]
	v_mfma_f32_16x16x32_bf16 v[12:15], v[146:149], v[208:211], v[12:15]
	v_mfma_f32_16x16x32_bf16 v[8:11], v[150:153], v[204:207], v[8:11]
	v_mfma_f32_16x16x32_bf16 v[8:11], v[154:157], v[208:211], v[8:11]
	v_mfma_f32_16x16x32_bf16 v[24:27], v[150:153], v[174:177], v[24:27]
	v_mfma_f32_16x16x32_bf16 v[24:27], v[154:157], v[178:181], v[24:27]
	v_mfma_f32_16x16x32_bf16 v[40:43], v[150:153], v[166:169], v[40:43]
	v_mfma_f32_16x16x32_bf16 v[40:43], v[154:157], v[170:173], v[40:43]
	v_mfma_f32_16x16x32_bf16 v[56:59], v[150:153], v[158:161], v[56:59]
	v_mfma_f32_16x16x32_bf16 v[56:59], v[154:157], v[162:165], v[56:59]
	s_setprio 0
	s_barrier
; #define PG8_STAGE(bufoff, gbase, voff) do { _Pragma("unroll") for (int _i = 0; _i < 2; ++_i) \
;         __builtin_amdgcn_global_load_lds((const unsigned*)((const char*)(gbase) + (voff)[_i]), (LAS unsigned*)(lds + (bufoff) + ldsw + _i * 8192), 16, 0, 0); } while (0)
; #define PG8_LDA(dst, b, h) do { _Pragma("unroll") for (int m = 0; m < 4; ++m) _Pragma("unroll") for (int k = 0; k < 2; ++k) dst[m][k] = *(const LAS bf16x8*)(lds + PG8_SA(b, h) + aoff + m * 2048 + k * 1024); } while (0)
; #define PG8_LDB(dst, b, h) do { _Pragma("unroll") for (int n = 0; n < 2; ++n) _Pragma("unroll") for (int k = 0; k < 2; ++k) dst[n][k] = *(const LAS bf16x8*)(lds + PG8_SB(b, h) + boff + n * 2048 + k * 1024); } while (0)
; #define PG8_MMA(ai, bj, At, Bt) do { __builtin_amdgcn_s_setprio(1); _Pragma("unroll") for (int m = 0; m < 4; ++m) _Pragma("unroll") for (int n = 0; n < 2; ++n) _Pragma("unroll") for (int k = 0; k < 2; ++k) \
;         acc[ai][bj][m][n] = __builtin_amdgcn_mfma_f32_16x16x32_bf16(Bt[n][k], At[m][k], acc[ai][bj][m][n], 0, 0, 0); __builtin_amdgcn_s_setprio(0); } while (0)
; #define PG8_WAIT_V(n) asm volatile("s_waitcnt vmcnt(" #n ")" ::: "memory")
; #define PG8_WAIT_L(n) asm volatile("s_waitcnt lgkmcnt(" #n ")" ::: "memory")
; #define PG8_BAR __builtin_amdgcn_s_barrier()
; #define PG8_SCHED __builtin_amdgcn_sched_barrier(0)
; template <class Epi>
; __device__ __forceinline__ void gemm_phase(LAS unsigned char* lds, const Gemm g, const StaticOrder& S, const Epi& E) {
;     ...
;             PG8_STAGE(PG8_SB(0, 1), b2 + hstep, voffB);
;             PG8_WAIT_V(6); PG8_BAR; PG8_MMA(1, 1, At, B1); PG8_BAR;
;             PG8_LDB(B0, 1, 0); PG8_SCHED; PG8_LDA(At, 1, 0); PG8_STAGE(PG8_SA(0, 1), a2 + hstep, voffA);
;             PG8_WAIT_L(8); PG8_BAR; PG8_WAIT_L(0); PG8_MMA(0, 0, At, B0); PG8_BAR; PG8_SCHED;
;             PG8_LDB(B1, 1, 1); PG8_STAGE(PG8_SB(1, 0), b3, voffB);
;             PG8_BAR; PG8_WAIT_L(0); PG8_MMA(0, 1, At, B1); PG8_BAR;
;             PG8_LDA(At, 1, 1); PG8_STAGE(PG8_SA(1, 0), a3, voffA);
;             PG8_BAR; PG8_WAIT_L(0); PG8_MMA(1, 0, At, B0); PG8_BAR; PG8_SCHED;
	s_add_u32 s54, s30, 0x80000
	s_addc_u32 s55, s31, 0
	s_add_i32 s52, s56, s38
	v_lshl_add_u64 v[138:139], s[54:55], 0, v[184:185]
	s_mov_b32 m0, s52
	s_nop 0
	global_load_lds_dwordx4 v[138:139], off
	v_lshl_add_u64 v[138:139], s[54:55], 0, v[132:133]
	s_add_i32 m0, s52, 0x2000
	s_nop 0
	global_load_lds_dwordx4 v[138:139], off
	s_waitcnt vmcnt(6)
	s_barrier
	s_setprio 1
	v_mfma_f32_16x16x32_bf16 v[52:55], v[212:215], v[158:161], v[52:55]
	v_mfma_f32_16x16x32_bf16 v[52:55], v[216:219], v[162:165], v[52:55]
	v_mfma_f32_16x16x32_bf16 v[36:39], v[212:215], v[166:169], v[36:39]
	v_mfma_f32_16x16x32_bf16 v[36:39], v[216:219], v[170:173], v[36:39]
	v_mfma_f32_16x16x32_bf16 v[20:23], v[212:215], v[174:177], v[20:23]
	v_mfma_f32_16x16x32_bf16 v[20:23], v[216:219], v[178:181], v[20:23]
	v_mfma_f32_16x16x32_bf16 v[4:7], v[212:215], v[204:207], v[4:7]
	v_mfma_f32_16x16x32_bf16 v[4:7], v[216:219], v[208:211], v[4:7]
	v_mfma_f32_16x16x32_bf16 v[0:3], v[220:223], v[204:207], v[0:3]
	v_mfma_f32_16x16x32_bf16 v[0:3], v[224:227], v[208:211], v[0:3]
	v_mfma_f32_16x16x32_bf16 v[16:19], v[220:223], v[174:177], v[16:19]
	v_mfma_f32_16x16x32_bf16 v[16:19], v[224:227], v[178:181], v[16:19]
	v_mfma_f32_16x16x32_bf16 v[32:35], v[220:223], v[166:169], v[32:35]
	v_mfma_f32_16x16x32_bf16 v[32:35], v[224:227], v[170:173], v[32:35]
	v_mfma_f32_16x16x32_bf16 v[48:51], v[220:223], v[158:161], v[48:51]
	v_mfma_f32_16x16x32_bf16 v[48:51], v[224:227], v[162:165], v[48:51]
	s_setprio 0
	s_add_i32 s52, 0, 0x18000
	v_add_u32_e32 v154, s52, v143
	s_barrier
	ds_read_b128 v[138:141], v154
	ds_read_b128 v[146:149], v154 offset:1024
	ds_read_b128 v[150:153], v154 offset:2048
	ds_read_b128 v[154:157], v154 offset:3072
	s_add_u32 s34, s34, 0x80000
	s_addc_u32 s35, s35, 0
	s_mov_b32 m0, s39
	v_lshl_add_u64 v[212:213], s[34:35], 0, v[128:129]
	ds_read_b128 v[158:161], v145 offset:32768
	ds_read_b128 v[162:165], v145 offset:33792
	ds_read_b128 v[166:169], v145 offset:34816
	ds_read_b128 v[170:173], v145 offset:35840
	ds_read_b128 v[174:177], v145 offset:36864
	ds_read_b128 v[178:181], v145 offset:37888
	ds_read_b128 v[204:207], v145 offset:38912
	ds_read_b128 v[208:211], v145 offset:39936
	global_load_lds_dwordx4 v[212:213], off
	v_lshl_add_u64 v[212:213], s[34:35], 0, v[130:131]
	s_mov_b32 m0, s40
	s_nop 0
	global_load_lds_dwordx4 v[212:213], off
	s_waitcnt lgkmcnt(8)
	s_barrier
	s_waitcnt lgkmcnt(0)
	s_setprio 1
	s_waitcnt lgkmcnt(0)
	v_mfma_f32_16x16x32_bf16 v[124:127], v[138:141], v[158:161], v[124:127]
	v_mfma_f32_16x16x32_bf16 v[124:127], v[146:149], v[162:165], v[124:127]
	v_mfma_f32_16x16x32_bf16 v[108:111], v[138:141], v[166:169], v[108:111]
	v_mfma_f32_16x16x32_bf16 v[108:111], v[146:149], v[170:173], v[108:111]
	v_mfma_f32_16x16x32_bf16 v[92:95], v[138:141], v[174:177], v[92:95]
	v_mfma_f32_16x16x32_bf16 v[92:95], v[146:149], v[178:181], v[92:95]
	v_mfma_f32_16x16x32_bf16 v[76:79], v[138:141], v[204:207], v[76:79]
	v_mfma_f32_16x16x32_bf16 v[76:79], v[146:149], v[208:211], v[76:79]
	v_mfma_f32_16x16x32_bf16 v[72:75], v[150:153], v[204:207], v[72:75]
	v_mfma_f32_16x16x32_bf16 v[72:75], v[154:157], v[208:211], v[72:75]
	v_mfma_f32_16x16x32_bf16 v[88:91], v[150:153], v[174:177], v[88:91]
	v_mfma_f32_16x16x32_bf16 v[88:91], v[154:157], v[178:181], v[88:91]
	v_mfma_f32_16x16x32_bf16 v[104:107], v[150:153], v[166:169], v[104:107]
	v_mfma_f32_16x16x32_bf16 v[104:107], v[154:157], v[170:173], v[104:107]
	v_mfma_f32_16x16x32_bf16 v[120:123], v[150:153], v[158:161], v[120:123]
	v_mfma_f32_16x16x32_bf16 v[120:123], v[154:157], v[162:165], v[120:123]
	s_setprio 0
	s_barrier
	s_add_i32 s34, 0, 0x1c000
	s_add_i32 s35, s52, s38
	v_add_u32_e32 v187, s34, v143
	v_lshl_add_u64 v[182:183], v[182:183], 0, s[58:59]
	s_mov_b32 m0, s35
	ds_read_b128 v[212:215], v187
	ds_read_b128 v[216:219], v187 offset:1024
	ds_read_b128 v[220:223], v187 offset:2048
	ds_read_b128 v[224:227], v187 offset:3072
	global_load_lds_dwordx4 v[182:183], off
	v_lshl_add_u64 v[182:183], v[188:189], 0, s[58:59]
	s_add_i32 m0, s35, 0x2000
	s_nop 0
	global_load_lds_dwordx4 v[182:183], off
	s_barrier
	s_waitcnt lgkmcnt(0)
	s_setprio 1
	s_waitcnt lgkmcnt(0)
	v_mfma_f32_16x16x32_bf16 v[116:119], v[212:215], v[158:161], v[116:119]
	v_mfma_f32_16x16x32_bf16 v[116:119], v[216:219], v[162:165], v[116:119]
	v_mfma_f32_16x16x32_bf16 v[100:103], v[212:215], v[166:169], v[100:103]
	v_mfma_f32_16x16x32_bf16 v[100:103], v[216:219], v[170:173], v[100:103]
	v_mfma_f32_16x16x32_bf16 v[84:87], v[212:215], v[174:177], v[84:87]
	v_mfma_f32_16x16x32_bf16 v[84:87], v[216:219], v[178:181], v[84:87]
	v_mfma_f32_16x16x32_bf16 v[68:71], v[212:215], v[204:207], v[68:71]
	v_mfma_f32_16x16x32_bf16 v[68:71], v[216:219], v[208:211], v[68:71]
	v_mfma_f32_16x16x32_bf16 v[64:67], v[220:223], v[204:207], v[64:67]
	v_mfma_f32_16x16x32_bf16 v[64:67], v[224:227], v[208:211], v[64:67]
	v_mfma_f32_16x16x32_bf16 v[80:83], v[220:223], v[174:177], v[80:83]
	v_mfma_f32_16x16x32_bf16 v[80:83], v[224:227], v[178:181], v[80:83]
	v_mfma_f32_16x16x32_bf16 v[96:99], v[220:223], v[166:169], v[96:99]
	v_mfma_f32_16x16x32_bf16 v[96:99], v[224:227], v[170:173], v[96:99]
	v_mfma_f32_16x16x32_bf16 v[112:115], v[220:223], v[158:161], v[112:115]
	v_mfma_f32_16x16x32_bf16 v[112:115], v[224:227], v[162:165], v[112:115]
	s_setprio 0
	s_mov_b32 m0, s41
	v_lshl_add_u64 v[182:183], v[190:191], 0, s[58:59]
	s_barrier
; __device__ __forceinline__ float sigmoidf_(float x) { return __builtin_amdgcn_rcpf(1.0f + __builtin_amdgcn_exp2f(-1.4426950408889634f * x)); }
; #define PG8_STAGE(bufoff, gbase, voff) do { _Pragma("unroll") for (int _i = 0; _i < 2; ++_i) \
;         __builtin_amdgcn_global_load_lds((const unsigned*)((const char*)(gbase) + (voff)[_i]), (LAS unsigned*)(lds + (bufoff) + ldsw + _i * 8192), 16, 0, 0); } while (0)
; #define PG8_LDA(dst, b, h) do { _Pragma("unroll") for (int m = 0; m < 4; ++m) _Pragma("unroll") for (int k = 0; k < 2; ++k) dst[m][k] = *(const LAS bf16x8*)(lds + PG8_SA(b, h) + aoff + m * 2048 + k * 1024); } while (0)
; #define PG8_MMA(ai, bj, At, Bt) do { __builtin_amdgcn_s_setprio(1); _Pragma("unroll") for (int m = 0; m < 4; ++m) _Pragma("unroll") for (int n = 0; n < 2; ++n) _Pragma("unroll") for (int k = 0; k < 2; ++k) \
;         acc[ai][bj][m][n] = __builtin_amdgcn_mfma_f32_16x16x32_bf16(Bt[n][k], At[m][k], acc[ai][bj][m][n], 0, 0, 0); __builtin_amdgcn_s_setprio(0); } while (0)
; #define PG8_WAIT_V(n) asm volatile("s_waitcnt vmcnt(" #n ")" ::: "memory")
; #define PG8_WAIT_L(n) asm volatile("s_waitcnt lgkmcnt(" #n ")" ::: "memory")
; #define PG8_BAR __builtin_amdgcn_s_barrier()
; #define PG8_SCHED __builtin_amdgcn_sched_barrier(0)
; template <class Epi>
; __device__ __forceinline__ void gemm_phase(LAS unsigned char* lds, const Gemm g, const StaticOrder& S, const Epi& E) {
;     ...
;             PG8_LDA(At, 1, 1); PG8_STAGE(PG8_SA(1, 0), a3, voffA);
;             PG8_BAR; PG8_WAIT_L(0); PG8_MMA(1, 0, At, B0); PG8_BAR; PG8_SCHED;
;             PG8_STAGE(PG8_SB(1, 1), b3 + hstep, voffB);
;             PG8_WAIT_V(6); PG8_BAR; PG8_MMA(1, 1, At, B1); PG8_BAR;
;     __device__ __forceinline__ void operator()(const Acc& acc, const Unit& u, int wr, int wc, int fr, int fq) const {
;     ...
;                 for (int bj = 0; bj < 2; ++bj) { f32x4 v0 = acc[ai][bj][m][0], v1 = acc[ai][bj][m][1];
;                     if (act) {
; #pragma unroll
;                         for (int j = 0; j < 4; ++j) { v0[j] = sigmoidf_(v0[j]); v1[j] = sigmoidf_(v1[j]); } }
	ds_read_b128 v[158:161], v145 offset:49152
	ds_read_b128 v[162:165], v145 offset:50176
	ds_read_b128 v[166:169], v145 offset:51200
	ds_read_b128 v[170:173], v145 offset:52224
	ds_read_b128 v[174:177], v145 offset:53248
	ds_read_b128 v[178:181], v145 offset:54272
	ds_read_b128 v[204:207], v145 offset:55296
	ds_read_b128 v[208:211], v145 offset:56320
	global_load_lds_dwordx4 v[182:183], off
	v_lshl_add_u64 v[182:183], v[192:193], 0, s[58:59]
	s_mov_b32 m0, s42
	s_nop 0
	global_load_lds_dwordx4 v[182:183], off
	s_barrier
	s_waitcnt lgkmcnt(0)
	s_setprio 1
	s_waitcnt lgkmcnt(0)
	v_mfma_f32_16x16x32_bf16 v[60:63], v[138:141], v[158:161], v[60:63]
	v_mfma_f32_16x16x32_bf16 v[60:63], v[146:149], v[162:165], v[60:63]
	v_mfma_f32_16x16x32_bf16 v[44:47], v[138:141], v[166:169], v[44:47]
	v_mfma_f32_16x16x32_bf16 v[44:47], v[146:149], v[170:173], v[44:47]
	v_mfma_f32_16x16x32_bf16 v[28:31], v[138:141], v[174:177], v[28:31]
	v_mfma_f32_16x16x32_bf16 v[28:31], v[146:149], v[178:181], v[28:31]
	v_mfma_f32_16x16x32_bf16 v[12:15], v[138:141], v[204:207], v[12:15]
	v_mfma_f32_16x16x32_bf16 v[12:15], v[146:149], v[208:211], v[12:15]
	v_mfma_f32_16x16x32_bf16 v[8:11], v[150:153], v[204:207], v[8:11]
	v_mfma_f32_16x16x32_bf16 v[8:11], v[154:157], v[208:211], v[8:11]
	v_mfma_f32_16x16x32_bf16 v[24:27], v[150:153], v[174:177], v[24:27]
	v_mfma_f32_16x16x32_bf16 v[24:27], v[154:157], v[178:181], v[24:27]
	v_mfma_f32_16x16x32_bf16 v[40:43], v[150:153], v[166:169], v[40:43]
	v_mfma_f32_16x16x32_bf16 v[40:43], v[154:157], v[170:173], v[40:43]
	v_mfma_f32_16x16x32_bf16 v[56:59], v[150:153], v[158:161], v[56:59]
	v_mfma_f32_16x16x32_bf16 v[56:59], v[154:157], v[162:165], v[56:59]
	s_setprio 0
	s_barrier
	s_add_u32 s30, s30, 0x80080
	s_addc_u32 s31, s31, 0
	s_add_i32 s34, s34, s38
	v_lshl_add_u64 v[138:139], s[30:31], 0, v[184:185]
	s_mov_b32 m0, s34
	s_nop 0
	global_load_lds_dwordx4 v[138:139], off
	v_lshl_add_u64 v[138:139], s[30:31], 0, v[132:133]
	s_add_i32 m0, s34, 0x2000
	s_nop 0
	global_load_lds_dwordx4 v[138:139], off
	s_waitcnt vmcnt(6)
	s_barrier
	s_setprio 1
	v_mfma_f32_16x16x32_bf16 v[52:55], v[212:215], v[158:161], v[52:55]
	v_mfma_f32_16x16x32_bf16 v[52:55], v[216:219], v[162:165], v[52:55]
	v_mfma_f32_16x16x32_bf16 v[36:39], v[212:215], v[166:169], v[36:39]
	v_mfma_f32_16x16x32_bf16 v[36:39], v[216:219], v[170:173], v[36:39]
	v_mfma_f32_16x16x32_bf16 v[20:23], v[212:215], v[174:177], v[20:23]
	v_mfma_f32_16x16x32_bf16 v[20:23], v[216:219], v[178:181], v[20:23]
	v_mfma_f32_16x16x32_bf16 v[4:7], v[212:215], v[204:207], v[4:7]
	v_mfma_f32_16x16x32_bf16 v[4:7], v[216:219], v[208:211], v[4:7]
	v_mfma_f32_16x16x32_bf16 v[0:3], v[220:223], v[204:207], v[0:3]
	v_mfma_f32_16x16x32_bf16 v[0:3], v[224:227], v[208:211], v[0:3]
	v_mfma_f32_16x16x32_bf16 v[16:19], v[220:223], v[174:177], v[16:19]
	v_mfma_f32_16x16x32_bf16 v[16:19], v[224:227], v[178:181], v[16:19]
	v_mfma_f32_16x16x32_bf16 v[32:35], v[220:223], v[166:169], v[32:35]
	v_mfma_f32_16x16x32_bf16 v[32:35], v[224:227], v[170:173], v[32:35]
	v_mfma_f32_16x16x32_bf16 v[48:51], v[220:223], v[158:161], v[48:51]
	v_mfma_f32_16x16x32_bf16 v[48:51], v[224:227], v[162:165], v[48:51]
	s_setprio 0
	s_add_i32 s51, s51, 2
	s_add_u32 s8, s8, 0x100
	s_addc_u32 s9, s9, 0
	s_add_u32 s47, s47, 0x100
	s_addc_u32 s50, s50, 0
	s_cmp_gt_u32 s51, 29
	s_barrier
	s_cbranch_scc0 .LBB0_490
	v_cndmask_b32_e64 v138, 0, 1, s[16:17]
	v_cmp_ne_u32_e64 s[8:9], 1, v138
	s_andn2_b64 vcc, exec, s[16:17]
	s_cbranch_vccnz .LBB0_493
	v_mul_f32_e32 v124, 0xbfb8aa3b, v124
	v_mul_f32_e32 v120, 0xbfb8aa3b, v120
	v_mul_f32_e32 v125, 0xbfb8aa3b, v125
	v_mul_f32_e32 v121, 0xbfb8aa3b, v121
	v_mul_f32_e32 v126, 0xbfb8aa3b, v126
	v_mul_f32_e32 v122, 0xbfb8aa3b, v122
	v_mul_f32_e32 v127, 0xbfb8aa3b, v127
	v_mul_f32_e32 v123, 0xbfb8aa3b, v123
	v_exp_f32_e32 v124, v124
	v_exp_f32_e32 v120, v120
	v_exp_f32_e32 v125, v125
	v_exp_f32_e32 v121, v121
	v_exp_f32_e32 v126, v126
	v_exp_f32_e32 v122, v122
	v_exp_f32_e32 v127, v127
	v_exp_f32_e32 v123, v123
	v_add_f32_e32 v124, 1.0, v124
	v_add_f32_e32 v120, 1.0, v120
	v_add_f32_e32 v125, 1.0, v125
	v_add_f32_e32 v121, 1.0, v121
	v_add_f32_e32 v126, 1.0, v126
	v_add_f32_e32 v122, 1.0, v122
	v_add_f32_e32 v127, 1.0, v127
	v_add_f32_e32 v123, 1.0, v123
	v_rcp_f32_e32 v124, v124
	v_rcp_f32_e32 v120, v120
	v_rcp_f32_e32 v125, v125
	v_rcp_f32_e32 v121, v121
	v_rcp_f32_e32 v126, v126
	v_rcp_f32_e32 v122, v122
	v_rcp_f32_e32 v127, v127
	v_rcp_f32_e32 v123, v123

; #define PG8_STAGE(bufoff, gbase, voff) do { _Pragma("unroll") for (int _i = 0; _i < 2; ++_i) \
;         __builtin_amdgcn_global_load_lds((const unsigned*)((const char*)(gbase) + (voff)[_i]), (LAS unsigned*)(lds + (bufoff) + ldsw + _i * 8192), 16, 0, 0); } while (0)
; #define PG8_LDA(dst, b, h) do { _Pragma("unroll") for (int m = 0; m < 4; ++m) _Pragma("unroll") for (int k = 0; k < 2; ++k) dst[m][k] = *(const LAS bf16x8*)(lds + PG8_SA(b, h) + aoff + m * 2048 + k * 1024); } while (0)
; #define PG8_LDB(dst, b, h) do { _Pragma("unroll") for (int n = 0; n < 2; ++n) _Pragma("unroll") for (int k = 0; k < 2; ++k) dst[n][k] = *(const LAS bf16x8*)(lds + PG8_SB(b, h) + boff + n * 2048 + k * 1024); } while (0)
; #define PG8_MMA(ai, bj, At, Bt) do { __builtin_amdgcn_s_setprio(1); _Pragma("unroll") for (int m = 0; m < 4; ++m) _Pragma("unroll") for (int n = 0; n < 2; ++n) _Pragma("unroll") for (int k = 0; k < 2; ++k) \
;         acc[ai][bj][m][n] = __builtin_amdgcn_mfma_f32_16x16x32_bf16(Bt[n][k], At[m][k], acc[ai][bj][m][n], 0, 0, 0); __builtin_amdgcn_s_setprio(0); } while (0)
; #define PG8_WAIT_L(n) asm volatile("s_waitcnt lgkmcnt(" #n ")" ::: "memory")
; #define PG8_BAR __builtin_amdgcn_s_barrier()
; #define PG8_SCHED __builtin_amdgcn_sched_barrier(0)
; template <class Epi>
; __device__ __forceinline__ void gemm_phase(LAS unsigned char* lds, const Gemm g, const StaticOrder& S, const Epi& E) {
;     ...
;         for (int t = 0; t < nt; t += 2) {
;             const bool last = (t == nt - 2);
;             const char* a1 = cA + (size_t)(t + 1) * kstep;
;             const char* a2 = last ? nA : cA + (size_t)(t + 2) * kstep; const char* b2 = last ? nB : cB + (size_t)(t + 2) * kstep;
;             const char* a3 = a2 + kstep; const char* b3 = b2 + kstep;
;             PG8_LDB(B0, 0, 0); PG8_SCHED; PG8_LDA(At, 0, 0); PG8_STAGE(PG8_SA(1, 1), a1 + hstep, voffA);
;             PG8_WAIT_L(8); PG8_BAR; PG8_WAIT_L(0); PG8_MMA(0, 0, At, B0); PG8_BAR; PG8_SCHED;
;             PG8_LDB(B1, 0, 1); PG8_STAGE(PG8_SB(0, 0), b2, voffB);
;             PG8_BAR; PG8_WAIT_L(0); PG8_MMA(0, 1, At, B1); PG8_BAR;
;             PG8_LDA(At, 0, 1); PG8_STAGE(PG8_SA(0, 0), a2, voffA);
;             PG8_BAR; PG8_WAIT_L(0); PG8_MMA(1, 0, At, B0); PG8_BAR; PG8_SCHED;
.LBB0_591:
	s_add_i32 s68, s8, 2
	s_add_u32 s36, s0, 0x80
	s_addc_u32 s9, s1, 0
	s_add_i32 s66, 0, 0x10000
	v_add_u32_e32 v60, s66, v233
	ds_read_b128 v[48:51], v60
	ds_read_b128 v[52:55], v60 offset:1024
	ds_read_b128 v[56:59], v60 offset:2048
	ds_read_b128 v[60:63], v60 offset:3072
	s_cmp_eq_u32 s55, s8
	s_cselect_b32 s8, s34, s36
	s_cselect_b32 s9, s35, s9
	s_cselect_b32 s37, s11, s63
	s_cselect_b32 s36, s10, s43
	v_lshl_add_u64 v[176:177], s[0:1], 0, v[214:215]
	s_add_i32 m0, s44, 0xc000
	ds_read_b128 v[68:71], v248
	ds_read_b128 v[76:79], v248 offset:1024
	ds_read_b128 v[80:83], v248 offset:2048
	ds_read_b128 v[84:87], v248 offset:3072
	ds_read_b128 v[160:163], v248 offset:4096
	ds_read_b128 v[164:167], v248 offset:5120
	ds_read_b128 v[168:171], v248 offset:6144
	ds_read_b128 v[172:175], v248 offset:7168
	global_load_lds_dwordx4 v[176:177], off
	v_lshl_add_u64 v[176:177], s[0:1], 0, v[216:217]
	s_add_i32 m0, s44, 0xe000
	s_nop 0
	global_load_lds_dwordx4 v[176:177], off
	s_waitcnt lgkmcnt(8)
	s_barrier
	s_waitcnt lgkmcnt(0)
	s_setprio 1
	s_waitcnt lgkmcnt(0)
	v_mfma_f32_16x16x32_bf16 v[156:159], v[48:51], v[68:71], v[156:159]
	v_mfma_f32_16x16x32_bf16 v[156:159], v[52:55], v[76:79], v[156:159]
	v_mfma_f32_16x16x32_bf16 v[140:143], v[48:51], v[80:83], v[140:143]
	v_mfma_f32_16x16x32_bf16 v[140:143], v[52:55], v[84:87], v[140:143]
	v_mfma_f32_16x16x32_bf16 v[124:127], v[48:51], v[160:163], v[124:127]
	v_mfma_f32_16x16x32_bf16 v[124:127], v[52:55], v[164:167], v[124:127]
	v_mfma_f32_16x16x32_bf16 v[108:111], v[48:51], v[168:171], v[108:111]
	v_mfma_f32_16x16x32_bf16 v[108:111], v[52:55], v[172:175], v[108:111]
	v_mfma_f32_16x16x32_bf16 v[104:107], v[56:59], v[168:171], v[104:107]
	v_mfma_f32_16x16x32_bf16 v[104:107], v[60:63], v[172:175], v[104:107]
	v_mfma_f32_16x16x32_bf16 v[120:123], v[56:59], v[160:163], v[120:123]
	v_mfma_f32_16x16x32_bf16 v[120:123], v[60:63], v[164:167], v[120:123]
	v_mfma_f32_16x16x32_bf16 v[136:139], v[56:59], v[80:83], v[136:139]
	v_mfma_f32_16x16x32_bf16 v[136:139], v[60:63], v[84:87], v[136:139]
	v_mfma_f32_16x16x32_bf16 v[152:155], v[56:59], v[68:71], v[152:155]
	v_mfma_f32_16x16x32_bf16 v[152:155], v[60:63], v[76:79], v[152:155]
	s_setprio 0
	s_barrier
	s_add_i32 s67, 0, 0x14000
	s_add_i32 s66, s66, s41
	v_add_u32_e32 v187, s67, v233
	v_lshl_add_u64 v[230:231], s[36:37], 0, v[184:185]
	s_mov_b32 m0, s66
	ds_read_b128 v[176:179], v187
	ds_read_b128 v[180:183], v187 offset:1024
	ds_read_b128 v[218:221], v187 offset:2048
	ds_read_b128 v[222:225], v187 offset:3072
	global_load_lds_dwordx4 v[230:231], off
	v_lshl_add_u64 v[250:251], s[36:37], 0, v[212:213]
	s_add_i32 m0, s66, 0x2000
	s_nop 0
	global_load_lds_dwordx4 v[250:251], off
	s_barrier
	s_waitcnt lgkmcnt(0)
	s_setprio 1
	s_waitcnt lgkmcnt(0)
	v_mfma_f32_16x16x32_bf16 v[148:151], v[176:179], v[68:71], v[148:151]
	v_mfma_f32_16x16x32_bf16 v[68:71], v[218:221], v[68:71], v[144:147]
	v_mfma_f32_16x16x32_bf16 v[148:151], v[180:183], v[76:79], v[148:151]
	v_mfma_f32_16x16x32_bf16 v[68:71], v[222:225], v[76:79], v[68:71]
	v_mfma_f32_16x16x32_bf16 v[76:79], v[176:179], v[80:83], v[132:135]
	v_mfma_f32_16x16x32_bf16 v[80:83], v[218:221], v[80:83], v[128:131]
	v_mfma_f32_16x16x32_bf16 v[112:115], v[218:221], v[160:163], v[112:115]
	v_mfma_f32_16x16x32_bf16 v[100:103], v[176:179], v[168:171], v[100:103]
	v_mfma_f32_16x16x32_bf16 v[96:99], v[218:221], v[168:171], v[96:99]
	v_mfma_f32_16x16x32_bf16 v[76:79], v[180:183], v[84:87], v[76:79]
	v_mfma_f32_16x16x32_bf16 v[80:83], v[222:225], v[84:87], v[80:83]
	v_mfma_f32_16x16x32_bf16 v[84:87], v[176:179], v[160:163], v[116:119]
	v_mfma_f32_16x16x32_bf16 v[112:115], v[222:225], v[164:167], v[112:115]
	v_mfma_f32_16x16x32_bf16 v[100:103], v[180:183], v[172:175], v[100:103]
	v_mfma_f32_16x16x32_bf16 v[96:99], v[222:225], v[172:175], v[96:99]
	v_mfma_f32_16x16x32_bf16 v[84:87], v[180:183], v[164:167], v[84:87]
	s_setprio 0
	s_mov_b32 m0, s44
	v_lshl_add_u64 v[238:239], s[8:9], 0, v[208:209]
	s_barrier
	ds_read_b128 v[116:119], v248 offset:16384
	ds_read_b128 v[128:131], v248 offset:17408
	ds_read_b128 v[132:135], v248 offset:18432
	ds_read_b128 v[144:147], v248 offset:19456
	ds_read_b128 v[160:163], v248 offset:20480
	ds_read_b128 v[164:167], v248 offset:21504
	ds_read_b128 v[168:171], v248 offset:22528
	ds_read_b128 v[172:175], v248 offset:23552
	global_load_lds_dwordx4 v[238:239], off
	v_lshl_add_u64 v[188:189], s[8:9], 0, v[210:211]
	s_mov_b32 m0, s45
	s_nop 0
	global_load_lds_dwordx4 v[188:189], off
	s_barrier
	s_waitcnt lgkmcnt(0)
	s_setprio 1
	s_waitcnt lgkmcnt(0)
	v_mfma_f32_16x16x32_bf16 v[92:95], v[48:51], v[116:119], v[92:95]
	v_mfma_f32_16x16x32_bf16 v[92:95], v[52:55], v[128:131], v[92:95]
	v_mfma_f32_16x16x32_bf16 v[44:47], v[48:51], v[132:135], v[44:47]
	v_mfma_f32_16x16x32_bf16 v[44:47], v[52:55], v[144:147], v[44:47]
	v_mfma_f32_16x16x32_bf16 v[28:31], v[48:51], v[160:163], v[28:31]
	v_mfma_f32_16x16x32_bf16 v[28:31], v[52:55], v[164:167], v[28:31]
	v_mfma_f32_16x16x32_bf16 v[12:15], v[48:51], v[168:171], v[12:15]
	v_mfma_f32_16x16x32_bf16 v[12:15], v[52:55], v[172:175], v[12:15]
	v_mfma_f32_16x16x32_bf16 v[8:11], v[56:59], v[168:171], v[8:11]
	v_mfma_f32_16x16x32_bf16 v[8:11], v[60:63], v[172:175], v[8:11]
	v_mfma_f32_16x16x32_bf16 v[24:27], v[56:59], v[160:163], v[24:27]
	v_mfma_f32_16x16x32_bf16 v[24:27], v[60:63], v[164:167], v[24:27]
	v_mfma_f32_16x16x32_bf16 v[40:43], v[56:59], v[132:135], v[40:43]
	v_mfma_f32_16x16x32_bf16 v[40:43], v[60:63], v[144:147], v[40:43]
	v_mfma_f32_16x16x32_bf16 v[88:91], v[56:59], v[116:119], v[88:91]
	v_mfma_f32_16x16x32_bf16 v[88:91], v[60:63], v[128:131], v[88:91]
	s_setprio 0
	s_barrier
; #define PG8_STAGE(bufoff, gbase, voff) do { _Pragma("unroll") for (int _i = 0; _i < 2; ++_i) \
;         __builtin_amdgcn_global_load_lds((const unsigned*)((const char*)(gbase) + (voff)[_i]), (LAS unsigned*)(lds + (bufoff) + ldsw + _i * 8192), 16, 0, 0); } while (0)
; #define PG8_LDA(dst, b, h) do { _Pragma("unroll") for (int m = 0; m < 4; ++m) _Pragma("unroll") for (int k = 0; k < 2; ++k) dst[m][k] = *(const LAS bf16x8*)(lds + PG8_SA(b, h) + aoff + m * 2048 + k * 1024); } while (0)
; #define PG8_LDB(dst, b, h) do { _Pragma("unroll") for (int n = 0; n < 2; ++n) _Pragma("unroll") for (int k = 0; k < 2; ++k) dst[n][k] = *(const LAS bf16x8*)(lds + PG8_SB(b, h) + boff + n * 2048 + k * 1024); } while (0)
; #define PG8_MMA(ai, bj, At, Bt) do { __builtin_amdgcn_s_setprio(1); _Pragma("unroll") for (int m = 0; m < 4; ++m) _Pragma("unroll") for (int n = 0; n < 2; ++n) _Pragma("unroll") for (int k = 0; k < 2; ++k) \
;         acc[ai][bj][m][n] = __builtin_amdgcn_mfma_f32_16x16x32_bf16(Bt[n][k], At[m][k], acc[ai][bj][m][n], 0, 0, 0); __builtin_amdgcn_s_setprio(0); } while (0)
; #define PG8_WAIT_V(n) asm volatile("s_waitcnt vmcnt(" #n ")" ::: "memory")
; #define PG8_WAIT_L(n) asm volatile("s_waitcnt lgkmcnt(" #n ")" ::: "memory")
; #define PG8_BAR __builtin_amdgcn_s_barrier()
; #define PG8_SCHED __builtin_amdgcn_sched_barrier(0)
; template <class Epi>
; __device__ __forceinline__ void gemm_phase(LAS unsigned char* lds, const Gemm g, const StaticOrder& S, const Epi& E) {
;     ...
;             PG8_STAGE(PG8_SB(0, 1), b2 + hstep, voffB);
;             PG8_WAIT_V(6); PG8_BAR; PG8_MMA(1, 1, At, B1); PG8_BAR;
;             PG8_LDB(B0, 1, 0); PG8_SCHED; PG8_LDA(At, 1, 0); PG8_STAGE(PG8_SA(0, 1), a2 + hstep, voffA);
;             PG8_WAIT_L(8); PG8_BAR; PG8_WAIT_L(0); PG8_MMA(0, 0, At, B0); PG8_BAR; PG8_SCHED;
;             PG8_LDB(B1, 1, 1); PG8_STAGE(PG8_SB(1, 0), b3, voffB);
;             PG8_BAR; PG8_WAIT_L(0); PG8_MMA(0, 1, At, B1); PG8_BAR;
	s_add_u32 s36, s36, s52
	s_addc_u32 s37, s37, 0
	s_add_i32 s66, s67, s41
	v_lshl_add_u64 v[190:191], s[36:37], 0, v[184:185]
	s_mov_b32 m0, s66
	v_lshl_add_u64 v[192:193], s[36:37], 0, v[212:213]
	global_load_lds_dwordx4 v[190:191], off
	s_add_i32 m0, s66, 0x2000
	s_nop 0
	global_load_lds_dwordx4 v[192:193], off
	s_waitcnt vmcnt(6)
	s_barrier
	s_setprio 1
	v_mfma_f32_16x16x32_bf16 v[36:39], v[176:179], v[132:135], v[36:39]
	v_mfma_f32_16x16x32_bf16 v[36:39], v[180:183], v[144:147], v[36:39]
	v_mfma_f32_16x16x32_bf16 v[20:23], v[176:179], v[160:163], v[20:23]
	v_mfma_f32_16x16x32_bf16 v[20:23], v[180:183], v[164:167], v[20:23]
	v_mfma_f32_16x16x32_bf16 v[4:7], v[176:179], v[168:171], v[4:7]
	v_mfma_f32_16x16x32_bf16 v[4:7], v[180:183], v[172:175], v[4:7]
	v_mfma_f32_16x16x32_bf16 v[48:51], v[176:179], v[116:119], v[72:75]
	v_mfma_f32_16x16x32_bf16 v[48:51], v[180:183], v[128:131], v[48:51]
	v_mfma_f32_16x16x32_bf16 v[52:55], v[218:221], v[116:119], v[64:67]
	v_mfma_f32_16x16x32_bf16 v[52:55], v[222:225], v[128:131], v[52:55]
	v_mfma_f32_16x16x32_bf16 v[0:3], v[218:221], v[168:171], v[0:3]
	v_mfma_f32_16x16x32_bf16 v[0:3], v[222:225], v[172:175], v[0:3]
	v_mfma_f32_16x16x32_bf16 v[16:19], v[218:221], v[160:163], v[16:19]
	v_mfma_f32_16x16x32_bf16 v[16:19], v[222:225], v[164:167], v[16:19]
	v_mfma_f32_16x16x32_bf16 v[32:35], v[218:221], v[132:135], v[32:35]
	v_mfma_f32_16x16x32_bf16 v[32:35], v[222:225], v[144:147], v[32:35]
	s_setprio 0
	s_add_i32 s36, 0, 0x18000
	v_add_u32_e32 v72, s36, v233
	s_barrier
	ds_read_b128 v[56:59], v72
	ds_read_b128 v[60:63], v72 offset:1024
	ds_read_b128 v[64:67], v72 offset:2048
	ds_read_b128 v[72:75], v72 offset:3072
	s_add_u32 s8, s8, s52
	s_addc_u32 s9, s9, 0
	s_mov_b32 m0, s46
	v_lshl_add_u64 v[132:133], s[8:9], 0, v[208:209]
	ds_read_b128 v[116:119], v248 offset:32768
	ds_read_b128 v[128:131], v248 offset:33792
	ds_read_b128 v[160:163], v248 offset:34816
	ds_read_b128 v[164:167], v248 offset:35840
	ds_read_b128 v[168:171], v248 offset:36864
	ds_read_b128 v[172:175], v248 offset:37888
	ds_read_b128 v[176:179], v248 offset:38912
	ds_read_b128 v[180:183], v248 offset:39936
	global_load_lds_dwordx4 v[132:133], off
	v_lshl_add_u64 v[132:133], s[8:9], 0, v[210:211]
	s_mov_b32 m0, s47
	s_nop 0
	global_load_lds_dwordx4 v[132:133], off
	s_waitcnt lgkmcnt(8)
	s_barrier
	s_waitcnt lgkmcnt(0)
	s_setprio 1
	s_waitcnt lgkmcnt(0)
	v_mfma_f32_16x16x32_bf16 v[132:135], v[56:59], v[116:119], v[156:159]
	v_mfma_f32_16x16x32_bf16 v[156:159], v[60:63], v[128:131], v[132:135]
	v_mfma_f32_16x16x32_bf16 v[132:135], v[64:67], v[116:119], v[152:155]
	v_mfma_f32_16x16x32_bf16 v[152:155], v[72:75], v[128:131], v[132:135]
	v_mfma_f32_16x16x32_bf16 v[132:135], v[56:59], v[160:163], v[140:143]
	v_mfma_f32_16x16x32_bf16 v[140:143], v[60:63], v[164:167], v[132:135]
	v_mfma_f32_16x16x32_bf16 v[132:135], v[64:67], v[160:163], v[136:139]
	v_mfma_f32_16x16x32_bf16 v[124:127], v[56:59], v[168:171], v[124:127]
	v_mfma_f32_16x16x32_bf16 v[120:123], v[64:67], v[168:171], v[120:123]
	v_mfma_f32_16x16x32_bf16 v[108:111], v[56:59], v[176:179], v[108:111]
	v_mfma_f32_16x16x32_bf16 v[104:107], v[64:67], v[176:179], v[104:107]
	v_mfma_f32_16x16x32_bf16 v[136:139], v[72:75], v[164:167], v[132:135]
	v_mfma_f32_16x16x32_bf16 v[124:127], v[60:63], v[172:175], v[124:127]
	v_mfma_f32_16x16x32_bf16 v[120:123], v[72:75], v[172:175], v[120:123]
	v_mfma_f32_16x16x32_bf16 v[108:111], v[60:63], v[180:183], v[108:111]
	v_mfma_f32_16x16x32_bf16 v[104:107], v[72:75], v[180:183], v[104:107]
	s_setprio 0
	s_barrier
	s_add_i32 s8, 0, 0x1c000
	v_add_u32_e32 v132, s8, v233
	s_add_i32 s9, s36, s41
	ds_read_b128 v[218:221], v132
	ds_read_b128 v[222:225], v132 offset:1024
	ds_read_b128 v[226:229], v132 offset:2048
	ds_read_b128 v[204:207], v132 offset:3072
	v_lshl_add_u64 v[132:133], v[230:231], 0, s[58:59]
	s_mov_b32 m0, s9
	s_nop 0
	global_load_lds_dwordx4 v[132:133], off
	v_lshl_add_u64 v[132:133], v[250:251], 0, s[58:59]
	s_add_i32 m0, s9, 0x2000
	s_nop 0
	global_load_lds_dwordx4 v[132:133], off
	s_barrier
; #define PG8_STAGE(bufoff, gbase, voff) do { _Pragma("unroll") for (int _i = 0; _i < 2; ++_i) \
;         __builtin_amdgcn_global_load_lds((const unsigned*)((const char*)(gbase) + (voff)[_i]), (LAS unsigned*)(lds + (bufoff) + ldsw + _i * 8192), 16, 0, 0); } while (0)
; #define PG8_LDA(dst, b, h) do { _Pragma("unroll") for (int m = 0; m < 4; ++m) _Pragma("unroll") for (int k = 0; k < 2; ++k) dst[m][k] = *(const LAS bf16x8*)(lds + PG8_SA(b, h) + aoff + m * 2048 + k * 1024); } while (0)
; #define PG8_MMA(ai, bj, At, Bt) do { __builtin_amdgcn_s_setprio(1); _Pragma("unroll") for (int m = 0; m < 4; ++m) _Pragma("unroll") for (int n = 0; n < 2; ++n) _Pragma("unroll") for (int k = 0; k < 2; ++k) \
;         acc[ai][bj][m][n] = __builtin_amdgcn_mfma_f32_16x16x32_bf16(Bt[n][k], At[m][k], acc[ai][bj][m][n], 0, 0, 0); __builtin_amdgcn_s_setprio(0); } while (0)
; #define PG8_WAIT_V(n) asm volatile("s_waitcnt vmcnt(" #n ")" ::: "memory")
; #define PG8_WAIT_L(n) asm volatile("s_waitcnt lgkmcnt(" #n ")" ::: "memory")
; #define PG8_BAR __builtin_amdgcn_s_barrier()
; #define PG8_SCHED __builtin_amdgcn_sched_barrier(0)
; template <class Epi>
; __device__ __forceinline__ void gemm_phase(LAS unsigned char* lds, const Gemm g, const StaticOrder& S, const Epi& E) {
;     ...
;             PG8_LDA(At, 1, 1); PG8_STAGE(PG8_SA(1, 0), a3, voffA);
;             PG8_BAR; PG8_WAIT_L(0); PG8_MMA(1, 0, At, B0); PG8_BAR; PG8_SCHED;
;             PG8_STAGE(PG8_SB(1, 1), b3 + hstep, voffB);
;             PG8_WAIT_V(6); PG8_BAR; PG8_MMA(1, 1, At, B1); PG8_BAR;
;     __device__ __forceinline__ void operator()(const Acc& acc, const Unit& u, int wr, int wc, int fr, int fq) const {
;         const int row0 = u.pm * 256 + wr * 64 + fr, col0 = u.pn * 256 + wc * 32 + 8 * fq;
;         const bf16_t* __restrict__ xr = xres; bf16_t* __restrict__ op = out;
;         f32x4 gv[2][2], bv[2][2];
;         if (stats) {
; #pragma unroll
;             for (int bj = 0; bj < 2; ++bj)
; #pragma unroll
;                 for (int n = 0; n < 2; ++n) { gv[bj][n] = *(const f32x4*)(lg + col0 + bj * 128 + n * 4); bv[bj][n] = *(const f32x4*)(lb + col0 + bj * 128 + n * 4); } }
	s_waitcnt lgkmcnt(0)
	s_setprio 1
	s_waitcnt lgkmcnt(0)
	v_mfma_f32_16x16x32_bf16 v[68:71], v[226:229], v[116:119], v[68:71]
	v_mfma_f32_16x16x32_bf16 v[132:135], v[218:221], v[116:119], v[148:151]
	v_mfma_f32_16x16x32_bf16 v[144:147], v[204:207], v[128:131], v[68:71]
	v_mfma_f32_16x16x32_bf16 v[68:71], v[218:221], v[160:163], v[76:79]
	v_mfma_f32_16x16x32_bf16 v[148:151], v[222:225], v[128:131], v[132:135]
	v_mfma_f32_16x16x32_bf16 v[132:135], v[222:225], v[164:167], v[68:71]
	v_mfma_f32_16x16x32_bf16 v[68:71], v[226:229], v[160:163], v[80:83]
	v_mfma_f32_16x16x32_bf16 v[128:131], v[204:207], v[164:167], v[68:71]
	v_mfma_f32_16x16x32_bf16 v[68:71], v[218:221], v[168:171], v[84:87]
	v_mfma_f32_16x16x32_bf16 v[116:119], v[222:225], v[172:175], v[68:71]
	v_mfma_f32_16x16x32_bf16 v[68:71], v[226:229], v[168:171], v[112:115]
	v_mfma_f32_16x16x32_bf16 v[112:115], v[204:207], v[172:175], v[68:71]
	v_mfma_f32_16x16x32_bf16 v[68:71], v[218:221], v[176:179], v[100:103]
	v_mfma_f32_16x16x32_bf16 v[100:103], v[222:225], v[180:183], v[68:71]
	v_mfma_f32_16x16x32_bf16 v[68:71], v[226:229], v[176:179], v[96:99]
	v_mfma_f32_16x16x32_bf16 v[96:99], v[204:207], v[180:183], v[68:71]
	s_setprio 0
	s_mov_b32 m0, s50
	v_lshl_add_u64 v[176:177], v[238:239], 0, s[58:59]
	s_barrier
	s_nop 2
	ds_read_b128 v[68:71], v248 offset:49152
	ds_read_b128 v[76:79], v248 offset:50176
	ds_read_b128 v[80:83], v248 offset:51200
	ds_read_b128 v[84:87], v248 offset:52224
	ds_read_b128 v[160:163], v248 offset:53248
	ds_read_b128 v[164:167], v248 offset:54272
	ds_read_b128 v[168:171], v248 offset:55296
	ds_read_b128 v[172:175], v248 offset:56320
	global_load_lds_dwordx4 v[176:177], off
	v_lshl_add_u64 v[176:177], v[188:189], 0, s[58:59]
	s_mov_b32 m0, s51
	s_nop 0
	global_load_lds_dwordx4 v[176:177], off
	s_barrier
	s_waitcnt lgkmcnt(0)
	s_setprio 1
	s_waitcnt lgkmcnt(0)
	v_mfma_f32_16x16x32_bf16 v[92:95], v[56:59], v[68:71], v[92:95]
	v_mfma_f32_16x16x32_bf16 v[92:95], v[60:63], v[76:79], v[92:95]
	v_mfma_f32_16x16x32_bf16 v[44:47], v[56:59], v[80:83], v[44:47]
	v_mfma_f32_16x16x32_bf16 v[44:47], v[60:63], v[84:87], v[44:47]
	v_mfma_f32_16x16x32_bf16 v[28:31], v[56:59], v[160:163], v[28:31]
	v_mfma_f32_16x16x32_bf16 v[28:31], v[60:63], v[164:167], v[28:31]
	v_mfma_f32_16x16x32_bf16 v[12:15], v[56:59], v[168:171], v[12:15]
	v_mfma_f32_16x16x32_bf16 v[12:15], v[60:63], v[172:175], v[12:15]
	v_mfma_f32_16x16x32_bf16 v[8:11], v[64:67], v[168:171], v[8:11]
	v_mfma_f32_16x16x32_bf16 v[8:11], v[72:75], v[172:175], v[8:11]
	v_mfma_f32_16x16x32_bf16 v[24:27], v[64:67], v[160:163], v[24:27]
	v_mfma_f32_16x16x32_bf16 v[24:27], v[72:75], v[164:167], v[24:27]
	v_mfma_f32_16x16x32_bf16 v[40:43], v[64:67], v[80:83], v[40:43]
	v_mfma_f32_16x16x32_bf16 v[40:43], v[72:75], v[84:87], v[40:43]
	v_mfma_f32_16x16x32_bf16 v[88:91], v[64:67], v[68:71], v[88:91]
	v_mfma_f32_16x16x32_bf16 v[88:91], v[72:75], v[76:79], v[88:91]
	s_setprio 0
	s_barrier
	s_add_i32 s8, s8, s41
	v_lshl_add_u64 v[56:57], v[190:191], 0, s[58:59]
	s_mov_b32 m0, s8
	s_nop 0
	global_load_lds_dwordx4 v[56:57], off
	v_lshl_add_u64 v[56:57], v[192:193], 0, s[58:59]
	s_add_i32 m0, s8, 0x2000
	s_nop 0
	global_load_lds_dwordx4 v[56:57], off
	s_waitcnt vmcnt(6)
	s_barrier
	s_setprio 1
	v_mfma_f32_16x16x32_bf16 v[48:51], v[218:221], v[68:71], v[48:51]
	v_mfma_f32_16x16x32_bf16 v[72:75], v[222:225], v[76:79], v[48:51]
	v_mfma_f32_16x16x32_bf16 v[48:51], v[226:229], v[68:71], v[52:55]
	v_mfma_f32_16x16x32_bf16 v[36:39], v[218:221], v[80:83], v[36:39]
	v_mfma_f32_16x16x32_bf16 v[32:35], v[226:229], v[80:83], v[32:35]
	v_mfma_f32_16x16x32_bf16 v[20:23], v[218:221], v[160:163], v[20:23]
	v_mfma_f32_16x16x32_bf16 v[16:19], v[226:229], v[160:163], v[16:19]
	v_mfma_f32_16x16x32_bf16 v[4:7], v[218:221], v[168:171], v[4:7]
	v_mfma_f32_16x16x32_bf16 v[0:3], v[226:229], v[168:171], v[0:3]
	v_mfma_f32_16x16x32_bf16 v[64:67], v[204:207], v[76:79], v[48:51]
	v_mfma_f32_16x16x32_bf16 v[36:39], v[222:225], v[84:87], v[36:39]
	v_mfma_f32_16x16x32_bf16 v[32:35], v[204:207], v[84:87], v[32:35]
	v_mfma_f32_16x16x32_bf16 v[20:23], v[222:225], v[164:167], v[20:23]
	v_mfma_f32_16x16x32_bf16 v[16:19], v[204:207], v[164:167], v[16:19]
	v_mfma_f32_16x16x32_bf16 v[4:7], v[222:225], v[172:175], v[4:7]
	v_mfma_f32_16x16x32_bf16 v[0:3], v[204:207], v[172:175], v[0:3]
	s_setprio 0
	s_add_u32 s0, s0, 0x100
	s_addc_u32 s1, s1, 0
	s_add_u32 s43, s43, 0x100
	s_addc_u32 s63, s63, 0
	s_cmp_ge_u32 s68, s54
	s_mov_b32 s8, s68
	s_barrier
	s_cbranch_scc0 .LBB0_591
	v_lshl_or_b32 v224, s42, 8, v247
	v_cndmask_b32_e64 v48, 0, 1, s[30:31]
	v_cmp_ne_u32_e64 s[8:9], 1, v48
	s_andn2_b64 vcc, exec, s[30:31]
	v_ashrrev_i32_e32 v225, 31, v224
	s_cbranch_vccnz .LBB0_594
	v_lshlrev_b64 v[48:49], 2, v[224:225]
	v_lshl_add_u64 v[52:53], s[20:21], 0, v[48:49]
	v_lshl_add_u64 v[60:61], s[22:23], 0, v[48:49]
	global_load_dwordx4 v[68:71], v[52:53], off offset:16
	global_load_dwordx4 v[80:83], v[52:53], off
	global_load_dwordx4 v[76:79], v[60:61], off offset:16
	global_load_dwordx4 v[84:87], v[60:61], off
	global_load_dwordx4 v[48:51], v[52:53], off offset:528
	global_load_dwordx4 v[56:59], v[52:53], off offset:512
	s_nop 0
	global_load_dwordx4 v[52:55], v[60:61], off offset:528
	s_nop 0
	global_load_dwordx4 v[60:63], v[60:61], off offset:512

; #define PG8_STAGE(bufoff, gbase, voff) do { _Pragma("unroll") for (int _i = 0; _i < 2; ++_i) \
;         __builtin_amdgcn_global_load_lds((const unsigned*)((const char*)(gbase) + (voff)[_i]), (LAS unsigned*)(lds + (bufoff) + ldsw + _i * 8192), 16, 0, 0); } while (0)
; #define PG8_LDA(dst, b, h) do { _Pragma("unroll") for (int m = 0; m < 4; ++m) _Pragma("unroll") for (int k = 0; k < 2; ++k) dst[m][k] = *(const LAS bf16x8*)(lds + PG8_SA(b, h) + aoff + m * 2048 + k * 1024); } while (0)
; #define PG8_LDB(dst, b, h) do { _Pragma("unroll") for (int n = 0; n < 2; ++n) _Pragma("unroll") for (int k = 0; k < 2; ++k) dst[n][k] = *(const LAS bf16x8*)(lds + PG8_SB(b, h) + boff + n * 2048 + k * 1024); } while (0)
; #define PG8_MMA(ai, bj, At, Bt) do { __builtin_amdgcn_s_setprio(1); _Pragma("unroll") for (int m = 0; m < 4; ++m) _Pragma("unroll") for (int n = 0; n < 2; ++n) _Pragma("unroll") for (int k = 0; k < 2; ++k) \
;         acc[ai][bj][m][n] = __builtin_amdgcn_mfma_f32_16x16x32_bf16(Bt[n][k], At[m][k], acc[ai][bj][m][n], 0, 0, 0); __builtin_amdgcn_s_setprio(0); } while (0)
; #define PG8_WAIT_L(n) asm volatile("s_waitcnt lgkmcnt(" #n ")" ::: "memory")
; #define PG8_BAR __builtin_amdgcn_s_barrier()
; #define PG8_SCHED __builtin_amdgcn_sched_barrier(0)
; template <class Epi>
; __device__ __forceinline__ void gemm_phase(LAS unsigned char* lds, const Gemm g, const StaticOrder& S, const Epi& E) {
;     ...
;         for (int t = 0; t < nt; t += 2) {
;             const bool last = (t == nt - 2);
;             const char* a1 = cA + (size_t)(t + 1) * kstep;
;             const char* a2 = last ? nA : cA + (size_t)(t + 2) * kstep; const char* b2 = last ? nB : cB + (size_t)(t + 2) * kstep;
;             const char* a3 = a2 + kstep; const char* b3 = b2 + kstep;
;             PG8_LDB(B0, 0, 0); PG8_SCHED; PG8_LDA(At, 0, 0); PG8_STAGE(PG8_SA(1, 1), a1 + hstep, voffA);
;             PG8_WAIT_L(8); PG8_BAR; PG8_WAIT_L(0); PG8_MMA(0, 0, At, B0); PG8_BAR; PG8_SCHED;
;             PG8_LDB(B1, 0, 1); PG8_STAGE(PG8_SB(0, 0), b2, voffB);
;             PG8_BAR; PG8_WAIT_L(0); PG8_MMA(0, 1, At, B1); PG8_BAR;
;             PG8_LDA(At, 0, 1); PG8_STAGE(PG8_SA(0, 0), a2, voffA);
;             PG8_BAR; PG8_WAIT_L(0); PG8_MMA(1, 0, At, B0); PG8_BAR; PG8_SCHED;
.LBB0_721:
	s_add_u32 s18, s16, 0xfff80080
	s_addc_u32 s19, s17, -1
	s_add_i32 s39, 0, 0x10000
	v_add_u32_e32 v154, s39, v139
	ds_read_b128 v[142:145], v154
	ds_read_b128 v[146:149], v154 offset:1024
	ds_read_b128 v[150:153], v154 offset:2048
	ds_read_b128 v[154:157], v154 offset:3072
	s_cmp_eq_u32 s38, 28
	s_cselect_b32 s21, s9, s19
	s_cselect_b32 s20, s34, s18
	s_cselect_b32 s19, s1, s37
	s_cselect_b32 s18, s35, s36
	v_lshl_add_u64 v[182:183], s[16:17], 0, v[134:135]
	s_add_i32 m0, s15, 0xc000
	ds_read_b128 v[158:161], v141
	ds_read_b128 v[162:165], v141 offset:1024
	ds_read_b128 v[166:169], v141 offset:2048
	ds_read_b128 v[170:173], v141 offset:3072
	ds_read_b128 v[174:177], v141 offset:4096
	ds_read_b128 v[178:181], v141 offset:5120
	ds_read_b128 v[208:211], v141 offset:6144
	ds_read_b128 v[212:215], v141 offset:7168
	global_load_lds_dwordx4 v[182:183], off
	v_lshl_add_u64 v[182:183], s[16:17], 0, v[136:137]
	s_add_i32 m0, s15, 0xe000
	s_nop 0
	global_load_lds_dwordx4 v[182:183], off
	s_waitcnt lgkmcnt(8)
	s_barrier
	s_waitcnt lgkmcnt(0)
	s_setprio 1
	s_waitcnt lgkmcnt(0)
	v_mfma_f32_16x16x32_bf16 v[124:127], v[142:145], v[158:161], v[124:127]
	v_mfma_f32_16x16x32_bf16 v[124:127], v[146:149], v[162:165], v[124:127]
	v_mfma_f32_16x16x32_bf16 v[108:111], v[142:145], v[166:169], v[108:111]
	v_mfma_f32_16x16x32_bf16 v[108:111], v[146:149], v[170:173], v[108:111]
	v_mfma_f32_16x16x32_bf16 v[92:95], v[142:145], v[174:177], v[92:95]
	v_mfma_f32_16x16x32_bf16 v[92:95], v[146:149], v[178:181], v[92:95]
	v_mfma_f32_16x16x32_bf16 v[76:79], v[142:145], v[208:211], v[76:79]
	v_mfma_f32_16x16x32_bf16 v[76:79], v[146:149], v[212:215], v[76:79]
	v_mfma_f32_16x16x32_bf16 v[68:71], v[150:153], v[208:211], v[68:71]
	v_mfma_f32_16x16x32_bf16 v[68:71], v[154:157], v[212:215], v[68:71]
	v_mfma_f32_16x16x32_bf16 v[84:87], v[150:153], v[174:177], v[84:87]
	v_mfma_f32_16x16x32_bf16 v[84:87], v[154:157], v[178:181], v[84:87]
	v_mfma_f32_16x16x32_bf16 v[100:103], v[150:153], v[166:169], v[100:103]
	v_mfma_f32_16x16x32_bf16 v[100:103], v[154:157], v[170:173], v[100:103]
	v_mfma_f32_16x16x32_bf16 v[116:119], v[150:153], v[158:161], v[116:119]
	v_mfma_f32_16x16x32_bf16 v[116:119], v[154:157], v[162:165], v[116:119]
	s_setprio 0
	s_barrier
	s_add_i32 s42, 0, 0x14000
	v_add_u32_e32 v182, s42, v139
	s_add_i32 s39, s39, s24
	ds_read_b128 v[216:219], v182
	ds_read_b128 v[220:223], v182 offset:1024
	ds_read_b128 v[224:227], v182 offset:2048
	ds_read_b128 v[228:231], v182 offset:3072
	v_lshl_add_u64 v[182:183], s[18:19], 0, v[184:185]
	s_mov_b32 m0, s39
	v_lshl_add_u64 v[204:205], s[18:19], 0, v[128:129]
	global_load_lds_dwordx4 v[182:183], off
	s_add_i32 m0, s39, 0x2000
	s_nop 0
	global_load_lds_dwordx4 v[204:205], off
	s_barrier
	s_waitcnt lgkmcnt(0)
	s_setprio 1
	s_waitcnt lgkmcnt(0)
	v_mfma_f32_16x16x32_bf16 v[120:123], v[216:219], v[158:161], v[120:123]
	v_mfma_f32_16x16x32_bf16 v[120:123], v[220:223], v[162:165], v[120:123]
	v_mfma_f32_16x16x32_bf16 v[104:107], v[216:219], v[166:169], v[104:107]
	v_mfma_f32_16x16x32_bf16 v[104:107], v[220:223], v[170:173], v[104:107]
	v_mfma_f32_16x16x32_bf16 v[88:91], v[216:219], v[174:177], v[88:91]
	v_mfma_f32_16x16x32_bf16 v[88:91], v[220:223], v[178:181], v[88:91]
	v_mfma_f32_16x16x32_bf16 v[72:75], v[216:219], v[208:211], v[72:75]
	v_mfma_f32_16x16x32_bf16 v[72:75], v[220:223], v[212:215], v[72:75]
	v_mfma_f32_16x16x32_bf16 v[64:67], v[224:227], v[208:211], v[64:67]
	v_mfma_f32_16x16x32_bf16 v[64:67], v[228:231], v[212:215], v[64:67]
	v_mfma_f32_16x16x32_bf16 v[80:83], v[224:227], v[174:177], v[80:83]
	v_mfma_f32_16x16x32_bf16 v[80:83], v[228:231], v[178:181], v[80:83]
	v_mfma_f32_16x16x32_bf16 v[96:99], v[224:227], v[166:169], v[96:99]
	v_mfma_f32_16x16x32_bf16 v[96:99], v[228:231], v[170:173], v[96:99]
	v_mfma_f32_16x16x32_bf16 v[112:115], v[224:227], v[158:161], v[112:115]
	v_mfma_f32_16x16x32_bf16 v[112:115], v[228:231], v[162:165], v[112:115]
	s_setprio 0
	s_mov_b32 m0, s15
	v_lshl_add_u64 v[206:207], s[20:21], 0, v[132:133]
	s_barrier
	ds_read_b128 v[158:161], v141 offset:16384
	ds_read_b128 v[162:165], v141 offset:17408
	ds_read_b128 v[166:169], v141 offset:18432
	ds_read_b128 v[170:173], v141 offset:19456
	ds_read_b128 v[174:177], v141 offset:20480
	ds_read_b128 v[178:181], v141 offset:21504
	ds_read_b128 v[208:211], v141 offset:22528
	ds_read_b128 v[212:215], v141 offset:23552
	global_load_lds_dwordx4 v[206:207], off
	v_lshl_add_u64 v[232:233], s[20:21], 0, v[130:131]
	s_mov_b32 m0, s26
	s_nop 0
	global_load_lds_dwordx4 v[232:233], off
	s_barrier
	s_waitcnt lgkmcnt(0)
	s_setprio 1
	s_waitcnt lgkmcnt(0)
	v_mfma_f32_16x16x32_bf16 v[60:63], v[142:145], v[158:161], v[60:63]
	v_mfma_f32_16x16x32_bf16 v[60:63], v[146:149], v[162:165], v[60:63]
	v_mfma_f32_16x16x32_bf16 v[44:47], v[142:145], v[166:169], v[44:47]
	v_mfma_f32_16x16x32_bf16 v[44:47], v[146:149], v[170:173], v[44:47]
	v_mfma_f32_16x16x32_bf16 v[28:31], v[142:145], v[174:177], v[28:31]
	v_mfma_f32_16x16x32_bf16 v[28:31], v[146:149], v[178:181], v[28:31]
	v_mfma_f32_16x16x32_bf16 v[12:15], v[142:145], v[208:211], v[12:15]
	v_mfma_f32_16x16x32_bf16 v[12:15], v[146:149], v[212:215], v[12:15]
	v_mfma_f32_16x16x32_bf16 v[4:7], v[150:153], v[208:211], v[4:7]
	v_mfma_f32_16x16x32_bf16 v[4:7], v[154:157], v[212:215], v[4:7]
	v_mfma_f32_16x16x32_bf16 v[20:23], v[150:153], v[174:177], v[20:23]
	v_mfma_f32_16x16x32_bf16 v[20:23], v[154:157], v[178:181], v[20:23]
	v_mfma_f32_16x16x32_bf16 v[36:39], v[150:153], v[166:169], v[36:39]
	v_mfma_f32_16x16x32_bf16 v[36:39], v[154:157], v[170:173], v[36:39]
	v_mfma_f32_16x16x32_bf16 v[52:55], v[150:153], v[158:161], v[52:55]
	v_mfma_f32_16x16x32_bf16 v[52:55], v[154:157], v[162:165], v[52:55]
	s_setprio 0
	s_barrier
; #define PG8_STAGE(bufoff, gbase, voff) do { _Pragma("unroll") for (int _i = 0; _i < 2; ++_i) \
;         __builtin_amdgcn_global_load_lds((const unsigned*)((const char*)(gbase) + (voff)[_i]), (LAS unsigned*)(lds + (bufoff) + ldsw + _i * 8192), 16, 0, 0); } while (0)
; #define PG8_LDA(dst, b, h) do { _Pragma("unroll") for (int m = 0; m < 4; ++m) _Pragma("unroll") for (int k = 0; k < 2; ++k) dst[m][k] = *(const LAS bf16x8*)(lds + PG8_SA(b, h) + aoff + m * 2048 + k * 1024); } while (0)
; #define PG8_LDB(dst, b, h) do { _Pragma("unroll") for (int n = 0; n < 2; ++n) _Pragma("unroll") for (int k = 0; k < 2; ++k) dst[n][k] = *(const LAS bf16x8*)(lds + PG8_SB(b, h) + boff + n * 2048 + k * 1024); } while (0)
; #define PG8_MMA(ai, bj, At, Bt) do { __builtin_amdgcn_s_setprio(1); _Pragma("unroll") for (int m = 0; m < 4; ++m) _Pragma("unroll") for (int n = 0; n < 2; ++n) _Pragma("unroll") for (int k = 0; k < 2; ++k) \
;         acc[ai][bj][m][n] = __builtin_amdgcn_mfma_f32_16x16x32_bf16(Bt[n][k], At[m][k], acc[ai][bj][m][n], 0, 0, 0); __builtin_amdgcn_s_setprio(0); } while (0)
; #define PG8_WAIT_V(n) asm volatile("s_waitcnt vmcnt(" #n ")" ::: "memory")
; #define PG8_WAIT_L(n) asm volatile("s_waitcnt lgkmcnt(" #n ")" ::: "memory")
; #define PG8_BAR __builtin_amdgcn_s_barrier()
; #define PG8_SCHED __builtin_amdgcn_sched_barrier(0)
; template <class Epi>
; __device__ __forceinline__ void gemm_phase(LAS unsigned char* lds, const Gemm g, const StaticOrder& S, const Epi& E) {
;     ...
;             PG8_STAGE(PG8_SB(0, 1), b2 + hstep, voffB);
;             PG8_WAIT_V(6); PG8_BAR; PG8_MMA(1, 1, At, B1); PG8_BAR;
;             PG8_LDB(B0, 1, 0); PG8_SCHED; PG8_LDA(At, 1, 0); PG8_STAGE(PG8_SA(0, 1), a2 + hstep, voffA);
;             PG8_WAIT_L(8); PG8_BAR; PG8_WAIT_L(0); PG8_MMA(0, 0, At, B0); PG8_BAR; PG8_SCHED;
;             PG8_LDB(B1, 1, 1); PG8_STAGE(PG8_SB(1, 0), b3, voffB);
;             PG8_BAR; PG8_WAIT_L(0); PG8_MMA(0, 1, At, B1); PG8_BAR;
;             PG8_LDA(At, 1, 1); PG8_STAGE(PG8_SA(1, 0), a3, voffA);
;             PG8_BAR; PG8_WAIT_L(0); PG8_MMA(1, 0, At, B0); PG8_BAR; PG8_SCHED;
	s_add_u32 s40, s18, 0x80000
	s_addc_u32 s41, s19, 0
	s_add_i32 s39, s42, s24
	v_lshl_add_u64 v[142:143], s[40:41], 0, v[184:185]
	s_mov_b32 m0, s39
	s_nop 0
	global_load_lds_dwordx4 v[142:143], off
	v_lshl_add_u64 v[142:143], s[40:41], 0, v[128:129]
	s_add_i32 m0, s39, 0x2000
	s_nop 0
	global_load_lds_dwordx4 v[142:143], off
	s_waitcnt vmcnt(6)
	s_barrier
	s_setprio 1
	v_mfma_f32_16x16x32_bf16 v[56:59], v[216:219], v[158:161], v[56:59]
	v_mfma_f32_16x16x32_bf16 v[56:59], v[220:223], v[162:165], v[56:59]
	v_mfma_f32_16x16x32_bf16 v[40:43], v[216:219], v[166:169], v[40:43]
	v_mfma_f32_16x16x32_bf16 v[40:43], v[220:223], v[170:173], v[40:43]
	v_mfma_f32_16x16x32_bf16 v[24:27], v[216:219], v[174:177], v[24:27]
	v_mfma_f32_16x16x32_bf16 v[24:27], v[220:223], v[178:181], v[24:27]
	v_mfma_f32_16x16x32_bf16 v[8:11], v[216:219], v[208:211], v[8:11]
	v_mfma_f32_16x16x32_bf16 v[8:11], v[220:223], v[212:215], v[8:11]
	v_mfma_f32_16x16x32_bf16 v[0:3], v[224:227], v[208:211], v[0:3]
	v_mfma_f32_16x16x32_bf16 v[0:3], v[228:231], v[212:215], v[0:3]
	v_mfma_f32_16x16x32_bf16 v[16:19], v[224:227], v[174:177], v[16:19]
	v_mfma_f32_16x16x32_bf16 v[16:19], v[228:231], v[178:181], v[16:19]
	v_mfma_f32_16x16x32_bf16 v[32:35], v[224:227], v[166:169], v[32:35]
	v_mfma_f32_16x16x32_bf16 v[32:35], v[228:231], v[170:173], v[32:35]
	v_mfma_f32_16x16x32_bf16 v[48:51], v[224:227], v[158:161], v[48:51]
	v_mfma_f32_16x16x32_bf16 v[48:51], v[228:231], v[162:165], v[48:51]
	s_setprio 0
	s_add_i32 s39, 0, 0x18000
	v_add_u32_e32 v154, s39, v139
	s_barrier
	ds_read_b128 v[142:145], v154
	ds_read_b128 v[146:149], v154 offset:1024
	ds_read_b128 v[150:153], v154 offset:2048
	ds_read_b128 v[154:157], v154 offset:3072
	s_add_u32 s20, s20, 0x80000
	s_addc_u32 s21, s21, 0
	s_mov_b32 m0, s27
	v_lshl_add_u64 v[216:217], s[20:21], 0, v[132:133]
	ds_read_b128 v[158:161], v141 offset:32768
	ds_read_b128 v[162:165], v141 offset:33792
	ds_read_b128 v[166:169], v141 offset:34816
	ds_read_b128 v[170:173], v141 offset:35840
	ds_read_b128 v[174:177], v141 offset:36864
	ds_read_b128 v[178:181], v141 offset:37888
	ds_read_b128 v[208:211], v141 offset:38912
	ds_read_b128 v[212:215], v141 offset:39936
	global_load_lds_dwordx4 v[216:217], off
	v_lshl_add_u64 v[216:217], s[20:21], 0, v[130:131]
	s_mov_b32 m0, s28
	s_nop 0
	global_load_lds_dwordx4 v[216:217], off
	s_waitcnt lgkmcnt(8)
	s_barrier
	s_waitcnt lgkmcnt(0)
	s_setprio 1
	s_waitcnt lgkmcnt(0)
	v_mfma_f32_16x16x32_bf16 v[124:127], v[142:145], v[158:161], v[124:127]
	v_mfma_f32_16x16x32_bf16 v[124:127], v[146:149], v[162:165], v[124:127]
	v_mfma_f32_16x16x32_bf16 v[108:111], v[142:145], v[166:169], v[108:111]
	v_mfma_f32_16x16x32_bf16 v[108:111], v[146:149], v[170:173], v[108:111]
	v_mfma_f32_16x16x32_bf16 v[92:95], v[142:145], v[174:177], v[92:95]
	v_mfma_f32_16x16x32_bf16 v[92:95], v[146:149], v[178:181], v[92:95]
	v_mfma_f32_16x16x32_bf16 v[76:79], v[142:145], v[208:211], v[76:79]
	v_mfma_f32_16x16x32_bf16 v[76:79], v[146:149], v[212:215], v[76:79]
	v_mfma_f32_16x16x32_bf16 v[68:71], v[150:153], v[208:211], v[68:71]
	v_mfma_f32_16x16x32_bf16 v[68:71], v[154:157], v[212:215], v[68:71]
	v_mfma_f32_16x16x32_bf16 v[84:87], v[150:153], v[174:177], v[84:87]
	v_mfma_f32_16x16x32_bf16 v[84:87], v[154:157], v[178:181], v[84:87]
	v_mfma_f32_16x16x32_bf16 v[100:103], v[150:153], v[166:169], v[100:103]
	v_mfma_f32_16x16x32_bf16 v[100:103], v[154:157], v[170:173], v[100:103]
	v_mfma_f32_16x16x32_bf16 v[116:119], v[150:153], v[158:161], v[116:119]
	v_mfma_f32_16x16x32_bf16 v[116:119], v[154:157], v[162:165], v[116:119]
	s_setprio 0
	s_barrier
	s_add_i32 s20, 0, 0x1c000
	s_add_i32 s21, s39, s24
	v_add_u32_e32 v187, s20, v139
	v_lshl_add_u64 v[182:183], v[182:183], 0, s[58:59]
	s_mov_b32 m0, s21
	ds_read_b128 v[216:219], v187
	ds_read_b128 v[220:223], v187 offset:1024
	ds_read_b128 v[224:227], v187 offset:2048
	ds_read_b128 v[228:231], v187 offset:3072
	global_load_lds_dwordx4 v[182:183], off
	v_lshl_add_u64 v[182:183], v[204:205], 0, s[58:59]
	s_add_i32 m0, s21, 0x2000
	s_nop 0
	global_load_lds_dwordx4 v[182:183], off
	s_barrier
	s_waitcnt lgkmcnt(0)
	s_setprio 1
	s_waitcnt lgkmcnt(0)
	v_mfma_f32_16x16x32_bf16 v[120:123], v[216:219], v[158:161], v[120:123]
	v_mfma_f32_16x16x32_bf16 v[120:123], v[220:223], v[162:165], v[120:123]
	v_mfma_f32_16x16x32_bf16 v[104:107], v[216:219], v[166:169], v[104:107]
	v_mfma_f32_16x16x32_bf16 v[104:107], v[220:223], v[170:173], v[104:107]
	v_mfma_f32_16x16x32_bf16 v[88:91], v[216:219], v[174:177], v[88:91]
	v_mfma_f32_16x16x32_bf16 v[88:91], v[220:223], v[178:181], v[88:91]
	v_mfma_f32_16x16x32_bf16 v[72:75], v[216:219], v[208:211], v[72:75]
	v_mfma_f32_16x16x32_bf16 v[72:75], v[220:223], v[212:215], v[72:75]
	v_mfma_f32_16x16x32_bf16 v[64:67], v[224:227], v[208:211], v[64:67]
	v_mfma_f32_16x16x32_bf16 v[64:67], v[228:231], v[212:215], v[64:67]
	v_mfma_f32_16x16x32_bf16 v[80:83], v[224:227], v[174:177], v[80:83]
	v_mfma_f32_16x16x32_bf16 v[80:83], v[228:231], v[178:181], v[80:83]
	v_mfma_f32_16x16x32_bf16 v[96:99], v[224:227], v[166:169], v[96:99]
	v_mfma_f32_16x16x32_bf16 v[96:99], v[228:231], v[170:173], v[96:99]
	v_mfma_f32_16x16x32_bf16 v[112:115], v[224:227], v[158:161], v[112:115]
	v_mfma_f32_16x16x32_bf16 v[112:115], v[228:231], v[162:165], v[112:115]
	s_setprio 0
	s_mov_b32 m0, s29
	v_lshl_add_u64 v[182:183], v[206:207], 0, s[58:59]
	s_barrier
	ds_read_b128 v[158:161], v141 offset:49152
	ds_read_b128 v[162:165], v141 offset:50176
	ds_read_b128 v[166:169], v141 offset:51200
	ds_read_b128 v[170:173], v141 offset:52224
	ds_read_b128 v[174:177], v141 offset:53248
	ds_read_b128 v[178:181], v141 offset:54272
	ds_read_b128 v[208:211], v141 offset:55296
	ds_read_b128 v[212:215], v141 offset:56320
	global_load_lds_dwordx4 v[182:183], off
	v_lshl_add_u64 v[182:183], v[232:233], 0, s[58:59]
	s_mov_b32 m0, s30
	s_nop 0
	global_load_lds_dwordx4 v[182:183], off
	s_barrier
; __device__ __forceinline__ unsigned pk2(float lo, float hi) { unsigned r; asm("v_cvt_pk_bf16_f32 %0, %1, %2" : "=v"(r) : "v"(lo), "v"(hi)); return r; }
; __device__ __forceinline__ float sigmoidf_(float x) { return __builtin_amdgcn_rcpf(1.0f + __builtin_amdgcn_exp2f(-1.4426950408889634f * x)); }
; #define PG8_STAGE(bufoff, gbase, voff) do { _Pragma("unroll") for (int _i = 0; _i < 2; ++_i) \
;         __builtin_amdgcn_global_load_lds((const unsigned*)((const char*)(gbase) + (voff)[_i]), (LAS unsigned*)(lds + (bufoff) + ldsw + _i * 8192), 16, 0, 0); } while (0)
; #define PG8_LDA(dst, b, h) do { _Pragma("unroll") for (int m = 0; m < 4; ++m) _Pragma("unroll") for (int k = 0; k < 2; ++k) dst[m][k] = *(const LAS bf16x8*)(lds + PG8_SA(b, h) + aoff + m * 2048 + k * 1024); } while (0)
; #define PG8_MMA(ai, bj, At, Bt) do { __builtin_amdgcn_s_setprio(1); _Pragma("unroll") for (int m = 0; m < 4; ++m) _Pragma("unroll") for (int n = 0; n < 2; ++n) _Pragma("unroll") for (int k = 0; k < 2; ++k) \
;         acc[ai][bj][m][n] = __builtin_amdgcn_mfma_f32_16x16x32_bf16(Bt[n][k], At[m][k], acc[ai][bj][m][n], 0, 0, 0); __builtin_amdgcn_s_setprio(0); } while (0)
; template <class Epi>
; __device__ __forceinline__ void gemm_phase(LAS unsigned char* lds, const Gemm g, const StaticOrder& S, const Epi& E) {
;     ...
;             PG8_LDA(At, 1, 1); PG8_STAGE(PG8_SA(1, 0), a3, voffA);
;             PG8_BAR; PG8_WAIT_L(0); PG8_MMA(1, 0, At, B0); PG8_BAR; PG8_SCHED;
;             PG8_STAGE(PG8_SB(1, 1), b3 + hstep, voffB);
;             PG8_WAIT_V(6); PG8_BAR; PG8_MMA(1, 1, At, B1); PG8_BAR;
;     __device__ __forceinline__ void operator()(const Acc& acc, const Unit& u, int wr, int wc, int fr, int fq) const {
;         const int row0 = u.pm * 256 + wr * 64 + fr, col0 = u.pn * 128 + wc * 32 + 8 * fq;
; #pragma unroll
;         for (int ai = 0; ai < 2; ++ai)
; #pragma unroll
;             for (int m = 0; m < 4; ++m) {
;                 float h[8];
; #pragma unroll
;                 for (int n = 0; n < 2; ++n)
; #pragma unroll
;                     for (int j = 0; j < 4; ++j) { const float gv = acc[ai][0][m][n][j], uv = acc[ai][1][m][n][j]; h[n * 4 + j] = gv * sigmoidf_(gv) * uv; }
;                 u32x4 w; w.x = pk2(h[0], h[1]); w.y = pk2(h[2], h[3]); w.z = pk2(h[4], h[5]); w.w = pk2(h[6], h[7]);
;                 *(u32x4*)(H + (size_t)(row0 + ai * 128 + m * 16) * DFF + col0) = w;
	s_waitcnt lgkmcnt(0)
	s_setprio 1
	s_waitcnt lgkmcnt(0)
	v_mfma_f32_16x16x32_bf16 v[60:63], v[142:145], v[158:161], v[60:63]
	v_mfma_f32_16x16x32_bf16 v[60:63], v[146:149], v[162:165], v[60:63]
	v_mfma_f32_16x16x32_bf16 v[44:47], v[142:145], v[166:169], v[44:47]
	v_mfma_f32_16x16x32_bf16 v[44:47], v[146:149], v[170:173], v[44:47]
	v_mfma_f32_16x16x32_bf16 v[28:31], v[142:145], v[174:177], v[28:31]
	v_mfma_f32_16x16x32_bf16 v[28:31], v[146:149], v[178:181], v[28:31]
	v_mfma_f32_16x16x32_bf16 v[12:15], v[142:145], v[208:211], v[12:15]
	v_mfma_f32_16x16x32_bf16 v[12:15], v[146:149], v[212:215], v[12:15]
	v_mfma_f32_16x16x32_bf16 v[4:7], v[150:153], v[208:211], v[4:7]
	v_mfma_f32_16x16x32_bf16 v[4:7], v[154:157], v[212:215], v[4:7]
	v_mfma_f32_16x16x32_bf16 v[20:23], v[150:153], v[174:177], v[20:23]
	v_mfma_f32_16x16x32_bf16 v[20:23], v[154:157], v[178:181], v[20:23]
	v_mfma_f32_16x16x32_bf16 v[36:39], v[150:153], v[166:169], v[36:39]
	v_mfma_f32_16x16x32_bf16 v[36:39], v[154:157], v[170:173], v[36:39]
	v_mfma_f32_16x16x32_bf16 v[52:55], v[150:153], v[158:161], v[52:55]
	v_mfma_f32_16x16x32_bf16 v[52:55], v[154:157], v[162:165], v[52:55]
	s_setprio 0
	s_barrier
	s_add_u32 s18, s18, 0x80080
	s_addc_u32 s19, s19, 0
	s_add_i32 s20, s20, s24
	v_lshl_add_u64 v[142:143], s[18:19], 0, v[184:185]
	s_mov_b32 m0, s20
	s_nop 0
	global_load_lds_dwordx4 v[142:143], off
	v_lshl_add_u64 v[142:143], s[18:19], 0, v[128:129]
	s_add_i32 m0, s20, 0x2000
	s_nop 0
	global_load_lds_dwordx4 v[142:143], off
	s_waitcnt vmcnt(6)
	s_barrier
	s_setprio 1
	v_mfma_f32_16x16x32_bf16 v[56:59], v[216:219], v[158:161], v[56:59]
	v_mfma_f32_16x16x32_bf16 v[56:59], v[220:223], v[162:165], v[56:59]
	v_mfma_f32_16x16x32_bf16 v[40:43], v[216:219], v[166:169], v[40:43]
	v_mfma_f32_16x16x32_bf16 v[40:43], v[220:223], v[170:173], v[40:43]
	v_mfma_f32_16x16x32_bf16 v[24:27], v[216:219], v[174:177], v[24:27]
	v_mfma_f32_16x16x32_bf16 v[24:27], v[220:223], v[178:181], v[24:27]
	v_mfma_f32_16x16x32_bf16 v[8:11], v[216:219], v[208:211], v[8:11]
	v_mfma_f32_16x16x32_bf16 v[8:11], v[220:223], v[212:215], v[8:11]
	v_mfma_f32_16x16x32_bf16 v[0:3], v[224:227], v[208:211], v[0:3]
	v_mfma_f32_16x16x32_bf16 v[0:3], v[228:231], v[212:215], v[0:3]
	v_mfma_f32_16x16x32_bf16 v[16:19], v[224:227], v[174:177], v[16:19]
	v_mfma_f32_16x16x32_bf16 v[16:19], v[228:231], v[178:181], v[16:19]
	v_mfma_f32_16x16x32_bf16 v[32:35], v[224:227], v[166:169], v[32:35]
	v_mfma_f32_16x16x32_bf16 v[32:35], v[228:231], v[170:173], v[32:35]
	v_mfma_f32_16x16x32_bf16 v[48:51], v[224:227], v[158:161], v[48:51]
	v_mfma_f32_16x16x32_bf16 v[48:51], v[228:231], v[162:165], v[48:51]
	s_setprio 0
	s_add_i32 s38, s38, 2
	s_add_u32 s16, s16, 0x100
	s_addc_u32 s17, s17, 0
	s_add_u32 s36, s36, 0x100
	s_addc_u32 s37, s37, 0
	s_cmp_gt_u32 s38, 29
	s_barrier
	s_cbranch_scc0 .LBB0_721
	v_mul_f32_e32 v143, 0xbfb8aa3b, v124
	v_exp_f32_e32 v143, v143
	v_lshl_or_b32 v144, s3, 7, v140
	v_lshl_add_u32 v142, s14, 8, v138
	v_ashrrev_i32_e32 v145, 31, v144
	v_add_f32_e32 v143, 1.0, v143
	v_rcp_f32_e32 v143, v143
	s_movk_i32 s1, 0x2c00
	s_and_b64 vcc, exec, s[6:7]
	s_mov_b32 s3, s0
	v_mul_f32_e32 v124, v124, v143
	v_mul_f32_e32 v120, v124, v120
	v_mul_f32_e32 v124, 0xbfb8aa3b, v125
	v_exp_f32_e32 v124, v124
	s_mov_b32 s14, s8
	s_mov_b64 s[18:19], s[12:13]
	v_add_f32_e32 v124, 1.0, v124
	v_rcp_f32_e32 v124, v124
	s_nop 0
	v_mul_f32_e32 v124, v125, v124
	v_mul_f32_e32 v121, v124, v121
	v_mul_f32_e32 v124, 0xbfb8aa3b, v126
	v_exp_f32_e32 v124, v124
	s_nop 0
	v_add_f32_e32 v124, 1.0, v124
	v_rcp_f32_e32 v124, v124
	s_nop 0
	v_mul_f32_e32 v124, v126, v124
	v_mul_f32_e32 v122, v124, v122
	v_mul_f32_e32 v124, 0xbfb8aa3b, v127
	v_exp_f32_e32 v124, v124
	s_nop 0
	v_add_f32_e32 v124, 1.0, v124
	v_rcp_f32_e32 v124, v124
	s_nop 0
	v_mul_f32_e32 v124, v127, v124
	v_mul_f32_e32 v123, v124, v123
	v_mul_f32_e32 v124, 0xbfb8aa3b, v116
	v_exp_f32_e32 v124, v124
	s_nop 0
	v_add_f32_e32 v124, 1.0, v124
	v_rcp_f32_e32 v124, v124
	s_nop 0
	v_mul_f32_e32 v116, v116, v124
	v_mul_f32_e32 v112, v116, v112
	v_mul_f32_e32 v116, 0xbfb8aa3b, v117
	v_exp_f32_e32 v116, v116
	s_nop 0
	v_add_f32_e32 v116, 1.0, v116
	v_rcp_f32_e32 v116, v116
	s_nop 0
	v_mul_f32_e32 v116, v117, v116
	v_mul_f32_e32 v113, v116, v113
	v_mul_f32_e32 v116, 0xbfb8aa3b, v118
	v_exp_f32_e32 v116, v116
	v_cvt_pk_bf16_f32 v117, v122, v123
	s_nop 0
	v_add_f32_e32 v116, 1.0, v116
	v_rcp_f32_e32 v116, v116
	s_nop 0
	v_mul_f32_e32 v116, v118, v116
	v_mul_f32_e32 v114, v116, v114
	v_mul_f32_e32 v116, 0xbfb8aa3b, v119
	v_exp_f32_e32 v116, v116
	v_cvt_pk_bf16_f32 v118, v112, v113
	v_mov_b64_e32 v[112:113], s[66:67]
	v_add_f32_e32 v116, 1.0, v116
	v_rcp_f32_e32 v116, v116
	s_nop 0
	v_mul_f32_e32 v116, v119, v116
	v_mul_f32_e32 v115, v116, v115
	v_cvt_pk_bf16_f32 v116, v120, v121
	v_cvt_pk_bf16_f32 v119, v114, v115
	v_mad_i64_i32 v[120:121], s[16:17], v142, s1, v[112:113]
	v_lshlrev_b64 v[114:115], 1, v[144:145]
	v_lshl_add_u64 v[120:121], v[120:121], 0, v[114:115]
	global_store_dwordx4 v[120:121], v[116:119], off
	s_nop 1
	v_mul_f32_e32 v116, 0xbfb8aa3b, v108
	v_exp_f32_e32 v116, v116
	s_nop 0
	v_add_f32_e32 v116, 1.0, v116
	v_rcp_f32_e32 v116, v116
	s_nop 0
	v_mul_f32_e32 v108, v108, v116
	v_mul_f32_e32 v104, v108, v104
	v_mul_f32_e32 v108, 0xbfb8aa3b, v109
	v_exp_f32_e32 v108, v108
	s_nop 0
	v_add_f32_e32 v108, 1.0, v108
	v_rcp_f32_e32 v108, v108
	s_nop 0
	v_mul_f32_e32 v108, v109, v108
	v_mul_f32_e32 v105, v108, v105
	v_mul_f32_e32 v108, 0xbfb8aa3b, v110
	v_exp_f32_e32 v108, v108
	s_nop 0
	v_add_f32_e32 v108, 1.0, v108
	v_rcp_f32_e32 v108, v108
	s_nop 0
	v_mul_f32_e32 v108, v110, v108
	v_mul_f32_e32 v106, v108, v106
; __device__ __forceinline__ unsigned pk2(float lo, float hi) { unsigned r; asm("v_cvt_pk_bf16_f32 %0, %1, %2" : "=v"(r) : "v"(lo), "v"(hi)); return r; }
; __device__ __forceinline__ float sigmoidf_(float x) { return __builtin_amdgcn_rcpf(1.0f + __builtin_amdgcn_exp2f(-1.4426950408889634f * x)); }
;     __device__ __forceinline__ void operator()(const Acc& acc, const Unit& u, int wr, int wc, int fr, int fq) const {
;         const int row0 = u.pm * 256 + wr * 64 + fr, col0 = u.pn * 128 + wc * 32 + 8 * fq;
; #pragma unroll
;         for (int ai = 0; ai < 2; ++ai)
; #pragma unroll
;             for (int m = 0; m < 4; ++m) {
;                 float h[8];
; #pragma unroll
;                 for (int n = 0; n < 2; ++n)
; #pragma unroll
;                     for (int j = 0; j < 4; ++j) { const float gv = acc[ai][0][m][n][j], uv = acc[ai][1][m][n][j]; h[n * 4 + j] = gv * sigmoidf_(gv) * uv; }
;                 u32x4 w; w.x = pk2(h[0], h[1]); w.y = pk2(h[2], h[3]); w.z = pk2(h[4], h[5]); w.w = pk2(h[6], h[7]);
;                 *(u32x4*)(H + (size_t)(row0 + ai * 128 + m * 16) * DFF + col0) = w;
	v_mul_f32_e32 v108, 0xbfb8aa3b, v111
	v_exp_f32_e32 v108, v108
	s_nop 0
	v_add_f32_e32 v108, 1.0, v108
	v_rcp_f32_e32 v108, v108
	s_nop 0
	v_mul_f32_e32 v108, v111, v108
	v_mul_f32_e32 v107, v108, v107
	v_mul_f32_e32 v108, 0xbfb8aa3b, v100
	v_exp_f32_e32 v108, v108
	s_nop 0
	v_add_f32_e32 v108, 1.0, v108
	v_rcp_f32_e32 v108, v108
	s_nop 0
	v_mul_f32_e32 v100, v100, v108
	v_mul_f32_e32 v100, v100, v96
	v_mul_f32_e32 v96, 0xbfb8aa3b, v101
	v_exp_f32_e32 v96, v96
	s_nop 0
	v_add_f32_e32 v96, 1.0, v96
	v_rcp_f32_e32 v96, v96
	s_nop 0
	v_mul_f32_e32 v96, v101, v96
	v_mul_f32_e32 v101, v96, v97
	v_mul_f32_e32 v96, 0xbfb8aa3b, v102
	v_exp_f32_e32 v96, v96
	v_cvt_pk_bf16_f32 v97, v106, v107
	s_nop 0
	v_add_f32_e32 v96, 1.0, v96
	v_rcp_f32_e32 v96, v96
	s_nop 0
	v_mul_f32_e32 v96, v102, v96
	v_mul_f32_e32 v102, v96, v98
	v_mul_f32_e32 v96, 0xbfb8aa3b, v103
	v_exp_f32_e32 v96, v96
	v_cvt_pk_bf16_f32 v98, v100, v101
	v_or_b32_e32 v100, 16, v142
	v_mad_i64_i32 v[100:101], s[16:17], v100, s1, v[112:113]
	v_add_f32_e32 v96, 1.0, v96
	v_rcp_f32_e32 v96, v96
	v_lshl_add_u64 v[100:101], v[100:101], 0, v[114:115]
	v_mul_f32_e32 v96, v103, v96
	v_mul_f32_e32 v99, v96, v99
	v_cvt_pk_bf16_f32 v96, v104, v105
	v_cvt_pk_bf16_f32 v99, v102, v99
	global_store_dwordx4 v[100:101], v[96:99], off
	s_nop 1
	v_mul_f32_e32 v96, 0xbfb8aa3b, v92
	v_exp_f32_e32 v96, v96
	s_nop 0
	v_add_f32_e32 v96, 1.0, v96
	v_rcp_f32_e32 v96, v96
	s_nop 0
	v_mul_f32_e32 v92, v92, v96
	v_mul_f32_e32 v88, v92, v88
	v_mul_f32_e32 v92, 0xbfb8aa3b, v93
	v_exp_f32_e32 v92, v92
	s_nop 0
	v_add_f32_e32 v92, 1.0, v92
	v_rcp_f32_e32 v92, v92
	s_nop 0
	v_mul_f32_e32 v92, v93, v92
	v_mul_f32_e32 v89, v92, v89
	v_mul_f32_e32 v92, 0xbfb8aa3b, v94
	v_exp_f32_e32 v92, v92
	s_nop 0
	v_add_f32_e32 v92, 1.0, v92
	v_rcp_f32_e32 v92, v92
	s_nop 0
	v_mul_f32_e32 v92, v94, v92
	v_mul_f32_e32 v90, v92, v90
	v_mul_f32_e32 v92, 0xbfb8aa3b, v95
	v_exp_f32_e32 v92, v92
	s_nop 0
	v_add_f32_e32 v92, 1.0, v92
	v_rcp_f32_e32 v92, v92
	s_nop 0
	v_mul_f32_e32 v92, v95, v92
	v_mul_f32_e32 v91, v92, v91
	v_mul_f32_e32 v92, 0xbfb8aa3b, v84
	v_exp_f32_e32 v92, v92
	s_nop 0
	v_add_f32_e32 v92, 1.0, v92
	v_rcp_f32_e32 v92, v92
	s_nop 0
	v_mul_f32_e32 v84, v84, v92
	v_mul_f32_e32 v84, v84, v80
	v_mul_f32_e32 v80, 0xbfb8aa3b, v85
	v_exp_f32_e32 v80, v80
	s_nop 0
	v_add_f32_e32 v80, 1.0, v80
	v_rcp_f32_e32 v80, v80
	s_nop 0
	v_mul_f32_e32 v80, v85, v80
	v_mul_f32_e32 v85, v80, v81
	v_mul_f32_e32 v80, 0xbfb8aa3b, v86
	v_exp_f32_e32 v80, v80
	v_cvt_pk_bf16_f32 v81, v90, v91
	s_nop 0
	v_add_f32_e32 v80, 1.0, v80
	v_rcp_f32_e32 v80, v80
	s_nop 0
	v_mul_f32_e32 v80, v86, v80
	v_mul_f32_e32 v86, v80, v82
	v_mul_f32_e32 v80, 0xbfb8aa3b, v87
	v_exp_f32_e32 v80, v80
	v_cvt_pk_bf16_f32 v82, v84, v85
	v_or_b32_e32 v84, 32, v142
	v_mad_i64_i32 v[84:85], s[16:17], v84, s1, v[112:113]
	v_add_f32_e32 v80, 1.0, v80
	v_rcp_f32_e32 v80, v80
	v_lshl_add_u64 v[84:85], v[84:85], 0, v[114:115]
	v_mul_f32_e32 v80, v87, v80
	v_mul_f32_e32 v83, v80, v83
	v_cvt_pk_bf16_f32 v80, v88, v89
	v_cvt_pk_bf16_f32 v83, v86, v83
	global_store_dwordx4 v[84:85], v[80:83], off
	s_nop 1
	v_mul_f32_e32 v80, 0xbfb8aa3b, v76
	v_exp_f32_e32 v80, v80
	s_nop 0
	v_add_f32_e32 v80, 1.0, v80
	v_rcp_f32_e32 v80, v80
	s_nop 0
	v_mul_f32_e32 v76, v76, v80
	v_mul_f32_e32 v72, v76, v72
	v_mul_f32_e32 v76, 0xbfb8aa3b, v77
	v_exp_f32_e32 v76, v76
	s_nop 0
	v_add_f32_e32 v76, 1.0, v76
	v_rcp_f32_e32 v76, v76
	s_nop 0
	v_mul_f32_e32 v76, v77, v76
	v_mul_f32_e32 v73, v76, v73
	v_mul_f32_e32 v76, 0xbfb8aa3b, v78
	v_exp_f32_e32 v76, v76
	s_nop 0
	v_add_f32_e32 v76, 1.0, v76
	v_rcp_f32_e32 v76, v76
	s_nop 0
	v_mul_f32_e32 v76, v78, v76
	v_mul_f32_e32 v74, v76, v74
	v_mul_f32_e32 v76, 0xbfb8aa3b, v79
	v_exp_f32_e32 v76, v76
	s_nop 0
	v_add_f32_e32 v76, 1.0, v76
	v_rcp_f32_e32 v76, v76
	s_nop 0
	v_mul_f32_e32 v76, v79, v76
	v_mul_f32_e32 v75, v76, v75
	v_mul_f32_e32 v76, 0xbfb8aa3b, v68
	v_exp_f32_e32 v76, v76
	s_nop 0
	v_add_f32_e32 v76, 1.0, v76
	v_rcp_f32_e32 v76, v76
	s_nop 0
	v_mul_f32_e32 v68, v68, v76
	v_mul_f32_e32 v68, v68, v64
	v_mul_f32_e32 v64, 0xbfb8aa3b, v69
	v_exp_f32_e32 v64, v64
	s_nop 0
	v_add_f32_e32 v64, 1.0, v64
	v_rcp_f32_e32 v64, v64
	s_nop 0
	v_mul_f32_e32 v64, v69, v64
	v_mul_f32_e32 v69, v64, v65
	v_mul_f32_e32 v64, 0xbfb8aa3b, v70
	v_exp_f32_e32 v64, v64
	v_cvt_pk_bf16_f32 v65, v74, v75
	s_nop 0
	v_add_f32_e32 v64, 1.0, v64
	v_rcp_f32_e32 v64, v64
	s_nop 0
	v_mul_f32_e32 v64, v70, v64
	v_mul_f32_e32 v70, v64, v66
	v_mul_f32_e32 v64, 0xbfb8aa3b, v71
	v_exp_f32_e32 v64, v64
	v_cvt_pk_bf16_f32 v66, v68, v69
	v_or_b32_e32 v68, 48, v142
	v_mad_i64_i32 v[68:69], s[16:17], v68, s1, v[112:113]
	v_add_f32_e32 v64, 1.0, v64
	v_rcp_f32_e32 v64, v64
	v_lshl_add_u64 v[68:69], v[68:69], 0, v[114:115]
	v_mul_f32_e32 v64, v71, v64
	v_mul_f32_e32 v67, v64, v67
	v_cvt_pk_bf16_f32 v64, v72, v73
	v_cvt_pk_bf16_f32 v67, v70, v67
	global_store_dwordx4 v[68:69], v[64:67], off
	s_nop 1
	v_mul_f32_e32 v65, 0xbfb8aa3b, v60
	v_exp_f32_e32 v65, v65
	v_add_u32_e32 v64, 0x80, v142
	v_add_f32_e32 v65, 1.0, v65
	v_rcp_f32_e32 v65, v65
	s_nop 0
	v_mul_f32_e32 v60, v60, v65
	v_mul_f32_e32 v56, v60, v56
	v_mul_f32_e32 v60, 0xbfb8aa3b, v61
	v_exp_f32_e32 v60, v60
	s_nop 0
	v_add_f32_e32 v60, 1.0, v60
	v_rcp_f32_e32 v60, v60
	s_nop 0
	v_mul_f32_e32 v60, v61, v60
	v_mul_f32_e32 v57, v60, v57
	v_mul_f32_e32 v60, 0xbfb8aa3b, v62
	v_exp_f32_e32 v60, v60
	s_nop 0
	v_add_f32_e32 v60, 1.0, v60
	v_rcp_f32_e32 v60, v60
	s_nop 0
	v_mul_f32_e32 v60, v62, v60
	v_mul_f32_e32 v58, v60, v58
	v_mul_f32_e32 v60, 0xbfb8aa3b, v63
	v_exp_f32_e32 v60, v60
	s_nop 0
	v_add_f32_e32 v60, 1.0, v60
	v_rcp_f32_e32 v60, v60
; __device__ __forceinline__ unsigned pk2(float lo, float hi) { unsigned r; asm("v_cvt_pk_bf16_f32 %0, %1, %2" : "=v"(r) : "v"(lo), "v"(hi)); return r; }
; __device__ __forceinline__ float sigmoidf_(float x) { return __builtin_amdgcn_rcpf(1.0f + __builtin_amdgcn_exp2f(-1.4426950408889634f * x)); }
; #define PG8_WAIT_V(n) asm volatile("s_waitcnt vmcnt(" #n ")" ::: "memory")
; #define PG8_BAR __builtin_amdgcn_s_barrier()
; template <class Epi>
; __device__ __forceinline__ void gemm_phase(LAS unsigned char* lds, const Gemm g, const StaticOrder& S, const Epi& E) {
;     ...
;         E(acc, cur, wr, wc, fr, fq);
;         if (!has_next) break;
; #pragma unroll
;         for (int a = 0; a < 2; ++a)
; #pragma unroll
;             for (int b = 0; b < 2; ++b)
; #pragma unroll
;                 for (int m = 0; m < 4; ++m)
; #pragma unroll
;                     for (int n = 0; n < 2; ++n) acc[a][b][m][n] = (f32x4){0.f, 0.f, 0.f, 0.f};
;         cur = nxt; cA = nA; cB = nB; ++ui;
;     }
;     PG8_WAIT_V(0);
;     if (wr == 0) PG8_BAR;
;     __device__ __forceinline__ void operator()(const Acc& acc, const Unit& u, int wr, int wc, int fr, int fq) const {
;         const int row0 = u.pm * 256 + wr * 64 + fr, col0 = u.pn * 128 + wc * 32 + 8 * fq;
; #pragma unroll
;         for (int ai = 0; ai < 2; ++ai)
; #pragma unroll
;             for (int m = 0; m < 4; ++m) {
;                 float h[8];
; #pragma unroll
;                 for (int n = 0; n < 2; ++n)
; #pragma unroll
;                     for (int j = 0; j < 4; ++j) { const float gv = acc[ai][0][m][n][j], uv = acc[ai][1][m][n][j]; h[n * 4 + j] = gv * sigmoidf_(gv) * uv; }
;                 u32x4 w; w.x = pk2(h[0], h[1]); w.y = pk2(h[2], h[3]); w.z = pk2(h[4], h[5]); w.w = pk2(h[6], h[7]);
;                 *(u32x4*)(H + (size_t)(row0 + ai * 128 + m * 16) * DFF + col0) = w;
	s_nop 0
	v_mul_f32_e32 v60, v63, v60
	v_mul_f32_e32 v59, v60, v59
	v_mul_f32_e32 v60, 0xbfb8aa3b, v52
	v_exp_f32_e32 v60, v60
	s_nop 0
	v_add_f32_e32 v60, 1.0, v60
	v_rcp_f32_e32 v60, v60
	s_nop 0
	v_mul_f32_e32 v52, v52, v60
	v_mul_f32_e32 v52, v52, v48
	v_mul_f32_e32 v48, 0xbfb8aa3b, v53
	v_exp_f32_e32 v48, v48
	s_nop 0
	v_add_f32_e32 v48, 1.0, v48
	v_rcp_f32_e32 v48, v48
	s_nop 0
	v_mul_f32_e32 v48, v53, v48
	v_mul_f32_e32 v53, v48, v49
	v_mul_f32_e32 v48, 0xbfb8aa3b, v54
	v_exp_f32_e32 v48, v48
	v_cvt_pk_bf16_f32 v49, v58, v59
	s_nop 0
	v_add_f32_e32 v48, 1.0, v48
	v_rcp_f32_e32 v48, v48
	s_nop 0
	v_mul_f32_e32 v48, v54, v48
	v_mul_f32_e32 v54, v48, v50
	v_mul_f32_e32 v48, 0xbfb8aa3b, v55
	v_exp_f32_e32 v48, v48
	v_cvt_pk_bf16_f32 v50, v52, v53
	v_mad_i64_i32 v[52:53], s[16:17], v64, s1, v[112:113]
	v_add_f32_e32 v48, 1.0, v48
	v_rcp_f32_e32 v48, v48
	v_lshl_add_u64 v[52:53], v[52:53], 0, v[114:115]
	v_mul_f32_e32 v48, v55, v48
	v_mul_f32_e32 v51, v48, v51
	v_cvt_pk_bf16_f32 v48, v56, v57
	v_cvt_pk_bf16_f32 v51, v54, v51
	global_store_dwordx4 v[52:53], v[48:51], off
	s_nop 1
	v_mul_f32_e32 v48, 0xbfb8aa3b, v44
	v_exp_f32_e32 v48, v48
	s_nop 0
	v_add_f32_e32 v48, 1.0, v48
	v_rcp_f32_e32 v48, v48
	s_nop 0
	v_mul_f32_e32 v44, v44, v48
	v_mul_f32_e32 v40, v44, v40
	v_mul_f32_e32 v44, 0xbfb8aa3b, v45
	v_exp_f32_e32 v44, v44
	s_nop 0
	v_add_f32_e32 v44, 1.0, v44
	v_rcp_f32_e32 v44, v44
	s_nop 0
	v_mul_f32_e32 v44, v45, v44
	v_mul_f32_e32 v41, v44, v41
	v_mul_f32_e32 v44, 0xbfb8aa3b, v46
	v_exp_f32_e32 v44, v44
	s_nop 0
	v_add_f32_e32 v44, 1.0, v44
	v_rcp_f32_e32 v44, v44
	s_nop 0
	v_mul_f32_e32 v44, v46, v44
	v_mul_f32_e32 v42, v44, v42
	v_mul_f32_e32 v44, 0xbfb8aa3b, v47
	v_exp_f32_e32 v44, v44
	s_nop 0
	v_add_f32_e32 v44, 1.0, v44
	v_rcp_f32_e32 v44, v44
	s_nop 0
	v_mul_f32_e32 v44, v47, v44
	v_mul_f32_e32 v43, v44, v43
	v_mul_f32_e32 v44, 0xbfb8aa3b, v36
	v_exp_f32_e32 v44, v44
	s_nop 0
	v_add_f32_e32 v44, 1.0, v44
	v_rcp_f32_e32 v44, v44
	s_nop 0
	v_mul_f32_e32 v36, v36, v44
	v_mul_f32_e32 v36, v36, v32
	v_mul_f32_e32 v32, 0xbfb8aa3b, v37
	v_exp_f32_e32 v32, v32
	s_nop 0
	v_add_f32_e32 v32, 1.0, v32
	v_rcp_f32_e32 v32, v32
	s_nop 0
	v_mul_f32_e32 v32, v37, v32
	v_mul_f32_e32 v37, v32, v33
	v_mul_f32_e32 v32, 0xbfb8aa3b, v38
	v_exp_f32_e32 v32, v32
	v_cvt_pk_bf16_f32 v33, v42, v43
	s_nop 0
	v_add_f32_e32 v32, 1.0, v32
	v_rcp_f32_e32 v32, v32
	s_nop 0
	v_mul_f32_e32 v32, v38, v32
	v_mul_f32_e32 v38, v32, v34
	v_mul_f32_e32 v32, 0xbfb8aa3b, v39
	v_exp_f32_e32 v32, v32
	v_cvt_pk_bf16_f32 v34, v36, v37
	v_add_u32_e32 v36, 0x90, v142
	v_mad_i64_i32 v[36:37], s[16:17], v36, s1, v[112:113]
	v_add_f32_e32 v32, 1.0, v32
	v_rcp_f32_e32 v32, v32
	v_lshl_add_u64 v[36:37], v[36:37], 0, v[114:115]
	v_mul_f32_e32 v32, v39, v32
	v_mul_f32_e32 v35, v32, v35
	v_cvt_pk_bf16_f32 v32, v40, v41
	v_cvt_pk_bf16_f32 v35, v38, v35
	global_store_dwordx4 v[36:37], v[32:35], off
	s_nop 1
	v_mul_f32_e32 v32, 0xbfb8aa3b, v28
	v_exp_f32_e32 v32, v32
	s_nop 0
	v_add_f32_e32 v32, 1.0, v32
	v_rcp_f32_e32 v32, v32
	s_nop 0
	v_mul_f32_e32 v28, v28, v32
	v_mul_f32_e32 v24, v28, v24
	v_mul_f32_e32 v28, 0xbfb8aa3b, v29
	v_exp_f32_e32 v28, v28
	s_nop 0
	v_add_f32_e32 v28, 1.0, v28
	v_rcp_f32_e32 v28, v28
	s_nop 0
	v_mul_f32_e32 v28, v29, v28
	v_mul_f32_e32 v25, v28, v25
	v_mul_f32_e32 v28, 0xbfb8aa3b, v30
	v_exp_f32_e32 v28, v28
	s_nop 0
	v_add_f32_e32 v28, 1.0, v28
	v_rcp_f32_e32 v28, v28
	s_nop 0
	v_mul_f32_e32 v28, v30, v28
	v_mul_f32_e32 v26, v28, v26
	v_mul_f32_e32 v28, 0xbfb8aa3b, v31
	v_exp_f32_e32 v28, v28
	s_nop 0
	v_add_f32_e32 v28, 1.0, v28
	v_rcp_f32_e32 v28, v28
	s_nop 0
	v_mul_f32_e32 v28, v31, v28
	v_mul_f32_e32 v27, v28, v27
	v_mul_f32_e32 v28, 0xbfb8aa3b, v20
	v_exp_f32_e32 v28, v28
	s_nop 0
	v_add_f32_e32 v28, 1.0, v28
	v_rcp_f32_e32 v28, v28
	s_nop 0
	v_mul_f32_e32 v20, v20, v28
	v_mul_f32_e32 v20, v20, v16
	v_mul_f32_e32 v16, 0xbfb8aa3b, v21
	v_exp_f32_e32 v16, v16
	s_nop 0
	v_add_f32_e32 v16, 1.0, v16
	v_rcp_f32_e32 v16, v16
	s_nop 0
	v_mul_f32_e32 v16, v21, v16
	v_mul_f32_e32 v21, v16, v17
	v_mul_f32_e32 v16, 0xbfb8aa3b, v22
	v_exp_f32_e32 v16, v16
	v_cvt_pk_bf16_f32 v17, v26, v27
	s_nop 0
	v_add_f32_e32 v16, 1.0, v16
	v_rcp_f32_e32 v16, v16
	s_nop 0
	v_mul_f32_e32 v16, v22, v16
	v_mul_f32_e32 v22, v16, v18
	v_mul_f32_e32 v16, 0xbfb8aa3b, v23
	v_exp_f32_e32 v16, v16
	v_cvt_pk_bf16_f32 v18, v20, v21
	v_add_u32_e32 v20, 0xa0, v142
	v_mad_i64_i32 v[20:21], s[16:17], v20, s1, v[112:113]
	v_add_f32_e32 v16, 1.0, v16
	v_rcp_f32_e32 v16, v16
	v_lshl_add_u64 v[20:21], v[20:21], 0, v[114:115]
	v_mul_f32_e32 v16, v23, v16
	v_mul_f32_e32 v19, v16, v19
	v_cvt_pk_bf16_f32 v16, v24, v25
	v_cvt_pk_bf16_f32 v19, v22, v19
	global_store_dwordx4 v[20:21], v[16:19], off
	s_nop 1
	v_mul_f32_e32 v16, 0xbfb8aa3b, v12
	v_exp_f32_e32 v16, v16
	s_nop 0
	v_add_f32_e32 v16, 1.0, v16
	v_rcp_f32_e32 v16, v16
	s_nop 0
	v_mul_f32_e32 v12, v12, v16
	v_mul_f32_e32 v8, v12, v8
	v_mul_f32_e32 v12, 0xbfb8aa3b, v13
	v_exp_f32_e32 v12, v12
	s_nop 0
	v_add_f32_e32 v12, 1.0, v12
	v_rcp_f32_e32 v12, v12
	s_nop 0
	v_mul_f32_e32 v12, v13, v12
	v_mul_f32_e32 v9, v12, v9
	v_mul_f32_e32 v12, 0xbfb8aa3b, v14
	v_exp_f32_e32 v12, v12
	s_nop 0
	v_add_f32_e32 v12, 1.0, v12
	v_rcp_f32_e32 v12, v12
	s_nop 0
	v_mul_f32_e32 v12, v14, v12
	v_mul_f32_e32 v10, v12, v10
	v_mul_f32_e32 v12, 0xbfb8aa3b, v15
	v_exp_f32_e32 v12, v12
	s_nop 0
	v_add_f32_e32 v12, 1.0, v12
	v_rcp_f32_e32 v12, v12
	s_nop 0
	v_mul_f32_e32 v12, v15, v12
	v_mul_f32_e32 v11, v12, v11
	v_mul_f32_e32 v12, 0xbfb8aa3b, v4
	v_exp_f32_e32 v12, v12
	s_nop 0
	v_add_f32_e32 v12, 1.0, v12
	v_rcp_f32_e32 v12, v12
	s_nop 0
	v_mul_f32_e32 v4, v4, v12
	v_mul_f32_e32 v4, v4, v0
	v_mul_f32_e32 v0, 0xbfb8aa3b, v5
	v_exp_f32_e32 v0, v0
	s_nop 0
	v_add_f32_e32 v0, 1.0, v0
	v_rcp_f32_e32 v0, v0
	s_nop 0
	v_mul_f32_e32 v0, v5, v0
	v_mul_f32_e32 v5, v0, v1
	v_mul_f32_e32 v0, 0xbfb8aa3b, v6
	v_exp_f32_e32 v0, v0
	v_cvt_pk_bf16_f32 v1, v10, v11
	s_nop 0
	v_add_f32_e32 v0, 1.0, v0
	v_rcp_f32_e32 v0, v0
	s_nop 0
	v_mul_f32_e32 v0, v6, v0
	v_mul_f32_e32 v6, v0, v2
	v_mul_f32_e32 v0, 0xbfb8aa3b, v7
	v_exp_f32_e32 v0, v0
	v_cvt_pk_bf16_f32 v2, v4, v5
	v_add_u32_e32 v4, 0xb0, v142
	v_mad_i64_i32 v[4:5], s[16:17], v4, s1, v[112:113]
	v_add_f32_e32 v0, 1.0, v0
	v_rcp_f32_e32 v0, v0
	v_lshl_add_u64 v[4:5], v[4:5], 0, v[114:115]
	s_mov_b64 s[16:17], s[10:11]
	v_mul_f32_e32 v0, v7, v0
	v_mul_f32_e32 v3, v0, v3
	v_cvt_pk_bf16_f32 v0, v8, v9
	v_cvt_pk_bf16_f32 v3, v6, v3
	global_store_dwordx4 v[4:5], v[0:3], off
	s_cbranch_vccz .LBB0_718
	s_waitcnt vmcnt(0)
	s_cmpk_gt_u32 s23, 0xff
	s_cbranch_scc1 .LBB0_725
	s_barrier
